# P10: waves 4-7 run sweep h0, sweep h1, LN2 h1, LN2 h0 (half-0 sums parked in workspace) so LayerNorm phases sit beside the partner wave's sweep; plus lean sweep, LN2 preload, P6 epilogue prefetch, att
# baseline (speedup 1.0000x reference)
.LBB0_1009:
	s_andn2_saveexec_b64 s[0:1], s[0:1]
	v_mul_f32_e32 v5, v3, v3
	v_mov_b32_e32 v6, 0x3ba10414
	v_fmac_f32_e32 v6, 0xba1345e1, v5
	v_fmaak_f32 v6, v5, v6, 0xbcdac9b8
	v_fmaak_f32 v6, v5, v6, 0x3de703be
	v_fmaak_f32 v6, v5, v6, 0xbec09330
	v_fmaak_f32 v5, v5, v6, 0x3e0375d0
	v_fma_f32 v5, |v3|, v5, |v3|
	s_or_b64 exec, exec, s[0:1]
	s_brev_b32 s0, -2
	v_bfi_b32 v3, s0, v5, v3
	v_mul_f32_e32 v4, 0.5, v4
	v_add_f32_e32 v3, 1.0, v3
	v_mul_f32_e32 v3, v4, v3
	s_waitcnt vmcnt(0)
	v_mul_f32_e32 v2, v2, v3
	v_mul_f32_e32 v2, 0x3e33a62d, v2
	v_cvt_pk_f16_f32 v2, v2, v2
	v_lshl_add_u32 v1, v1, 2, s26
	ds_write_b32 v1, v2 offset:4096
	v_and_b32_e32 v6, 0x7f, v65
	v_and_b32_e32 v7, 0x7f, v66
	s_waitcnt lgkmcnt(0)
	v_lshl_add_u32 v1, v6, 2, s26
	ds_read_b32 v1, v1 offset:4096
	v_lshl_add_u32 v2, v7, 2, s26
	ds_read_b32 v2, v2 offset:4096
	v_and_b32_e32 v3, 0x7f, v68
	v_and_b32_e32 v4, 0x7f, v67
	s_waitcnt lgkmcnt(1)
	ds_write_b32 v0, v1
	v_lshl_add_u32 v0, v46, 2, s26
	s_waitcnt lgkmcnt(1)
	ds_write_b32 v0, v2 offset:256
	v_and_b32_e32 v1, 0x7f, v85
	v_and_b32_e32 v2, 0x7f, v89
	v_lshl_add_u32 v1, v1, 2, s26
	v_lshl_add_u32 v2, v2, 2, s26
	ds_read_b32 v1, v1 offset:4608
	ds_read_b32 v2, v2 offset:4608
	v_and_b32_e32 v12, 0x7f, v70
	v_and_b32_e32 v13, 0x7f, v69
	v_and_b32_e32 v16, 0x7f, v71
	v_and_b32_e32 v18, 0x7f, v72
	s_waitcnt lgkmcnt(0)
	ds_write2st64_b32 v0, v1, v2 offset0:2 offset1:3
	v_lshl_add_u32 v1, v3, 2, s26
	v_lshl_add_u32 v2, v4, 2, s26
	ds_read_b32 v1, v1 offset:5120
	ds_read_b32 v2, v2 offset:5120
	v_lshrrev_b32_e32 v5, 3, v65
	v_lshrrev_b32_e32 v8, 3, v66
	v_lshrrev_b32_e32 v9, 3, v68
	v_lshrrev_b32_e32 v10, 3, v67
	s_waitcnt lgkmcnt(0)
	ds_write2st64_b32 v0, v1, v2 offset0:4 offset1:5
	v_and_b32_e32 v1, 0x7f, v86
	v_and_b32_e32 v2, 0x7f, v90
	v_lshl_add_u32 v1, v1, 2, s26
	v_lshl_add_u32 v2, v2, 2, s26
	ds_read_b32 v1, v1 offset:5632
	ds_read_b32 v2, v2 offset:5632
	v_lshrrev_b32_e32 v11, 3, v70
	v_lshrrev_b32_e32 v14, 3, v69
	v_lshrrev_b32_e32 v15, 3, v71
	v_lshrrev_b32_e32 v17, 3, v72
	s_waitcnt lgkmcnt(0)
	ds_write2st64_b32 v0, v1, v2 offset0:6 offset1:7
	v_lshl_add_u32 v1, v12, 2, s26
	v_lshl_add_u32 v2, v13, 2, s26
	ds_read_b32 v1, v1 offset:6144
	ds_read_b32 v2, v2 offset:6144
	s_mov_b32 s0, 0x1fffff80
	v_mov_b32_e32 v45, 0
	v_and_or_b32 v93, v5, s0, v6
	v_and_or_b32 v94, v8, s0, v7
	s_waitcnt lgkmcnt(0)
	ds_write2st64_b32 v0, v1, v2 offset0:8 offset1:9
	v_and_b32_e32 v1, 0x7f, v87
	v_and_b32_e32 v2, 0x7f, v91
	v_lshl_add_u32 v1, v1, 2, s26
	v_lshl_add_u32 v2, v2, 2, s26
	ds_read_b32 v1, v1 offset:6656
	ds_read_b32 v2, v2 offset:6656
	v_and_or_b32 v95, v9, s0, v3
	v_and_or_b32 v96, v10, s0, v4
	v_and_or_b32 v97, v11, s0, v12
	v_and_or_b32 v98, v14, s0, v13
	s_waitcnt lgkmcnt(0)
	ds_write2st64_b32 v0, v1, v2 offset0:10 offset1:11
	v_lshl_add_u32 v1, v16, 2, s26
	v_lshl_add_u32 v2, v18, 2, s26
	ds_read_b32 v1, v1 offset:7168
	ds_read_b32 v2, v2 offset:7168
	v_and_or_b32 v99, v15, s0, v16
	v_and_or_b32 v100, v17, s0, v18
	s_add_u32 s2, s72, 0x1ab00000
	s_mov_b64 s[0:1], 0x4300000
	s_waitcnt lgkmcnt(0)
	ds_write2st64_b32 v0, v1, v2 offset0:12 offset1:13
	v_and_b32_e32 v1, 0x7f, v92
	v_and_b32_e32 v2, 0x7f, v88
	v_lshl_add_u32 v1, v1, 2, s26
	v_lshl_add_u32 v2, v2, 2, s26
	ds_read_b32 v1, v1 offset:7680
	ds_read_b32 v2, v2 offset:7680
	s_addc_u32 s3, s73, 0
	s_mov_b32 s5, 0
	s_mov_b32 s6, 0x3f9837f0
	v_mov_b32_e32 v101, 0x3727c5ac
	s_waitcnt lgkmcnt(0)
	ds_write2st64_b32 v0, v1, v2 offset0:14 offset1:15
	s_waitcnt vmcnt(0) lgkmcnt(0)
	v_lshl_add_u64 v[0:1], s[72:73], 0, v[44:45]
	v_lshl_add_u64 v[76:77], v[0:1], 0, s[0:1]
	s_mov_b64 s[0:1], -1
	s_mov_b32 s7, 0xf800000
	v_mov_b32_e32 v102, 0x260
	s_movk_i32 s12, 0x1000
	s_mov_b32 s10, 0
	s_mov_b32 s100, 0

.Lmy_lrow0:
	s_waitcnt vmcnt(6)
	v_readlane_b32 s4, v51, 1
	v_readlane_b32 s0, v52, 0
	v_cvt_scalef32_pk_f16_fp4 v32, v0, 1.0
	v_cvt_scalef32_pk_f16_fp4 v33, v0, 1.0 op_sel:[1,0,0]
	v_cvt_scalef32_pk_f16_fp4 v34, v0, 1.0 op_sel:[0,1,0]
	v_cvt_scalef32_pk_f16_fp4 v35, v0, 1.0 op_sel:[1,1,0]
	v_cvt_scalef32_pk_f16_fp4 v36, v1, 1.0
	v_cvt_scalef32_pk_f16_fp4 v37, v1, 1.0 op_sel:[1,0,0]
	v_cvt_scalef32_pk_f16_fp4 v38, v1, 1.0 op_sel:[0,1,0]
	v_cvt_scalef32_pk_f16_fp4 v39, v1, 1.0 op_sel:[1,1,0]
	v_cvt_scalef32_pk_f16_fp4 v40, v2, 1.0
	v_cvt_scalef32_pk_f16_fp4 v41, v2, 1.0 op_sel:[1,0,0]
	v_cvt_scalef32_pk_f16_fp4 v42, v2, 1.0 op_sel:[0,1,0]
	v_cvt_scalef32_pk_f16_fp4 v43, v2, 1.0 op_sel:[1,1,0]
	v_cvt_scalef32_pk_f16_fp4 v44, v3, 1.0
	v_cvt_scalef32_pk_f16_fp4 v45, v3, 1.0 op_sel:[1,0,0]
	v_cvt_scalef32_pk_f16_fp4 v46, v3, 1.0 op_sel:[0,1,0]
	v_cvt_scalef32_pk_f16_fp4 v47, v3, 1.0 op_sel:[1,1,0]
	buffer_load_dwordx4 v[28:31], v115, s[12:15], s4 offen
	v_pk_fma_f16 v139, v32, s0, v139
	v_pk_fma_f16 v138, v33, s0, v138
	v_pk_fma_f16 v136, v34, s0, v136
	v_pk_fma_f16 v135, v35, s0, v135
	v_pk_fma_f16 v134, v36, s0, v134
	v_pk_fma_f16 v133, v37, s0, v133
	v_pk_fma_f16 v132, v38, s0, v132
	v_pk_fma_f16 v131, v39, s0, v131
	v_pk_fma_f16 v130, v40, s0, v130
	v_pk_fma_f16 v129, v41, s0, v129
	v_pk_fma_f16 v128, v42, s0, v128
	v_pk_fma_f16 v127, v43, s0, v127
	v_pk_fma_f16 v126, v44, s0, v126
	v_pk_fma_f16 v114, v45, s0, v114
	v_pk_fma_f16 v140, v46, s0, v140
	v_pk_fma_f16 v137, v47, s0, v137
	s_waitcnt vmcnt(6)
	v_readlane_b32 s4, v48, 2
	v_readlane_b32 s0, v53, 0
	v_cvt_scalef32_pk_f16_fp4 v32, v4, 1.0
	v_cvt_scalef32_pk_f16_fp4 v33, v4, 1.0 op_sel:[1,0,0]
	v_cvt_scalef32_pk_f16_fp4 v34, v4, 1.0 op_sel:[0,1,0]
	v_cvt_scalef32_pk_f16_fp4 v35, v4, 1.0 op_sel:[1,1,0]
	v_cvt_scalef32_pk_f16_fp4 v36, v5, 1.0
	v_cvt_scalef32_pk_f16_fp4 v37, v5, 1.0 op_sel:[1,0,0]
	v_cvt_scalef32_pk_f16_fp4 v38, v5, 1.0 op_sel:[0,1,0]
	v_cvt_scalef32_pk_f16_fp4 v39, v5, 1.0 op_sel:[1,1,0]
	v_cvt_scalef32_pk_f16_fp4 v40, v6, 1.0
	v_cvt_scalef32_pk_f16_fp4 v41, v6, 1.0 op_sel:[1,0,0]
	v_cvt_scalef32_pk_f16_fp4 v42, v6, 1.0 op_sel:[0,1,0]
	v_cvt_scalef32_pk_f16_fp4 v43, v6, 1.0 op_sel:[1,1,0]
	v_cvt_scalef32_pk_f16_fp4 v44, v7, 1.0
	v_cvt_scalef32_pk_f16_fp4 v45, v7, 1.0 op_sel:[1,0,0]
	v_cvt_scalef32_pk_f16_fp4 v46, v7, 1.0 op_sel:[0,1,0]
	v_cvt_scalef32_pk_f16_fp4 v47, v7, 1.0 op_sel:[1,1,0]
	buffer_load_dwordx4 v[0:3], v115, s[12:15], s4 offen
	v_pk_fma_f16 v124, v32, s0, v124
	v_pk_fma_f16 v123, v33, s0, v123
	v_pk_fma_f16 v121, v34, s0, v121
	v_pk_fma_f16 v120, v35, s0, v120
	v_pk_fma_f16 v119, v36, s0, v119
	v_pk_fma_f16 v118, v37, s0, v118
	v_pk_fma_f16 v117, v38, s0, v117
	v_pk_fma_f16 v116, v39, s0, v116
	v_pk_fma_f16 v113, v40, s0, v113
	v_pk_fma_f16 v112, v41, s0, v112
	v_pk_fma_f16 v67, v42, s0, v67
	v_pk_fma_f16 v66, v43, s0, v66
	v_pk_fma_f16 v65, v44, s0, v65
	v_pk_fma_f16 v64, v45, s0, v64
	v_pk_fma_f16 v125, v46, s0, v125
	v_pk_fma_f16 v122, v47, s0, v122
	s_waitcnt vmcnt(6)
	v_readlane_b32 s4, v49, 2
	v_readlane_b32 s0, v54, 0
	v_cvt_scalef32_pk_f16_fp4 v32, v8, 1.0
	v_cvt_scalef32_pk_f16_fp4 v33, v8, 1.0 op_sel:[1,0,0]
	v_cvt_scalef32_pk_f16_fp4 v34, v8, 1.0 op_sel:[0,1,0]
	v_cvt_scalef32_pk_f16_fp4 v35, v8, 1.0 op_sel:[1,1,0]
	v_cvt_scalef32_pk_f16_fp4 v36, v9, 1.0
	v_cvt_scalef32_pk_f16_fp4 v37, v9, 1.0 op_sel:[1,0,0]
	v_cvt_scalef32_pk_f16_fp4 v38, v9, 1.0 op_sel:[0,1,0]
	v_cvt_scalef32_pk_f16_fp4 v39, v9, 1.0 op_sel:[1,1,0]
	v_cvt_scalef32_pk_f16_fp4 v40, v10, 1.0
	v_cvt_scalef32_pk_f16_fp4 v41, v10, 1.0 op_sel:[1,0,0]
	v_cvt_scalef32_pk_f16_fp4 v42, v10, 1.0 op_sel:[0,1,0]
	v_cvt_scalef32_pk_f16_fp4 v43, v10, 1.0 op_sel:[1,1,0]
	v_cvt_scalef32_pk_f16_fp4 v44, v11, 1.0
	v_cvt_scalef32_pk_f16_fp4 v45, v11, 1.0 op_sel:[1,0,0]
	v_cvt_scalef32_pk_f16_fp4 v46, v11, 1.0 op_sel:[0,1,0]
	v_cvt_scalef32_pk_f16_fp4 v47, v11, 1.0 op_sel:[1,1,0]
	buffer_load_dwordx4 v[4:7], v115, s[12:15], s4 offen
	v_pk_fma_f16 v74, v32, s0, v74
	v_pk_fma_f16 v73, v33, s0, v73
	v_pk_fma_f16 v71, v34, s0, v71
	v_pk_fma_f16 v70, v35, s0, v70
	v_pk_fma_f16 v69, v36, s0, v69
	v_pk_fma_f16 v68, v37, s0, v68
	v_pk_fma_f16 v63, v38, s0, v63
	v_pk_fma_f16 v62, v39, s0, v62
	v_pk_fma_f16 v61, v40, s0, v61
	v_pk_fma_f16 v60, v41, s0, v60
	v_pk_fma_f16 v59, v42, s0, v59
	v_pk_fma_f16 v58, v43, s0, v58
	v_pk_fma_f16 v57, v44, s0, v57
	v_pk_fma_f16 v56, v45, s0, v56
	v_pk_fma_f16 v75, v46, s0, v75
	v_pk_fma_f16 v72, v47, s0, v72
	s_waitcnt vmcnt(6)
	v_readlane_b32 s4, v50, 2
	v_readlane_b32 s0, v55, 0
	v_cvt_scalef32_pk_f16_fp4 v32, v12, 1.0
	v_cvt_scalef32_pk_f16_fp4 v33, v12, 1.0 op_sel:[1,0,0]
	v_cvt_scalef32_pk_f16_fp4 v34, v12, 1.0 op_sel:[0,1,0]
	v_cvt_scalef32_pk_f16_fp4 v35, v12, 1.0 op_sel:[1,1,0]
	v_cvt_scalef32_pk_f16_fp4 v36, v13, 1.0
	v_cvt_scalef32_pk_f16_fp4 v37, v13, 1.0 op_sel:[1,0,0]
	v_cvt_scalef32_pk_f16_fp4 v38, v13, 1.0 op_sel:[0,1,0]
	v_cvt_scalef32_pk_f16_fp4 v39, v13, 1.0 op_sel:[1,1,0]
	v_cvt_scalef32_pk_f16_fp4 v40, v14, 1.0
	v_cvt_scalef32_pk_f16_fp4 v41, v14, 1.0 op_sel:[1,0,0]
	v_cvt_scalef32_pk_f16_fp4 v42, v14, 1.0 op_sel:[0,1,0]
	v_cvt_scalef32_pk_f16_fp4 v43, v14, 1.0 op_sel:[1,1,0]
	v_cvt_scalef32_pk_f16_fp4 v44, v15, 1.0
	v_cvt_scalef32_pk_f16_fp4 v45, v15, 1.0 op_sel:[1,0,0]
	v_cvt_scalef32_pk_f16_fp4 v46, v15, 1.0 op_sel:[0,1,0]
	v_cvt_scalef32_pk_f16_fp4 v47, v15, 1.0 op_sel:[1,1,0]
	buffer_load_dwordx4 v[8:11], v115, s[12:15], s4 offen
	v_pk_fma_f16 v162, v32, s0, v162
	v_pk_fma_f16 v161, v33, s0, v161
	v_pk_fma_f16 v160, v34, s0, v160
	v_pk_fma_f16 v159, v35, s0, v159
	v_pk_fma_f16 v158, v36, s0, v158
	v_pk_fma_f16 v157, v37, s0, v157
	v_pk_fma_f16 v156, v38, s0, v156
	v_pk_fma_f16 v147, v39, s0, v147
	v_pk_fma_f16 v146, v40, s0, v146
	v_pk_fma_f16 v145, v41, s0, v145
	v_pk_fma_f16 v144, v42, s0, v144
	v_pk_fma_f16 v143, v43, s0, v143
	v_pk_fma_f16 v142, v44, s0, v142
	v_pk_fma_f16 v141, v45, s0, v141
	v_pk_fma_f16 v149, v46, s0, v149
	v_pk_fma_f16 v148, v47, s0, v148
	s_waitcnt vmcnt(6)
	v_readlane_b32 s4, v51, 2
	v_readlane_b32 s0, v52, 1
	v_cvt_scalef32_pk_f16_fp4 v32, v16, 1.0
	v_cvt_scalef32_pk_f16_fp4 v33, v16, 1.0 op_sel:[1,0,0]
	v_cvt_scalef32_pk_f16_fp4 v34, v16, 1.0 op_sel:[0,1,0]
	v_cvt_scalef32_pk_f16_fp4 v35, v16, 1.0 op_sel:[1,1,0]
	v_cvt_scalef32_pk_f16_fp4 v36, v17, 1.0
	v_cvt_scalef32_pk_f16_fp4 v37, v17, 1.0 op_sel:[1,0,0]
	v_cvt_scalef32_pk_f16_fp4 v38, v17, 1.0 op_sel:[0,1,0]
	v_cvt_scalef32_pk_f16_fp4 v39, v17, 1.0 op_sel:[1,1,0]
	v_cvt_scalef32_pk_f16_fp4 v40, v18, 1.0
	v_cvt_scalef32_pk_f16_fp4 v41, v18, 1.0 op_sel:[1,0,0]
	v_cvt_scalef32_pk_f16_fp4 v42, v18, 1.0 op_sel:[0,1,0]
	v_cvt_scalef32_pk_f16_fp4 v43, v18, 1.0 op_sel:[1,1,0]
	v_cvt_scalef32_pk_f16_fp4 v44, v19, 1.0
	v_cvt_scalef32_pk_f16_fp4 v45, v19, 1.0 op_sel:[1,0,0]
	v_cvt_scalef32_pk_f16_fp4 v46, v19, 1.0 op_sel:[0,1,0]
	v_cvt_scalef32_pk_f16_fp4 v47, v19, 1.0 op_sel:[1,1,0]
	buffer_load_dwordx4 v[12:15], v115, s[12:15], s4 offen
	v_pk_fma_f16 v139, v32, s0, v139
	v_pk_fma_f16 v138, v33, s0, v138
	v_pk_fma_f16 v136, v34, s0, v136
	v_pk_fma_f16 v135, v35, s0, v135
	v_pk_fma_f16 v134, v36, s0, v134
	v_pk_fma_f16 v133, v37, s0, v133
	v_pk_fma_f16 v132, v38, s0, v132
	v_pk_fma_f16 v131, v39, s0, v131
	v_pk_fma_f16 v130, v40, s0, v130
	v_pk_fma_f16 v129, v41, s0, v129
	v_pk_fma_f16 v128, v42, s0, v128
	v_pk_fma_f16 v127, v43, s0, v127
	v_pk_fma_f16 v126, v44, s0, v126
	v_pk_fma_f16 v114, v45, s0, v114
	v_pk_fma_f16 v140, v46, s0, v140
	v_pk_fma_f16 v137, v47, s0, v137
	s_waitcnt vmcnt(6)
	v_readlane_b32 s4, v48, 3
	v_readlane_b32 s0, v53, 1
	v_cvt_scalef32_pk_f16_fp4 v32, v20, 1.0
	v_cvt_scalef32_pk_f16_fp4 v33, v20, 1.0 op_sel:[1,0,0]
	v_cvt_scalef32_pk_f16_fp4 v34, v20, 1.0 op_sel:[0,1,0]
	v_cvt_scalef32_pk_f16_fp4 v35, v20, 1.0 op_sel:[1,1,0]
	v_cvt_scalef32_pk_f16_fp4 v36, v21, 1.0
	v_cvt_scalef32_pk_f16_fp4 v37, v21, 1.0 op_sel:[1,0,0]
	v_cvt_scalef32_pk_f16_fp4 v38, v21, 1.0 op_sel:[0,1,0]
	v_cvt_scalef32_pk_f16_fp4 v39, v21, 1.0 op_sel:[1,1,0]
	v_cvt_scalef32_pk_f16_fp4 v40, v22, 1.0
	v_cvt_scalef32_pk_f16_fp4 v41, v22, 1.0 op_sel:[1,0,0]
	v_cvt_scalef32_pk_f16_fp4 v42, v22, 1.0 op_sel:[0,1,0]
	v_cvt_scalef32_pk_f16_fp4 v43, v22, 1.0 op_sel:[1,1,0]
	v_cvt_scalef32_pk_f16_fp4 v44, v23, 1.0
	v_cvt_scalef32_pk_f16_fp4 v45, v23, 1.0 op_sel:[1,0,0]
	v_cvt_scalef32_pk_f16_fp4 v46, v23, 1.0 op_sel:[0,1,0]
	v_cvt_scalef32_pk_f16_fp4 v47, v23, 1.0 op_sel:[1,1,0]
	buffer_load_dwordx4 v[16:19], v115, s[12:15], s4 offen
	v_pk_fma_f16 v124, v32, s0, v124
	v_pk_fma_f16 v123, v33, s0, v123
	v_pk_fma_f16 v121, v34, s0, v121
	v_pk_fma_f16 v120, v35, s0, v120
	v_pk_fma_f16 v119, v36, s0, v119
	v_pk_fma_f16 v118, v37, s0, v118
	v_pk_fma_f16 v117, v38, s0, v117
	v_pk_fma_f16 v116, v39, s0, v116
	v_pk_fma_f16 v113, v40, s0, v113
	v_pk_fma_f16 v112, v41, s0, v112
	v_pk_fma_f16 v67, v42, s0, v67
	v_pk_fma_f16 v66, v43, s0, v66
	v_pk_fma_f16 v65, v44, s0, v65
	v_pk_fma_f16 v64, v45, s0, v64
	v_pk_fma_f16 v125, v46, s0, v125
	v_pk_fma_f16 v122, v47, s0, v122
	s_waitcnt vmcnt(6)
	v_readlane_b32 s4, v49, 3
	v_readlane_b32 s0, v54, 1
	v_cvt_scalef32_pk_f16_fp4 v32, v24, 1.0
	v_cvt_scalef32_pk_f16_fp4 v33, v24, 1.0 op_sel:[1,0,0]
	v_cvt_scalef32_pk_f16_fp4 v34, v24, 1.0 op_sel:[0,1,0]
	v_cvt_scalef32_pk_f16_fp4 v35, v24, 1.0 op_sel:[1,1,0]
	v_cvt_scalef32_pk_f16_fp4 v36, v25, 1.0
	v_cvt_scalef32_pk_f16_fp4 v37, v25, 1.0 op_sel:[1,0,0]
	v_cvt_scalef32_pk_f16_fp4 v38, v25, 1.0 op_sel:[0,1,0]
	v_cvt_scalef32_pk_f16_fp4 v39, v25, 1.0 op_sel:[1,1,0]
	v_cvt_scalef32_pk_f16_fp4 v40, v26, 1.0
	v_cvt_scalef32_pk_f16_fp4 v41, v26, 1.0 op_sel:[1,0,0]
	v_cvt_scalef32_pk_f16_fp4 v42, v26, 1.0 op_sel:[0,1,0]
	v_cvt_scalef32_pk_f16_fp4 v43, v26, 1.0 op_sel:[1,1,0]
	v_cvt_scalef32_pk_f16_fp4 v44, v27, 1.0
	v_cvt_scalef32_pk_f16_fp4 v45, v27, 1.0 op_sel:[1,0,0]
	v_cvt_scalef32_pk_f16_fp4 v46, v27, 1.0 op_sel:[0,1,0]
	v_cvt_scalef32_pk_f16_fp4 v47, v27, 1.0 op_sel:[1,1,0]
	buffer_load_dwordx4 v[20:23], v115, s[12:15], s4 offen
	v_pk_fma_f16 v74, v32, s0, v74
	v_pk_fma_f16 v73, v33, s0, v73
	v_pk_fma_f16 v71, v34, s0, v71
	v_pk_fma_f16 v70, v35, s0, v70
	v_pk_fma_f16 v69, v36, s0, v69
	v_pk_fma_f16 v68, v37, s0, v68
	v_pk_fma_f16 v63, v38, s0, v63
	v_pk_fma_f16 v62, v39, s0, v62
	v_pk_fma_f16 v61, v40, s0, v61
	v_pk_fma_f16 v60, v41, s0, v60
	v_pk_fma_f16 v59, v42, s0, v59
	v_pk_fma_f16 v58, v43, s0, v58
	v_pk_fma_f16 v57, v44, s0, v57
	v_pk_fma_f16 v56, v45, s0, v56
	v_pk_fma_f16 v75, v46, s0, v75
	v_pk_fma_f16 v72, v47, s0, v72
	s_waitcnt vmcnt(6)
	v_readlane_b32 s4, v50, 3
	v_readlane_b32 s0, v55, 1
	v_cvt_scalef32_pk_f16_fp4 v32, v28, 1.0
	v_cvt_scalef32_pk_f16_fp4 v33, v28, 1.0 op_sel:[1,0,0]
	v_cvt_scalef32_pk_f16_fp4 v34, v28, 1.0 op_sel:[0,1,0]
	v_cvt_scalef32_pk_f16_fp4 v35, v28, 1.0 op_sel:[1,1,0]
	v_cvt_scalef32_pk_f16_fp4 v36, v29, 1.0
	v_cvt_scalef32_pk_f16_fp4 v37, v29, 1.0 op_sel:[1,0,0]
	v_cvt_scalef32_pk_f16_fp4 v38, v29, 1.0 op_sel:[0,1,0]
	v_cvt_scalef32_pk_f16_fp4 v39, v29, 1.0 op_sel:[1,1,0]
	v_cvt_scalef32_pk_f16_fp4 v40, v30, 1.0
	v_cvt_scalef32_pk_f16_fp4 v41, v30, 1.0 op_sel:[1,0,0]
	v_cvt_scalef32_pk_f16_fp4 v42, v30, 1.0 op_sel:[0,1,0]
	v_cvt_scalef32_pk_f16_fp4 v43, v30, 1.0 op_sel:[1,1,0]
	v_cvt_scalef32_pk_f16_fp4 v44, v31, 1.0
	v_cvt_scalef32_pk_f16_fp4 v45, v31, 1.0 op_sel:[1,0,0]
	v_cvt_scalef32_pk_f16_fp4 v46, v31, 1.0 op_sel:[0,1,0]
	v_cvt_scalef32_pk_f16_fp4 v47, v31, 1.0 op_sel:[1,1,0]
	buffer_load_dwordx4 v[24:27], v115, s[12:15], s4 offen
	v_pk_fma_f16 v162, v32, s0, v162
	v_pk_fma_f16 v161, v33, s0, v161
	v_pk_fma_f16 v160, v34, s0, v160
	v_pk_fma_f16 v159, v35, s0, v159
	v_pk_fma_f16 v158, v36, s0, v158
	v_pk_fma_f16 v157, v37, s0, v157
	v_pk_fma_f16 v156, v38, s0, v156
	v_pk_fma_f16 v147, v39, s0, v147
	v_pk_fma_f16 v146, v40, s0, v146
	v_pk_fma_f16 v145, v41, s0, v145
	v_pk_fma_f16 v144, v42, s0, v144
	v_pk_fma_f16 v143, v43, s0, v143
	v_pk_fma_f16 v142, v44, s0, v142
	v_pk_fma_f16 v141, v45, s0, v141
	v_pk_fma_f16 v149, v46, s0, v149
	v_pk_fma_f16 v148, v47, s0, v148
	s_waitcnt vmcnt(6)
	v_readlane_b32 s4, v51, 3
	v_readlane_b32 s0, v52, 2
	v_cvt_scalef32_pk_f16_fp4 v32, v0, 1.0
	v_cvt_scalef32_pk_f16_fp4 v33, v0, 1.0 op_sel:[1,0,0]
	v_cvt_scalef32_pk_f16_fp4 v34, v0, 1.0 op_sel:[0,1,0]
	v_cvt_scalef32_pk_f16_fp4 v35, v0, 1.0 op_sel:[1,1,0]
	v_cvt_scalef32_pk_f16_fp4 v36, v1, 1.0
	v_cvt_scalef32_pk_f16_fp4 v37, v1, 1.0 op_sel:[1,0,0]
	v_cvt_scalef32_pk_f16_fp4 v38, v1, 1.0 op_sel:[0,1,0]
	v_cvt_scalef32_pk_f16_fp4 v39, v1, 1.0 op_sel:[1,1,0]
	v_cvt_scalef32_pk_f16_fp4 v40, v2, 1.0
	v_cvt_scalef32_pk_f16_fp4 v41, v2, 1.0 op_sel:[1,0,0]
	v_cvt_scalef32_pk_f16_fp4 v42, v2, 1.0 op_sel:[0,1,0]
	v_cvt_scalef32_pk_f16_fp4 v43, v2, 1.0 op_sel:[1,1,0]
	v_cvt_scalef32_pk_f16_fp4 v44, v3, 1.0
	v_cvt_scalef32_pk_f16_fp4 v45, v3, 1.0 op_sel:[1,0,0]
	v_cvt_scalef32_pk_f16_fp4 v46, v3, 1.0 op_sel:[0,1,0]
	v_cvt_scalef32_pk_f16_fp4 v47, v3, 1.0 op_sel:[1,1,0]
	buffer_load_dwordx4 v[28:31], v115, s[12:15], s4 offen
	v_pk_fma_f16 v139, v32, s0, v139
	v_pk_fma_f16 v138, v33, s0, v138
	v_pk_fma_f16 v136, v34, s0, v136
	v_pk_fma_f16 v135, v35, s0, v135
	v_pk_fma_f16 v134, v36, s0, v134
	v_pk_fma_f16 v133, v37, s0, v133
	v_pk_fma_f16 v132, v38, s0, v132
	v_pk_fma_f16 v131, v39, s0, v131
	v_pk_fma_f16 v130, v40, s0, v130
	v_pk_fma_f16 v129, v41, s0, v129
	v_pk_fma_f16 v128, v42, s0, v128
	v_pk_fma_f16 v127, v43, s0, v127
	v_pk_fma_f16 v126, v44, s0, v126
	v_pk_fma_f16 v114, v45, s0, v114
	v_pk_fma_f16 v140, v46, s0, v140
	v_pk_fma_f16 v137, v47, s0, v137
	s_waitcnt vmcnt(6)
	v_readlane_b32 s4, v48, 4
	v_readlane_b32 s0, v53, 2
	v_cvt_scalef32_pk_f16_fp4 v32, v4, 1.0
	v_cvt_scalef32_pk_f16_fp4 v33, v4, 1.0 op_sel:[1,0,0]
	v_cvt_scalef32_pk_f16_fp4 v34, v4, 1.0 op_sel:[0,1,0]
	v_cvt_scalef32_pk_f16_fp4 v35, v4, 1.0 op_sel:[1,1,0]
	v_cvt_scalef32_pk_f16_fp4 v36, v5, 1.0
	v_cvt_scalef32_pk_f16_fp4 v37, v5, 1.0 op_sel:[1,0,0]
	v_cvt_scalef32_pk_f16_fp4 v38, v5, 1.0 op_sel:[0,1,0]
	v_cvt_scalef32_pk_f16_fp4 v39, v5, 1.0 op_sel:[1,1,0]
	v_cvt_scalef32_pk_f16_fp4 v40, v6, 1.0
	v_cvt_scalef32_pk_f16_fp4 v41, v6, 1.0 op_sel:[1,0,0]
	v_cvt_scalef32_pk_f16_fp4 v42, v6, 1.0 op_sel:[0,1,0]
	v_cvt_scalef32_pk_f16_fp4 v43, v6, 1.0 op_sel:[1,1,0]
	v_cvt_scalef32_pk_f16_fp4 v44, v7, 1.0
	v_cvt_scalef32_pk_f16_fp4 v45, v7, 1.0 op_sel:[1,0,0]
	v_cvt_scalef32_pk_f16_fp4 v46, v7, 1.0 op_sel:[0,1,0]
	v_cvt_scalef32_pk_f16_fp4 v47, v7, 1.0 op_sel:[1,1,0]
	buffer_load_dwordx4 v[0:3], v115, s[12:15], s4 offen
	v_pk_fma_f16 v124, v32, s0, v124
	v_pk_fma_f16 v123, v33, s0, v123
	v_pk_fma_f16 v121, v34, s0, v121
	v_pk_fma_f16 v120, v35, s0, v120
	v_pk_fma_f16 v119, v36, s0, v119
	v_pk_fma_f16 v118, v37, s0, v118
	v_pk_fma_f16 v117, v38, s0, v117
	v_pk_fma_f16 v116, v39, s0, v116
	v_pk_fma_f16 v113, v40, s0, v113
	v_pk_fma_f16 v112, v41, s0, v112
	v_pk_fma_f16 v67, v42, s0, v67
	v_pk_fma_f16 v66, v43, s0, v66
	v_pk_fma_f16 v65, v44, s0, v65
	v_pk_fma_f16 v64, v45, s0, v64
	v_pk_fma_f16 v125, v46, s0, v125
	v_pk_fma_f16 v122, v47, s0, v122
	s_waitcnt vmcnt(6)
	v_readlane_b32 s4, v49, 4
	v_readlane_b32 s0, v54, 2
	v_cvt_scalef32_pk_f16_fp4 v32, v8, 1.0
	v_cvt_scalef32_pk_f16_fp4 v33, v8, 1.0 op_sel:[1,0,0]
	v_cvt_scalef32_pk_f16_fp4 v34, v8, 1.0 op_sel:[0,1,0]
	v_cvt_scalef32_pk_f16_fp4 v35, v8, 1.0 op_sel:[1,1,0]
	v_cvt_scalef32_pk_f16_fp4 v36, v9, 1.0
	v_cvt_scalef32_pk_f16_fp4 v37, v9, 1.0 op_sel:[1,0,0]
	v_cvt_scalef32_pk_f16_fp4 v38, v9, 1.0 op_sel:[0,1,0]
	v_cvt_scalef32_pk_f16_fp4 v39, v9, 1.0 op_sel:[1,1,0]
	v_cvt_scalef32_pk_f16_fp4 v40, v10, 1.0
	v_cvt_scalef32_pk_f16_fp4 v41, v10, 1.0 op_sel:[1,0,0]
	v_cvt_scalef32_pk_f16_fp4 v42, v10, 1.0 op_sel:[0,1,0]
	v_cvt_scalef32_pk_f16_fp4 v43, v10, 1.0 op_sel:[1,1,0]
	v_cvt_scalef32_pk_f16_fp4 v44, v11, 1.0
	v_cvt_scalef32_pk_f16_fp4 v45, v11, 1.0 op_sel:[1,0,0]
	v_cvt_scalef32_pk_f16_fp4 v46, v11, 1.0 op_sel:[0,1,0]
	v_cvt_scalef32_pk_f16_fp4 v47, v11, 1.0 op_sel:[1,1,0]
	buffer_load_dwordx4 v[4:7], v115, s[12:15], s4 offen
	v_pk_fma_f16 v74, v32, s0, v74
	v_pk_fma_f16 v73, v33, s0, v73
	v_pk_fma_f16 v71, v34, s0, v71
	v_pk_fma_f16 v70, v35, s0, v70
	v_pk_fma_f16 v69, v36, s0, v69
	v_pk_fma_f16 v68, v37, s0, v68
	v_pk_fma_f16 v63, v38, s0, v63
	v_pk_fma_f16 v62, v39, s0, v62
	v_pk_fma_f16 v61, v40, s0, v61
	v_pk_fma_f16 v60, v41, s0, v60
	v_pk_fma_f16 v59, v42, s0, v59
	v_pk_fma_f16 v58, v43, s0, v58
	v_pk_fma_f16 v57, v44, s0, v57
	v_pk_fma_f16 v56, v45, s0, v56
	v_pk_fma_f16 v75, v46, s0, v75
	v_pk_fma_f16 v72, v47, s0, v72
	s_waitcnt vmcnt(6)
	v_readlane_b32 s4, v50, 4
	v_readlane_b32 s0, v55, 2
	v_cvt_scalef32_pk_f16_fp4 v32, v12, 1.0
	v_cvt_scalef32_pk_f16_fp4 v33, v12, 1.0 op_sel:[1,0,0]
	v_cvt_scalef32_pk_f16_fp4 v34, v12, 1.0 op_sel:[0,1,0]
	v_cvt_scalef32_pk_f16_fp4 v35, v12, 1.0 op_sel:[1,1,0]
	v_cvt_scalef32_pk_f16_fp4 v36, v13, 1.0
	v_cvt_scalef32_pk_f16_fp4 v37, v13, 1.0 op_sel:[1,0,0]
	v_cvt_scalef32_pk_f16_fp4 v38, v13, 1.0 op_sel:[0,1,0]
	v_cvt_scalef32_pk_f16_fp4 v39, v13, 1.0 op_sel:[1,1,0]
	v_cvt_scalef32_pk_f16_fp4 v40, v14, 1.0
	v_cvt_scalef32_pk_f16_fp4 v41, v14, 1.0 op_sel:[1,0,0]
	v_cvt_scalef32_pk_f16_fp4 v42, v14, 1.0 op_sel:[0,1,0]
	v_cvt_scalef32_pk_f16_fp4 v43, v14, 1.0 op_sel:[1,1,0]
	v_cvt_scalef32_pk_f16_fp4 v44, v15, 1.0
	v_cvt_scalef32_pk_f16_fp4 v45, v15, 1.0 op_sel:[1,0,0]
	v_cvt_scalef32_pk_f16_fp4 v46, v15, 1.0 op_sel:[0,1,0]
	v_cvt_scalef32_pk_f16_fp4 v47, v15, 1.0 op_sel:[1,1,0]
	buffer_load_dwordx4 v[8:11], v115, s[12:15], s4 offen
	v_pk_fma_f16 v162, v32, s0, v162
	v_pk_fma_f16 v161, v33, s0, v161
	v_pk_fma_f16 v160, v34, s0, v160
	v_pk_fma_f16 v159, v35, s0, v159
	v_pk_fma_f16 v158, v36, s0, v158
	v_pk_fma_f16 v157, v37, s0, v157
	v_pk_fma_f16 v156, v38, s0, v156
	v_pk_fma_f16 v147, v39, s0, v147
	v_pk_fma_f16 v146, v40, s0, v146
	v_pk_fma_f16 v145, v41, s0, v145
	v_pk_fma_f16 v144, v42, s0, v144
	v_pk_fma_f16 v143, v43, s0, v143
	v_pk_fma_f16 v142, v44, s0, v142
	v_pk_fma_f16 v141, v45, s0, v141
	v_pk_fma_f16 v149, v46, s0, v149
	v_pk_fma_f16 v148, v47, s0, v148
	s_waitcnt vmcnt(6)
	v_readlane_b32 s4, v51, 4
	v_readlane_b32 s0, v52, 3
	v_cvt_scalef32_pk_f16_fp4 v32, v16, 1.0
	v_cvt_scalef32_pk_f16_fp4 v33, v16, 1.0 op_sel:[1,0,0]
	v_cvt_scalef32_pk_f16_fp4 v34, v16, 1.0 op_sel:[0,1,0]
	v_cvt_scalef32_pk_f16_fp4 v35, v16, 1.0 op_sel:[1,1,0]
	v_cvt_scalef32_pk_f16_fp4 v36, v17, 1.0
	v_cvt_scalef32_pk_f16_fp4 v37, v17, 1.0 op_sel:[1,0,0]
	v_cvt_scalef32_pk_f16_fp4 v38, v17, 1.0 op_sel:[0,1,0]
	v_cvt_scalef32_pk_f16_fp4 v39, v17, 1.0 op_sel:[1,1,0]
	v_cvt_scalef32_pk_f16_fp4 v40, v18, 1.0
	v_cvt_scalef32_pk_f16_fp4 v41, v18, 1.0 op_sel:[1,0,0]
	v_cvt_scalef32_pk_f16_fp4 v42, v18, 1.0 op_sel:[0,1,0]
	v_cvt_scalef32_pk_f16_fp4 v43, v18, 1.0 op_sel:[1,1,0]
	v_cvt_scalef32_pk_f16_fp4 v44, v19, 1.0
	v_cvt_scalef32_pk_f16_fp4 v45, v19, 1.0 op_sel:[1,0,0]
	v_cvt_scalef32_pk_f16_fp4 v46, v19, 1.0 op_sel:[0,1,0]
	v_cvt_scalef32_pk_f16_fp4 v47, v19, 1.0 op_sel:[1,1,0]
	buffer_load_dwordx4 v[12:15], v115, s[12:15], s4 offen
	v_pk_fma_f16 v139, v32, s0, v139
	v_pk_fma_f16 v138, v33, s0, v138
	v_pk_fma_f16 v136, v34, s0, v136
	v_pk_fma_f16 v135, v35, s0, v135
	v_pk_fma_f16 v134, v36, s0, v134
	v_pk_fma_f16 v133, v37, s0, v133
	v_pk_fma_f16 v132, v38, s0, v132
	v_pk_fma_f16 v131, v39, s0, v131
	v_pk_fma_f16 v130, v40, s0, v130
	v_pk_fma_f16 v129, v41, s0, v129
	v_pk_fma_f16 v128, v42, s0, v128
	v_pk_fma_f16 v127, v43, s0, v127
	v_pk_fma_f16 v126, v44, s0, v126
	v_pk_fma_f16 v114, v45, s0, v114
	v_pk_fma_f16 v140, v46, s0, v140
	v_pk_fma_f16 v137, v47, s0, v137
	s_waitcnt vmcnt(6)
	v_readlane_b32 s4, v48, 5
	v_readlane_b32 s0, v53, 3
	v_cvt_scalef32_pk_f16_fp4 v32, v20, 1.0
	v_cvt_scalef32_pk_f16_fp4 v33, v20, 1.0 op_sel:[1,0,0]
	v_cvt_scalef32_pk_f16_fp4 v34, v20, 1.0 op_sel:[0,1,0]
	v_cvt_scalef32_pk_f16_fp4 v35, v20, 1.0 op_sel:[1,1,0]
	v_cvt_scalef32_pk_f16_fp4 v36, v21, 1.0
	v_cvt_scalef32_pk_f16_fp4 v37, v21, 1.0 op_sel:[1,0,0]
	v_cvt_scalef32_pk_f16_fp4 v38, v21, 1.0 op_sel:[0,1,0]
	v_cvt_scalef32_pk_f16_fp4 v39, v21, 1.0 op_sel:[1,1,0]
	v_cvt_scalef32_pk_f16_fp4 v40, v22, 1.0
	v_cvt_scalef32_pk_f16_fp4 v41, v22, 1.0 op_sel:[1,0,0]
	v_cvt_scalef32_pk_f16_fp4 v42, v22, 1.0 op_sel:[0,1,0]
	v_cvt_scalef32_pk_f16_fp4 v43, v22, 1.0 op_sel:[1,1,0]
	v_cvt_scalef32_pk_f16_fp4 v44, v23, 1.0
	v_cvt_scalef32_pk_f16_fp4 v45, v23, 1.0 op_sel:[1,0,0]
	v_cvt_scalef32_pk_f16_fp4 v46, v23, 1.0 op_sel:[0,1,0]
	v_cvt_scalef32_pk_f16_fp4 v47, v23, 1.0 op_sel:[1,1,0]
	buffer_load_dwordx4 v[16:19], v115, s[12:15], s4 offen
	v_pk_fma_f16 v124, v32, s0, v124
	v_pk_fma_f16 v123, v33, s0, v123
	v_pk_fma_f16 v121, v34, s0, v121
	v_pk_fma_f16 v120, v35, s0, v120
	v_pk_fma_f16 v119, v36, s0, v119
	v_pk_fma_f16 v118, v37, s0, v118
	v_pk_fma_f16 v117, v38, s0, v117
	v_pk_fma_f16 v116, v39, s0, v116
	v_pk_fma_f16 v113, v40, s0, v113
	v_pk_fma_f16 v112, v41, s0, v112
	v_pk_fma_f16 v67, v42, s0, v67
	v_pk_fma_f16 v66, v43, s0, v66
	v_pk_fma_f16 v65, v44, s0, v65
	v_pk_fma_f16 v64, v45, s0, v64
	v_pk_fma_f16 v125, v46, s0, v125
	v_pk_fma_f16 v122, v47, s0, v122
	s_waitcnt vmcnt(6)
	v_readlane_b32 s4, v49, 5
	v_readlane_b32 s0, v54, 3
	v_cvt_scalef32_pk_f16_fp4 v32, v24, 1.0
	v_cvt_scalef32_pk_f16_fp4 v33, v24, 1.0 op_sel:[1,0,0]
	v_cvt_scalef32_pk_f16_fp4 v34, v24, 1.0 op_sel:[0,1,0]
	v_cvt_scalef32_pk_f16_fp4 v35, v24, 1.0 op_sel:[1,1,0]
	v_cvt_scalef32_pk_f16_fp4 v36, v25, 1.0
	v_cvt_scalef32_pk_f16_fp4 v37, v25, 1.0 op_sel:[1,0,0]
	v_cvt_scalef32_pk_f16_fp4 v38, v25, 1.0 op_sel:[0,1,0]
	v_cvt_scalef32_pk_f16_fp4 v39, v25, 1.0 op_sel:[1,1,0]
	v_cvt_scalef32_pk_f16_fp4 v40, v26, 1.0
	v_cvt_scalef32_pk_f16_fp4 v41, v26, 1.0 op_sel:[1,0,0]
	v_cvt_scalef32_pk_f16_fp4 v42, v26, 1.0 op_sel:[0,1,0]
	v_cvt_scalef32_pk_f16_fp4 v43, v26, 1.0 op_sel:[1,1,0]
	v_cvt_scalef32_pk_f16_fp4 v44, v27, 1.0
	v_cvt_scalef32_pk_f16_fp4 v45, v27, 1.0 op_sel:[1,0,0]
	v_cvt_scalef32_pk_f16_fp4 v46, v27, 1.0 op_sel:[0,1,0]
	v_cvt_scalef32_pk_f16_fp4 v47, v27, 1.0 op_sel:[1,1,0]
	buffer_load_dwordx4 v[20:23], v115, s[12:15], s4 offen
	v_pk_fma_f16 v74, v32, s0, v74
	v_pk_fma_f16 v73, v33, s0, v73
	v_pk_fma_f16 v71, v34, s0, v71
	v_pk_fma_f16 v70, v35, s0, v70
	v_pk_fma_f16 v69, v36, s0, v69
	v_pk_fma_f16 v68, v37, s0, v68
	v_pk_fma_f16 v63, v38, s0, v63
	v_pk_fma_f16 v62, v39, s0, v62
	v_pk_fma_f16 v61, v40, s0, v61
	v_pk_fma_f16 v60, v41, s0, v60
	v_pk_fma_f16 v59, v42, s0, v59
	v_pk_fma_f16 v58, v43, s0, v58
	v_pk_fma_f16 v57, v44, s0, v57
	v_pk_fma_f16 v56, v45, s0, v56
	v_pk_fma_f16 v75, v46, s0, v75
	v_pk_fma_f16 v72, v47, s0, v72
	s_waitcnt vmcnt(6)
	v_readlane_b32 s4, v50, 5
	v_readlane_b32 s0, v55, 3
	v_cvt_scalef32_pk_f16_fp4 v32, v28, 1.0
	v_cvt_scalef32_pk_f16_fp4 v33, v28, 1.0 op_sel:[1,0,0]
	v_cvt_scalef32_pk_f16_fp4 v34, v28, 1.0 op_sel:[0,1,0]
	v_cvt_scalef32_pk_f16_fp4 v35, v28, 1.0 op_sel:[1,1,0]
	v_cvt_scalef32_pk_f16_fp4 v36, v29, 1.0
	v_cvt_scalef32_pk_f16_fp4 v37, v29, 1.0 op_sel:[1,0,0]
	v_cvt_scalef32_pk_f16_fp4 v38, v29, 1.0 op_sel:[0,1,0]
	v_cvt_scalef32_pk_f16_fp4 v39, v29, 1.0 op_sel:[1,1,0]
	v_cvt_scalef32_pk_f16_fp4 v40, v30, 1.0
	v_cvt_scalef32_pk_f16_fp4 v41, v30, 1.0 op_sel:[1,0,0]
	v_cvt_scalef32_pk_f16_fp4 v42, v30, 1.0 op_sel:[0,1,0]
	v_cvt_scalef32_pk_f16_fp4 v43, v30, 1.0 op_sel:[1,1,0]
	v_cvt_scalef32_pk_f16_fp4 v44, v31, 1.0
	v_cvt_scalef32_pk_f16_fp4 v45, v31, 1.0 op_sel:[1,0,0]
	v_cvt_scalef32_pk_f16_fp4 v46, v31, 1.0 op_sel:[0,1,0]
	v_cvt_scalef32_pk_f16_fp4 v47, v31, 1.0 op_sel:[1,1,0]
	buffer_load_dwordx4 v[24:27], v115, s[12:15], s4 offen
	v_pk_fma_f16 v162, v32, s0, v162
	v_pk_fma_f16 v161, v33, s0, v161
	v_pk_fma_f16 v160, v34, s0, v160
	v_pk_fma_f16 v159, v35, s0, v159
	v_pk_fma_f16 v158, v36, s0, v158
	v_pk_fma_f16 v157, v37, s0, v157
	v_pk_fma_f16 v156, v38, s0, v156
	v_pk_fma_f16 v147, v39, s0, v147
	v_pk_fma_f16 v146, v40, s0, v146
	v_pk_fma_f16 v145, v41, s0, v145
	v_pk_fma_f16 v144, v42, s0, v144
	v_pk_fma_f16 v143, v43, s0, v143
	v_pk_fma_f16 v142, v44, s0, v142
	v_pk_fma_f16 v141, v45, s0, v141
	v_pk_fma_f16 v149, v46, s0, v149
	v_pk_fma_f16 v148, v47, s0, v148
	s_waitcnt vmcnt(6)
	v_readlane_b32 s4, v51, 5
	v_readlane_b32 s0, v52, 4
	v_cvt_scalef32_pk_f16_fp4 v32, v0, 1.0
	v_cvt_scalef32_pk_f16_fp4 v33, v0, 1.0 op_sel:[1,0,0]
	v_cvt_scalef32_pk_f16_fp4 v34, v0, 1.0 op_sel:[0,1,0]
	v_cvt_scalef32_pk_f16_fp4 v35, v0, 1.0 op_sel:[1,1,0]
	v_cvt_scalef32_pk_f16_fp4 v36, v1, 1.0
	v_cvt_scalef32_pk_f16_fp4 v37, v1, 1.0 op_sel:[1,0,0]
	v_cvt_scalef32_pk_f16_fp4 v38, v1, 1.0 op_sel:[0,1,0]
	v_cvt_scalef32_pk_f16_fp4 v39, v1, 1.0 op_sel:[1,1,0]
	v_cvt_scalef32_pk_f16_fp4 v40, v2, 1.0
	v_cvt_scalef32_pk_f16_fp4 v41, v2, 1.0 op_sel:[1,0,0]
	v_cvt_scalef32_pk_f16_fp4 v42, v2, 1.0 op_sel:[0,1,0]
	v_cvt_scalef32_pk_f16_fp4 v43, v2, 1.0 op_sel:[1,1,0]
	v_cvt_scalef32_pk_f16_fp4 v44, v3, 1.0
	v_cvt_scalef32_pk_f16_fp4 v45, v3, 1.0 op_sel:[1,0,0]
	v_cvt_scalef32_pk_f16_fp4 v46, v3, 1.0 op_sel:[0,1,0]
	v_cvt_scalef32_pk_f16_fp4 v47, v3, 1.0 op_sel:[1,1,0]
	buffer_load_dwordx4 v[28:31], v115, s[12:15], s4 offen
	v_pk_fma_f16 v139, v32, s0, v139
	v_pk_fma_f16 v138, v33, s0, v138
	v_pk_fma_f16 v136, v34, s0, v136
	v_pk_fma_f16 v135, v35, s0, v135
	v_pk_fma_f16 v134, v36, s0, v134
	v_pk_fma_f16 v133, v37, s0, v133
	v_pk_fma_f16 v132, v38, s0, v132
	v_pk_fma_f16 v131, v39, s0, v131
	v_pk_fma_f16 v130, v40, s0, v130
	v_pk_fma_f16 v129, v41, s0, v129
	v_pk_fma_f16 v128, v42, s0, v128
	v_pk_fma_f16 v127, v43, s0, v127
	v_pk_fma_f16 v126, v44, s0, v126
	v_pk_fma_f16 v114, v45, s0, v114
	v_pk_fma_f16 v140, v46, s0, v140
	v_pk_fma_f16 v137, v47, s0, v137
	s_waitcnt vmcnt(6)
	v_readlane_b32 s4, v48, 6
	v_readlane_b32 s0, v53, 4
	v_cvt_scalef32_pk_f16_fp4 v32, v4, 1.0
	v_cvt_scalef32_pk_f16_fp4 v33, v4, 1.0 op_sel:[1,0,0]
	v_cvt_scalef32_pk_f16_fp4 v34, v4, 1.0 op_sel:[0,1,0]
	v_cvt_scalef32_pk_f16_fp4 v35, v4, 1.0 op_sel:[1,1,0]
	v_cvt_scalef32_pk_f16_fp4 v36, v5, 1.0
	v_cvt_scalef32_pk_f16_fp4 v37, v5, 1.0 op_sel:[1,0,0]
	v_cvt_scalef32_pk_f16_fp4 v38, v5, 1.0 op_sel:[0,1,0]
	v_cvt_scalef32_pk_f16_fp4 v39, v5, 1.0 op_sel:[1,1,0]
	v_cvt_scalef32_pk_f16_fp4 v40, v6, 1.0
	v_cvt_scalef32_pk_f16_fp4 v41, v6, 1.0 op_sel:[1,0,0]
	v_cvt_scalef32_pk_f16_fp4 v42, v6, 1.0 op_sel:[0,1,0]
	v_cvt_scalef32_pk_f16_fp4 v43, v6, 1.0 op_sel:[1,1,0]
	v_cvt_scalef32_pk_f16_fp4 v44, v7, 1.0
	v_cvt_scalef32_pk_f16_fp4 v45, v7, 1.0 op_sel:[1,0,0]
	v_cvt_scalef32_pk_f16_fp4 v46, v7, 1.0 op_sel:[0,1,0]
	v_cvt_scalef32_pk_f16_fp4 v47, v7, 1.0 op_sel:[1,1,0]
	buffer_load_dwordx4 v[0:3], v115, s[12:15], s4 offen
	v_pk_fma_f16 v124, v32, s0, v124
	v_pk_fma_f16 v123, v33, s0, v123
	v_pk_fma_f16 v121, v34, s0, v121
	v_pk_fma_f16 v120, v35, s0, v120
	v_pk_fma_f16 v119, v36, s0, v119
	v_pk_fma_f16 v118, v37, s0, v118
	v_pk_fma_f16 v117, v38, s0, v117
	v_pk_fma_f16 v116, v39, s0, v116
	v_pk_fma_f16 v113, v40, s0, v113
	v_pk_fma_f16 v112, v41, s0, v112
	v_pk_fma_f16 v67, v42, s0, v67
	v_pk_fma_f16 v66, v43, s0, v66
	v_pk_fma_f16 v65, v44, s0, v65
	v_pk_fma_f16 v64, v45, s0, v64
	v_pk_fma_f16 v125, v46, s0, v125
	v_pk_fma_f16 v122, v47, s0, v122
	s_waitcnt vmcnt(6)
	v_readlane_b32 s4, v49, 6
	v_readlane_b32 s0, v54, 4
	v_cvt_scalef32_pk_f16_fp4 v32, v8, 1.0
	v_cvt_scalef32_pk_f16_fp4 v33, v8, 1.0 op_sel:[1,0,0]
	v_cvt_scalef32_pk_f16_fp4 v34, v8, 1.0 op_sel:[0,1,0]
	v_cvt_scalef32_pk_f16_fp4 v35, v8, 1.0 op_sel:[1,1,0]
	v_cvt_scalef32_pk_f16_fp4 v36, v9, 1.0
	v_cvt_scalef32_pk_f16_fp4 v37, v9, 1.0 op_sel:[1,0,0]
	v_cvt_scalef32_pk_f16_fp4 v38, v9, 1.0 op_sel:[0,1,0]
	v_cvt_scalef32_pk_f16_fp4 v39, v9, 1.0 op_sel:[1,1,0]
	v_cvt_scalef32_pk_f16_fp4 v40, v10, 1.0
	v_cvt_scalef32_pk_f16_fp4 v41, v10, 1.0 op_sel:[1,0,0]
	v_cvt_scalef32_pk_f16_fp4 v42, v10, 1.0 op_sel:[0,1,0]
	v_cvt_scalef32_pk_f16_fp4 v43, v10, 1.0 op_sel:[1,1,0]
	v_cvt_scalef32_pk_f16_fp4 v44, v11, 1.0
	v_cvt_scalef32_pk_f16_fp4 v45, v11, 1.0 op_sel:[1,0,0]
	v_cvt_scalef32_pk_f16_fp4 v46, v11, 1.0 op_sel:[0,1,0]
	v_cvt_scalef32_pk_f16_fp4 v47, v11, 1.0 op_sel:[1,1,0]
	buffer_load_dwordx4 v[4:7], v115, s[12:15], s4 offen
	v_pk_fma_f16 v74, v32, s0, v74
	v_pk_fma_f16 v73, v33, s0, v73
	v_pk_fma_f16 v71, v34, s0, v71
	v_pk_fma_f16 v70, v35, s0, v70
	v_pk_fma_f16 v69, v36, s0, v69
	v_pk_fma_f16 v68, v37, s0, v68
	v_pk_fma_f16 v63, v38, s0, v63
	v_pk_fma_f16 v62, v39, s0, v62
	v_pk_fma_f16 v61, v40, s0, v61
	v_pk_fma_f16 v60, v41, s0, v60
	v_pk_fma_f16 v59, v42, s0, v59
	v_pk_fma_f16 v58, v43, s0, v58
	v_pk_fma_f16 v57, v44, s0, v57
	v_pk_fma_f16 v56, v45, s0, v56
	v_pk_fma_f16 v75, v46, s0, v75
	v_pk_fma_f16 v72, v47, s0, v72
	s_waitcnt vmcnt(6)
	v_readlane_b32 s4, v50, 6
	v_readlane_b32 s0, v55, 4
	v_cvt_scalef32_pk_f16_fp4 v32, v12, 1.0
	v_cvt_scalef32_pk_f16_fp4 v33, v12, 1.0 op_sel:[1,0,0]
	v_cvt_scalef32_pk_f16_fp4 v34, v12, 1.0 op_sel:[0,1,0]
	v_cvt_scalef32_pk_f16_fp4 v35, v12, 1.0 op_sel:[1,1,0]
	v_cvt_scalef32_pk_f16_fp4 v36, v13, 1.0
	v_cvt_scalef32_pk_f16_fp4 v37, v13, 1.0 op_sel:[1,0,0]
	v_cvt_scalef32_pk_f16_fp4 v38, v13, 1.0 op_sel:[0,1,0]
	v_cvt_scalef32_pk_f16_fp4 v39, v13, 1.0 op_sel:[1,1,0]
	v_cvt_scalef32_pk_f16_fp4 v40, v14, 1.0
	v_cvt_scalef32_pk_f16_fp4 v41, v14, 1.0 op_sel:[1,0,0]
	v_cvt_scalef32_pk_f16_fp4 v42, v14, 1.0 op_sel:[0,1,0]
	v_cvt_scalef32_pk_f16_fp4 v43, v14, 1.0 op_sel:[1,1,0]
	v_cvt_scalef32_pk_f16_fp4 v44, v15, 1.0
	v_cvt_scalef32_pk_f16_fp4 v45, v15, 1.0 op_sel:[1,0,0]
	v_cvt_scalef32_pk_f16_fp4 v46, v15, 1.0 op_sel:[0,1,0]
	v_cvt_scalef32_pk_f16_fp4 v47, v15, 1.0 op_sel:[1,1,0]
	buffer_load_dwordx4 v[8:11], v115, s[12:15], s4 offen
	v_pk_fma_f16 v162, v32, s0, v162
	v_pk_fma_f16 v161, v33, s0, v161
	v_pk_fma_f16 v160, v34, s0, v160
	v_pk_fma_f16 v159, v35, s0, v159
	v_pk_fma_f16 v158, v36, s0, v158
	v_pk_fma_f16 v157, v37, s0, v157
	v_pk_fma_f16 v156, v38, s0, v156
	v_pk_fma_f16 v147, v39, s0, v147
	v_pk_fma_f16 v146, v40, s0, v146
	v_pk_fma_f16 v145, v41, s0, v145
	v_pk_fma_f16 v144, v42, s0, v144
	v_pk_fma_f16 v143, v43, s0, v143
	v_pk_fma_f16 v142, v44, s0, v142
	v_pk_fma_f16 v141, v45, s0, v141
	v_pk_fma_f16 v149, v46, s0, v149
	v_pk_fma_f16 v148, v47, s0, v148
	s_waitcnt vmcnt(6)
	v_readlane_b32 s4, v51, 6
	v_readlane_b32 s0, v52, 5
	v_cvt_scalef32_pk_f16_fp4 v32, v16, 1.0
	v_cvt_scalef32_pk_f16_fp4 v33, v16, 1.0 op_sel:[1,0,0]
	v_cvt_scalef32_pk_f16_fp4 v34, v16, 1.0 op_sel:[0,1,0]
	v_cvt_scalef32_pk_f16_fp4 v35, v16, 1.0 op_sel:[1,1,0]
	v_cvt_scalef32_pk_f16_fp4 v36, v17, 1.0
	v_cvt_scalef32_pk_f16_fp4 v37, v17, 1.0 op_sel:[1,0,0]
	v_cvt_scalef32_pk_f16_fp4 v38, v17, 1.0 op_sel:[0,1,0]
	v_cvt_scalef32_pk_f16_fp4 v39, v17, 1.0 op_sel:[1,1,0]
	v_cvt_scalef32_pk_f16_fp4 v40, v18, 1.0
	v_cvt_scalef32_pk_f16_fp4 v41, v18, 1.0 op_sel:[1,0,0]
	v_cvt_scalef32_pk_f16_fp4 v42, v18, 1.0 op_sel:[0,1,0]
	v_cvt_scalef32_pk_f16_fp4 v43, v18, 1.0 op_sel:[1,1,0]
	v_cvt_scalef32_pk_f16_fp4 v44, v19, 1.0
	v_cvt_scalef32_pk_f16_fp4 v45, v19, 1.0 op_sel:[1,0,0]
	v_cvt_scalef32_pk_f16_fp4 v46, v19, 1.0 op_sel:[0,1,0]
	v_cvt_scalef32_pk_f16_fp4 v47, v19, 1.0 op_sel:[1,1,0]
	buffer_load_dwordx4 v[12:15], v115, s[12:15], s4 offen
	v_pk_fma_f16 v139, v32, s0, v139
	v_pk_fma_f16 v138, v33, s0, v138
	v_pk_fma_f16 v136, v34, s0, v136
	v_pk_fma_f16 v135, v35, s0, v135
	v_pk_fma_f16 v134, v36, s0, v134
	v_pk_fma_f16 v133, v37, s0, v133
	v_pk_fma_f16 v132, v38, s0, v132
	v_pk_fma_f16 v131, v39, s0, v131
	v_pk_fma_f16 v130, v40, s0, v130
	v_pk_fma_f16 v129, v41, s0, v129
	v_pk_fma_f16 v128, v42, s0, v128
	v_pk_fma_f16 v127, v43, s0, v127
	v_pk_fma_f16 v126, v44, s0, v126
	v_pk_fma_f16 v114, v45, s0, v114
	v_pk_fma_f16 v140, v46, s0, v140
	v_pk_fma_f16 v137, v47, s0, v137
	s_waitcnt vmcnt(6)
	v_readlane_b32 s4, v48, 7
	v_readlane_b32 s0, v53, 5
	v_cvt_scalef32_pk_f16_fp4 v32, v20, 1.0
	v_cvt_scalef32_pk_f16_fp4 v33, v20, 1.0 op_sel:[1,0,0]
	v_cvt_scalef32_pk_f16_fp4 v34, v20, 1.0 op_sel:[0,1,0]
	v_cvt_scalef32_pk_f16_fp4 v35, v20, 1.0 op_sel:[1,1,0]
	v_cvt_scalef32_pk_f16_fp4 v36, v21, 1.0
	v_cvt_scalef32_pk_f16_fp4 v37, v21, 1.0 op_sel:[1,0,0]
	v_cvt_scalef32_pk_f16_fp4 v38, v21, 1.0 op_sel:[0,1,0]
	v_cvt_scalef32_pk_f16_fp4 v39, v21, 1.0 op_sel:[1,1,0]
	v_cvt_scalef32_pk_f16_fp4 v40, v22, 1.0
	v_cvt_scalef32_pk_f16_fp4 v41, v22, 1.0 op_sel:[1,0,0]
	v_cvt_scalef32_pk_f16_fp4 v42, v22, 1.0 op_sel:[0,1,0]
	v_cvt_scalef32_pk_f16_fp4 v43, v22, 1.0 op_sel:[1,1,0]
	v_cvt_scalef32_pk_f16_fp4 v44, v23, 1.0
	v_cvt_scalef32_pk_f16_fp4 v45, v23, 1.0 op_sel:[1,0,0]
	v_cvt_scalef32_pk_f16_fp4 v46, v23, 1.0 op_sel:[0,1,0]
	v_cvt_scalef32_pk_f16_fp4 v47, v23, 1.0 op_sel:[1,1,0]
	buffer_load_dwordx4 v[16:19], v115, s[12:15], s4 offen
	v_pk_fma_f16 v124, v32, s0, v124
	v_pk_fma_f16 v123, v33, s0, v123
	v_pk_fma_f16 v121, v34, s0, v121
	v_pk_fma_f16 v120, v35, s0, v120
	v_pk_fma_f16 v119, v36, s0, v119
	v_pk_fma_f16 v118, v37, s0, v118
	v_pk_fma_f16 v117, v38, s0, v117
	v_pk_fma_f16 v116, v39, s0, v116
	v_pk_fma_f16 v113, v40, s0, v113
	v_pk_fma_f16 v112, v41, s0, v112
	v_pk_fma_f16 v67, v42, s0, v67
	v_pk_fma_f16 v66, v43, s0, v66
	v_pk_fma_f16 v65, v44, s0, v65
	v_pk_fma_f16 v64, v45, s0, v64
	v_pk_fma_f16 v125, v46, s0, v125
	v_pk_fma_f16 v122, v47, s0, v122
	s_waitcnt vmcnt(6)
	v_readlane_b32 s4, v49, 7
	v_readlane_b32 s0, v54, 5
	v_cvt_scalef32_pk_f16_fp4 v32, v24, 1.0
	v_cvt_scalef32_pk_f16_fp4 v33, v24, 1.0 op_sel:[1,0,0]
	v_cvt_scalef32_pk_f16_fp4 v34, v24, 1.0 op_sel:[0,1,0]
	v_cvt_scalef32_pk_f16_fp4 v35, v24, 1.0 op_sel:[1,1,0]
	v_cvt_scalef32_pk_f16_fp4 v36, v25, 1.0
	v_cvt_scalef32_pk_f16_fp4 v37, v25, 1.0 op_sel:[1,0,0]
	v_cvt_scalef32_pk_f16_fp4 v38, v25, 1.0 op_sel:[0,1,0]
	v_cvt_scalef32_pk_f16_fp4 v39, v25, 1.0 op_sel:[1,1,0]
	v_cvt_scalef32_pk_f16_fp4 v40, v26, 1.0
	v_cvt_scalef32_pk_f16_fp4 v41, v26, 1.0 op_sel:[1,0,0]
	v_cvt_scalef32_pk_f16_fp4 v42, v26, 1.0 op_sel:[0,1,0]
	v_cvt_scalef32_pk_f16_fp4 v43, v26, 1.0 op_sel:[1,1,0]
	v_cvt_scalef32_pk_f16_fp4 v44, v27, 1.0
	v_cvt_scalef32_pk_f16_fp4 v45, v27, 1.0 op_sel:[1,0,0]
	v_cvt_scalef32_pk_f16_fp4 v46, v27, 1.0 op_sel:[0,1,0]
	v_cvt_scalef32_pk_f16_fp4 v47, v27, 1.0 op_sel:[1,1,0]
	buffer_load_dwordx4 v[20:23], v115, s[12:15], s4 offen
	v_pk_fma_f16 v74, v32, s0, v74
	v_pk_fma_f16 v73, v33, s0, v73
	v_pk_fma_f16 v71, v34, s0, v71
	v_pk_fma_f16 v70, v35, s0, v70
	v_pk_fma_f16 v69, v36, s0, v69
	v_pk_fma_f16 v68, v37, s0, v68
	v_pk_fma_f16 v63, v38, s0, v63
	v_pk_fma_f16 v62, v39, s0, v62
	v_pk_fma_f16 v61, v40, s0, v61
	v_pk_fma_f16 v60, v41, s0, v60
	v_pk_fma_f16 v59, v42, s0, v59
	v_pk_fma_f16 v58, v43, s0, v58
	v_pk_fma_f16 v57, v44, s0, v57
	v_pk_fma_f16 v56, v45, s0, v56
	v_pk_fma_f16 v75, v46, s0, v75
	v_pk_fma_f16 v72, v47, s0, v72
	s_waitcnt vmcnt(6)
	v_readlane_b32 s4, v50, 7
	v_readlane_b32 s0, v55, 5
	v_cvt_scalef32_pk_f16_fp4 v32, v28, 1.0
	v_cvt_scalef32_pk_f16_fp4 v33, v28, 1.0 op_sel:[1,0,0]
	v_cvt_scalef32_pk_f16_fp4 v34, v28, 1.0 op_sel:[0,1,0]
	v_cvt_scalef32_pk_f16_fp4 v35, v28, 1.0 op_sel:[1,1,0]
	v_cvt_scalef32_pk_f16_fp4 v36, v29, 1.0
	v_cvt_scalef32_pk_f16_fp4 v37, v29, 1.0 op_sel:[1,0,0]
	v_cvt_scalef32_pk_f16_fp4 v38, v29, 1.0 op_sel:[0,1,0]
	v_cvt_scalef32_pk_f16_fp4 v39, v29, 1.0 op_sel:[1,1,0]
	v_cvt_scalef32_pk_f16_fp4 v40, v30, 1.0
	v_cvt_scalef32_pk_f16_fp4 v41, v30, 1.0 op_sel:[1,0,0]
	v_cvt_scalef32_pk_f16_fp4 v42, v30, 1.0 op_sel:[0,1,0]
	v_cvt_scalef32_pk_f16_fp4 v43, v30, 1.0 op_sel:[1,1,0]
	v_cvt_scalef32_pk_f16_fp4 v44, v31, 1.0
	v_cvt_scalef32_pk_f16_fp4 v45, v31, 1.0 op_sel:[1,0,0]
	v_cvt_scalef32_pk_f16_fp4 v46, v31, 1.0 op_sel:[0,1,0]
	v_cvt_scalef32_pk_f16_fp4 v47, v31, 1.0 op_sel:[1,1,0]
	buffer_load_dwordx4 v[24:27], v115, s[12:15], s4 offen
	v_pk_fma_f16 v162, v32, s0, v162
	v_pk_fma_f16 v161, v33, s0, v161
	v_pk_fma_f16 v160, v34, s0, v160
	v_pk_fma_f16 v159, v35, s0, v159
	v_pk_fma_f16 v158, v36, s0, v158
	v_pk_fma_f16 v157, v37, s0, v157
	v_pk_fma_f16 v156, v38, s0, v156
	v_pk_fma_f16 v147, v39, s0, v147
	v_pk_fma_f16 v146, v40, s0, v146
	v_pk_fma_f16 v145, v41, s0, v145
	v_pk_fma_f16 v144, v42, s0, v144
	v_pk_fma_f16 v143, v43, s0, v143
	v_pk_fma_f16 v142, v44, s0, v142
	v_pk_fma_f16 v141, v45, s0, v141
	v_pk_fma_f16 v149, v46, s0, v149
	v_pk_fma_f16 v148, v47, s0, v148
	s_waitcnt vmcnt(6)
	v_readlane_b32 s4, v51, 7
	v_readlane_b32 s0, v52, 6
	v_cvt_scalef32_pk_f16_fp4 v32, v0, 1.0
	v_cvt_scalef32_pk_f16_fp4 v33, v0, 1.0 op_sel:[1,0,0]
	v_cvt_scalef32_pk_f16_fp4 v34, v0, 1.0 op_sel:[0,1,0]
	v_cvt_scalef32_pk_f16_fp4 v35, v0, 1.0 op_sel:[1,1,0]
	v_cvt_scalef32_pk_f16_fp4 v36, v1, 1.0
	v_cvt_scalef32_pk_f16_fp4 v37, v1, 1.0 op_sel:[1,0,0]
	v_cvt_scalef32_pk_f16_fp4 v38, v1, 1.0 op_sel:[0,1,0]
	v_cvt_scalef32_pk_f16_fp4 v39, v1, 1.0 op_sel:[1,1,0]
	v_cvt_scalef32_pk_f16_fp4 v40, v2, 1.0
	v_cvt_scalef32_pk_f16_fp4 v41, v2, 1.0 op_sel:[1,0,0]
	v_cvt_scalef32_pk_f16_fp4 v42, v2, 1.0 op_sel:[0,1,0]
	v_cvt_scalef32_pk_f16_fp4 v43, v2, 1.0 op_sel:[1,1,0]
	v_cvt_scalef32_pk_f16_fp4 v44, v3, 1.0
	v_cvt_scalef32_pk_f16_fp4 v45, v3, 1.0 op_sel:[1,0,0]
	v_cvt_scalef32_pk_f16_fp4 v46, v3, 1.0 op_sel:[0,1,0]
	v_cvt_scalef32_pk_f16_fp4 v47, v3, 1.0 op_sel:[1,1,0]
	buffer_load_dwordx4 v[28:31], v115, s[12:15], s4 offen
	v_pk_fma_f16 v139, v32, s0, v139
	v_pk_fma_f16 v138, v33, s0, v138
	v_pk_fma_f16 v136, v34, s0, v136
	v_pk_fma_f16 v135, v35, s0, v135
	v_pk_fma_f16 v134, v36, s0, v134
	v_pk_fma_f16 v133, v37, s0, v133
	v_pk_fma_f16 v132, v38, s0, v132
	v_pk_fma_f16 v131, v39, s0, v131
	v_pk_fma_f16 v130, v40, s0, v130
	v_pk_fma_f16 v129, v41, s0, v129
	v_pk_fma_f16 v128, v42, s0, v128
	v_pk_fma_f16 v127, v43, s0, v127
	v_pk_fma_f16 v126, v44, s0, v126
	v_pk_fma_f16 v114, v45, s0, v114
	v_pk_fma_f16 v140, v46, s0, v140
	v_pk_fma_f16 v137, v47, s0, v137
	s_waitcnt vmcnt(6)
	v_readlane_b32 s4, v48, 8
	v_readlane_b32 s0, v53, 6
	v_cvt_scalef32_pk_f16_fp4 v32, v4, 1.0
	v_cvt_scalef32_pk_f16_fp4 v33, v4, 1.0 op_sel:[1,0,0]
	v_cvt_scalef32_pk_f16_fp4 v34, v4, 1.0 op_sel:[0,1,0]
	v_cvt_scalef32_pk_f16_fp4 v35, v4, 1.0 op_sel:[1,1,0]
	v_cvt_scalef32_pk_f16_fp4 v36, v5, 1.0
	v_cvt_scalef32_pk_f16_fp4 v37, v5, 1.0 op_sel:[1,0,0]
	v_cvt_scalef32_pk_f16_fp4 v38, v5, 1.0 op_sel:[0,1,0]
	v_cvt_scalef32_pk_f16_fp4 v39, v5, 1.0 op_sel:[1,1,0]
	v_cvt_scalef32_pk_f16_fp4 v40, v6, 1.0
	v_cvt_scalef32_pk_f16_fp4 v41, v6, 1.0 op_sel:[1,0,0]
	v_cvt_scalef32_pk_f16_fp4 v42, v6, 1.0 op_sel:[0,1,0]
	v_cvt_scalef32_pk_f16_fp4 v43, v6, 1.0 op_sel:[1,1,0]
	v_cvt_scalef32_pk_f16_fp4 v44, v7, 1.0
	v_cvt_scalef32_pk_f16_fp4 v45, v7, 1.0 op_sel:[1,0,0]
	v_cvt_scalef32_pk_f16_fp4 v46, v7, 1.0 op_sel:[0,1,0]
	v_cvt_scalef32_pk_f16_fp4 v47, v7, 1.0 op_sel:[1,1,0]
	buffer_load_dwordx4 v[0:3], v115, s[12:15], s4 offen
	v_pk_fma_f16 v124, v32, s0, v124
	v_pk_fma_f16 v123, v33, s0, v123
	v_pk_fma_f16 v121, v34, s0, v121
	v_pk_fma_f16 v120, v35, s0, v120
	v_pk_fma_f16 v119, v36, s0, v119
	v_pk_fma_f16 v118, v37, s0, v118
	v_pk_fma_f16 v117, v38, s0, v117
	v_pk_fma_f16 v116, v39, s0, v116
	v_pk_fma_f16 v113, v40, s0, v113
	v_pk_fma_f16 v112, v41, s0, v112
	v_pk_fma_f16 v67, v42, s0, v67
	v_pk_fma_f16 v66, v43, s0, v66
	v_pk_fma_f16 v65, v44, s0, v65
	v_pk_fma_f16 v64, v45, s0, v64
	v_pk_fma_f16 v125, v46, s0, v125
	v_pk_fma_f16 v122, v47, s0, v122
	s_waitcnt vmcnt(6)
	v_readlane_b32 s4, v49, 8
	v_readlane_b32 s0, v54, 6
	v_cvt_scalef32_pk_f16_fp4 v32, v8, 1.0
	v_cvt_scalef32_pk_f16_fp4 v33, v8, 1.0 op_sel:[1,0,0]
	v_cvt_scalef32_pk_f16_fp4 v34, v8, 1.0 op_sel:[0,1,0]
	v_cvt_scalef32_pk_f16_fp4 v35, v8, 1.0 op_sel:[1,1,0]
	v_cvt_scalef32_pk_f16_fp4 v36, v9, 1.0
	v_cvt_scalef32_pk_f16_fp4 v37, v9, 1.0 op_sel:[1,0,0]
	v_cvt_scalef32_pk_f16_fp4 v38, v9, 1.0 op_sel:[0,1,0]
	v_cvt_scalef32_pk_f16_fp4 v39, v9, 1.0 op_sel:[1,1,0]
	v_cvt_scalef32_pk_f16_fp4 v40, v10, 1.0
	v_cvt_scalef32_pk_f16_fp4 v41, v10, 1.0 op_sel:[1,0,0]
	v_cvt_scalef32_pk_f16_fp4 v42, v10, 1.0 op_sel:[0,1,0]
	v_cvt_scalef32_pk_f16_fp4 v43, v10, 1.0 op_sel:[1,1,0]
	v_cvt_scalef32_pk_f16_fp4 v44, v11, 1.0
	v_cvt_scalef32_pk_f16_fp4 v45, v11, 1.0 op_sel:[1,0,0]
	v_cvt_scalef32_pk_f16_fp4 v46, v11, 1.0 op_sel:[0,1,0]
	v_cvt_scalef32_pk_f16_fp4 v47, v11, 1.0 op_sel:[1,1,0]
	buffer_load_dwordx4 v[4:7], v115, s[12:15], s4 offen
	v_pk_fma_f16 v74, v32, s0, v74
	v_pk_fma_f16 v73, v33, s0, v73
	v_pk_fma_f16 v71, v34, s0, v71
	v_pk_fma_f16 v70, v35, s0, v70
	v_pk_fma_f16 v69, v36, s0, v69
	v_pk_fma_f16 v68, v37, s0, v68
	v_pk_fma_f16 v63, v38, s0, v63
	v_pk_fma_f16 v62, v39, s0, v62
	v_pk_fma_f16 v61, v40, s0, v61
	v_pk_fma_f16 v60, v41, s0, v60
	v_pk_fma_f16 v59, v42, s0, v59
	v_pk_fma_f16 v58, v43, s0, v58
	v_pk_fma_f16 v57, v44, s0, v57
	v_pk_fma_f16 v56, v45, s0, v56
	v_pk_fma_f16 v75, v46, s0, v75
	v_pk_fma_f16 v72, v47, s0, v72
	s_waitcnt vmcnt(6)
	v_readlane_b32 s4, v50, 8
	v_readlane_b32 s0, v55, 6
	v_cvt_scalef32_pk_f16_fp4 v32, v12, 1.0
	v_cvt_scalef32_pk_f16_fp4 v33, v12, 1.0 op_sel:[1,0,0]
	v_cvt_scalef32_pk_f16_fp4 v34, v12, 1.0 op_sel:[0,1,0]
	v_cvt_scalef32_pk_f16_fp4 v35, v12, 1.0 op_sel:[1,1,0]
	v_cvt_scalef32_pk_f16_fp4 v36, v13, 1.0
	v_cvt_scalef32_pk_f16_fp4 v37, v13, 1.0 op_sel:[1,0,0]
	v_cvt_scalef32_pk_f16_fp4 v38, v13, 1.0 op_sel:[0,1,0]
	v_cvt_scalef32_pk_f16_fp4 v39, v13, 1.0 op_sel:[1,1,0]
	v_cvt_scalef32_pk_f16_fp4 v40, v14, 1.0
	v_cvt_scalef32_pk_f16_fp4 v41, v14, 1.0 op_sel:[1,0,0]
	v_cvt_scalef32_pk_f16_fp4 v42, v14, 1.0 op_sel:[0,1,0]
	v_cvt_scalef32_pk_f16_fp4 v43, v14, 1.0 op_sel:[1,1,0]
	v_cvt_scalef32_pk_f16_fp4 v44, v15, 1.0
	v_cvt_scalef32_pk_f16_fp4 v45, v15, 1.0 op_sel:[1,0,0]
	v_cvt_scalef32_pk_f16_fp4 v46, v15, 1.0 op_sel:[0,1,0]
	v_cvt_scalef32_pk_f16_fp4 v47, v15, 1.0 op_sel:[1,1,0]
	buffer_load_dwordx4 v[8:11], v115, s[12:15], s4 offen
	v_pk_fma_f16 v162, v32, s0, v162
	v_pk_fma_f16 v161, v33, s0, v161
	v_pk_fma_f16 v160, v34, s0, v160
	v_pk_fma_f16 v159, v35, s0, v159
	v_pk_fma_f16 v158, v36, s0, v158
	v_pk_fma_f16 v157, v37, s0, v157
	v_pk_fma_f16 v156, v38, s0, v156
	v_pk_fma_f16 v147, v39, s0, v147
	v_pk_fma_f16 v146, v40, s0, v146
	v_pk_fma_f16 v145, v41, s0, v145
	v_pk_fma_f16 v144, v42, s0, v144
	v_pk_fma_f16 v143, v43, s0, v143
	v_pk_fma_f16 v142, v44, s0, v142
	v_pk_fma_f16 v141, v45, s0, v141
	v_pk_fma_f16 v149, v46, s0, v149
	v_pk_fma_f16 v148, v47, s0, v148
	s_waitcnt vmcnt(6)
	v_readlane_b32 s4, v51, 8
	v_readlane_b32 s0, v52, 7
	v_cvt_scalef32_pk_f16_fp4 v32, v16, 1.0
	v_cvt_scalef32_pk_f16_fp4 v33, v16, 1.0 op_sel:[1,0,0]
	v_cvt_scalef32_pk_f16_fp4 v34, v16, 1.0 op_sel:[0,1,0]
	v_cvt_scalef32_pk_f16_fp4 v35, v16, 1.0 op_sel:[1,1,0]
	v_cvt_scalef32_pk_f16_fp4 v36, v17, 1.0
	v_cvt_scalef32_pk_f16_fp4 v37, v17, 1.0 op_sel:[1,0,0]
	v_cvt_scalef32_pk_f16_fp4 v38, v17, 1.0 op_sel:[0,1,0]
	v_cvt_scalef32_pk_f16_fp4 v39, v17, 1.0 op_sel:[1,1,0]
	v_cvt_scalef32_pk_f16_fp4 v40, v18, 1.0
	v_cvt_scalef32_pk_f16_fp4 v41, v18, 1.0 op_sel:[1,0,0]
	v_cvt_scalef32_pk_f16_fp4 v42, v18, 1.0 op_sel:[0,1,0]
	v_cvt_scalef32_pk_f16_fp4 v43, v18, 1.0 op_sel:[1,1,0]
	v_cvt_scalef32_pk_f16_fp4 v44, v19, 1.0
	v_cvt_scalef32_pk_f16_fp4 v45, v19, 1.0 op_sel:[1,0,0]
	v_cvt_scalef32_pk_f16_fp4 v46, v19, 1.0 op_sel:[0,1,0]
	v_cvt_scalef32_pk_f16_fp4 v47, v19, 1.0 op_sel:[1,1,0]
	buffer_load_dwordx4 v[12:15], v115, s[12:15], s4 offen
	v_pk_fma_f16 v139, v32, s0, v139
	v_pk_fma_f16 v138, v33, s0, v138
	v_pk_fma_f16 v136, v34, s0, v136
	v_pk_fma_f16 v135, v35, s0, v135
	v_pk_fma_f16 v134, v36, s0, v134
	v_pk_fma_f16 v133, v37, s0, v133
	v_pk_fma_f16 v132, v38, s0, v132
	v_pk_fma_f16 v131, v39, s0, v131
	v_pk_fma_f16 v130, v40, s0, v130
	v_pk_fma_f16 v129, v41, s0, v129
	v_pk_fma_f16 v128, v42, s0, v128
	v_pk_fma_f16 v127, v43, s0, v127
	v_pk_fma_f16 v126, v44, s0, v126
	v_pk_fma_f16 v114, v45, s0, v114
	v_pk_fma_f16 v140, v46, s0, v140
	v_pk_fma_f16 v137, v47, s0, v137
	s_waitcnt vmcnt(6)
	v_readlane_b32 s4, v48, 9
	v_readlane_b32 s0, v53, 7
	v_cvt_scalef32_pk_f16_fp4 v32, v20, 1.0
	v_cvt_scalef32_pk_f16_fp4 v33, v20, 1.0 op_sel:[1,0,0]
	v_cvt_scalef32_pk_f16_fp4 v34, v20, 1.0 op_sel:[0,1,0]
	v_cvt_scalef32_pk_f16_fp4 v35, v20, 1.0 op_sel:[1,1,0]
	v_cvt_scalef32_pk_f16_fp4 v36, v21, 1.0
	v_cvt_scalef32_pk_f16_fp4 v37, v21, 1.0 op_sel:[1,0,0]
	v_cvt_scalef32_pk_f16_fp4 v38, v21, 1.0 op_sel:[0,1,0]
	v_cvt_scalef32_pk_f16_fp4 v39, v21, 1.0 op_sel:[1,1,0]
	v_cvt_scalef32_pk_f16_fp4 v40, v22, 1.0
	v_cvt_scalef32_pk_f16_fp4 v41, v22, 1.0 op_sel:[1,0,0]
	v_cvt_scalef32_pk_f16_fp4 v42, v22, 1.0 op_sel:[0,1,0]
	v_cvt_scalef32_pk_f16_fp4 v43, v22, 1.0 op_sel:[1,1,0]
	v_cvt_scalef32_pk_f16_fp4 v44, v23, 1.0
	v_cvt_scalef32_pk_f16_fp4 v45, v23, 1.0 op_sel:[1,0,0]
	v_cvt_scalef32_pk_f16_fp4 v46, v23, 1.0 op_sel:[0,1,0]
	v_cvt_scalef32_pk_f16_fp4 v47, v23, 1.0 op_sel:[1,1,0]
	buffer_load_dwordx4 v[16:19], v115, s[12:15], s4 offen
	v_pk_fma_f16 v124, v32, s0, v124
	v_pk_fma_f16 v123, v33, s0, v123
	v_pk_fma_f16 v121, v34, s0, v121
	v_pk_fma_f16 v120, v35, s0, v120
	v_pk_fma_f16 v119, v36, s0, v119
	v_pk_fma_f16 v118, v37, s0, v118
	v_pk_fma_f16 v117, v38, s0, v117
	v_pk_fma_f16 v116, v39, s0, v116
	v_pk_fma_f16 v113, v40, s0, v113
	v_pk_fma_f16 v112, v41, s0, v112
	v_pk_fma_f16 v67, v42, s0, v67
	v_pk_fma_f16 v66, v43, s0, v66
	v_pk_fma_f16 v65, v44, s0, v65
	v_pk_fma_f16 v64, v45, s0, v64
	v_pk_fma_f16 v125, v46, s0, v125
	v_pk_fma_f16 v122, v47, s0, v122
	s_waitcnt vmcnt(6)
	v_readlane_b32 s4, v49, 9
	v_readlane_b32 s0, v54, 7
	v_cvt_scalef32_pk_f16_fp4 v32, v24, 1.0
	v_cvt_scalef32_pk_f16_fp4 v33, v24, 1.0 op_sel:[1,0,0]
	v_cvt_scalef32_pk_f16_fp4 v34, v24, 1.0 op_sel:[0,1,0]
	v_cvt_scalef32_pk_f16_fp4 v35, v24, 1.0 op_sel:[1,1,0]
	v_cvt_scalef32_pk_f16_fp4 v36, v25, 1.0
	v_cvt_scalef32_pk_f16_fp4 v37, v25, 1.0 op_sel:[1,0,0]
	v_cvt_scalef32_pk_f16_fp4 v38, v25, 1.0 op_sel:[0,1,0]
	v_cvt_scalef32_pk_f16_fp4 v39, v25, 1.0 op_sel:[1,1,0]
	v_cvt_scalef32_pk_f16_fp4 v40, v26, 1.0
	v_cvt_scalef32_pk_f16_fp4 v41, v26, 1.0 op_sel:[1,0,0]
	v_cvt_scalef32_pk_f16_fp4 v42, v26, 1.0 op_sel:[0,1,0]
	v_cvt_scalef32_pk_f16_fp4 v43, v26, 1.0 op_sel:[1,1,0]
	v_cvt_scalef32_pk_f16_fp4 v44, v27, 1.0
	v_cvt_scalef32_pk_f16_fp4 v45, v27, 1.0 op_sel:[1,0,0]
	v_cvt_scalef32_pk_f16_fp4 v46, v27, 1.0 op_sel:[0,1,0]
	v_cvt_scalef32_pk_f16_fp4 v47, v27, 1.0 op_sel:[1,1,0]
	buffer_load_dwordx4 v[20:23], v115, s[12:15], s4 offen
	v_pk_fma_f16 v74, v32, s0, v74
	v_pk_fma_f16 v73, v33, s0, v73
	v_pk_fma_f16 v71, v34, s0, v71
	v_pk_fma_f16 v70, v35, s0, v70
	v_pk_fma_f16 v69, v36, s0, v69
	v_pk_fma_f16 v68, v37, s0, v68
	v_pk_fma_f16 v63, v38, s0, v63
	v_pk_fma_f16 v62, v39, s0, v62
	v_pk_fma_f16 v61, v40, s0, v61
	v_pk_fma_f16 v60, v41, s0, v60
	v_pk_fma_f16 v59, v42, s0, v59
	v_pk_fma_f16 v58, v43, s0, v58
	v_pk_fma_f16 v57, v44, s0, v57
	v_pk_fma_f16 v56, v45, s0, v56
	v_pk_fma_f16 v75, v46, s0, v75
	v_pk_fma_f16 v72, v47, s0, v72
	s_waitcnt vmcnt(6)
	v_readlane_b32 s4, v50, 9
	v_readlane_b32 s0, v55, 7
	v_cvt_scalef32_pk_f16_fp4 v32, v28, 1.0
	v_cvt_scalef32_pk_f16_fp4 v33, v28, 1.0 op_sel:[1,0,0]
	v_cvt_scalef32_pk_f16_fp4 v34, v28, 1.0 op_sel:[0,1,0]
	v_cvt_scalef32_pk_f16_fp4 v35, v28, 1.0 op_sel:[1,1,0]
	v_cvt_scalef32_pk_f16_fp4 v36, v29, 1.0
	v_cvt_scalef32_pk_f16_fp4 v37, v29, 1.0 op_sel:[1,0,0]
	v_cvt_scalef32_pk_f16_fp4 v38, v29, 1.0 op_sel:[0,1,0]
	v_cvt_scalef32_pk_f16_fp4 v39, v29, 1.0 op_sel:[1,1,0]
	v_cvt_scalef32_pk_f16_fp4 v40, v30, 1.0
	v_cvt_scalef32_pk_f16_fp4 v41, v30, 1.0 op_sel:[1,0,0]
	v_cvt_scalef32_pk_f16_fp4 v42, v30, 1.0 op_sel:[0,1,0]
	v_cvt_scalef32_pk_f16_fp4 v43, v30, 1.0 op_sel:[1,1,0]
	v_cvt_scalef32_pk_f16_fp4 v44, v31, 1.0
	v_cvt_scalef32_pk_f16_fp4 v45, v31, 1.0 op_sel:[1,0,0]
	v_cvt_scalef32_pk_f16_fp4 v46, v31, 1.0 op_sel:[0,1,0]
	v_cvt_scalef32_pk_f16_fp4 v47, v31, 1.0 op_sel:[1,1,0]
	buffer_load_dwordx4 v[24:27], v115, s[12:15], s4 offen
	v_pk_fma_f16 v162, v32, s0, v162
	v_pk_fma_f16 v161, v33, s0, v161
	v_pk_fma_f16 v160, v34, s0, v160
	v_pk_fma_f16 v159, v35, s0, v159
	v_pk_fma_f16 v158, v36, s0, v158
	v_pk_fma_f16 v157, v37, s0, v157
	v_pk_fma_f16 v156, v38, s0, v156
	v_pk_fma_f16 v147, v39, s0, v147
	v_pk_fma_f16 v146, v40, s0, v146
	v_pk_fma_f16 v145, v41, s0, v145
	v_pk_fma_f16 v144, v42, s0, v144
	v_pk_fma_f16 v143, v43, s0, v143
	v_pk_fma_f16 v142, v44, s0, v142
	v_pk_fma_f16 v141, v45, s0, v141
	v_pk_fma_f16 v149, v46, s0, v149
	v_pk_fma_f16 v148, v47, s0, v148
	s_waitcnt vmcnt(6)
	v_readlane_b32 s4, v51, 9
	v_readlane_b32 s0, v52, 8
	v_cvt_scalef32_pk_f16_fp4 v32, v0, 1.0
	v_cvt_scalef32_pk_f16_fp4 v33, v0, 1.0 op_sel:[1,0,0]
	v_cvt_scalef32_pk_f16_fp4 v34, v0, 1.0 op_sel:[0,1,0]
	v_cvt_scalef32_pk_f16_fp4 v35, v0, 1.0 op_sel:[1,1,0]
	v_cvt_scalef32_pk_f16_fp4 v36, v1, 1.0
	v_cvt_scalef32_pk_f16_fp4 v37, v1, 1.0 op_sel:[1,0,0]
	v_cvt_scalef32_pk_f16_fp4 v38, v1, 1.0 op_sel:[0,1,0]
	v_cvt_scalef32_pk_f16_fp4 v39, v1, 1.0 op_sel:[1,1,0]
	v_cvt_scalef32_pk_f16_fp4 v40, v2, 1.0
	v_cvt_scalef32_pk_f16_fp4 v41, v2, 1.0 op_sel:[1,0,0]
	v_cvt_scalef32_pk_f16_fp4 v42, v2, 1.0 op_sel:[0,1,0]
	v_cvt_scalef32_pk_f16_fp4 v43, v2, 1.0 op_sel:[1,1,0]
	v_cvt_scalef32_pk_f16_fp4 v44, v3, 1.0
	v_cvt_scalef32_pk_f16_fp4 v45, v3, 1.0 op_sel:[1,0,0]
	v_cvt_scalef32_pk_f16_fp4 v46, v3, 1.0 op_sel:[0,1,0]
	v_cvt_scalef32_pk_f16_fp4 v47, v3, 1.0 op_sel:[1,1,0]
	buffer_load_dwordx4 v[28:31], v115, s[12:15], s4 offen
	v_pk_fma_f16 v139, v32, s0, v139
	v_pk_fma_f16 v138, v33, s0, v138
	v_pk_fma_f16 v136, v34, s0, v136
	v_pk_fma_f16 v135, v35, s0, v135
	v_pk_fma_f16 v134, v36, s0, v134
	v_pk_fma_f16 v133, v37, s0, v133
	v_pk_fma_f16 v132, v38, s0, v132
	v_pk_fma_f16 v131, v39, s0, v131
	v_pk_fma_f16 v130, v40, s0, v130
	v_pk_fma_f16 v129, v41, s0, v129
	v_pk_fma_f16 v128, v42, s0, v128
	v_pk_fma_f16 v127, v43, s0, v127
	v_pk_fma_f16 v126, v44, s0, v126
	v_pk_fma_f16 v114, v45, s0, v114
	v_pk_fma_f16 v140, v46, s0, v140
	v_pk_fma_f16 v137, v47, s0, v137
	s_waitcnt vmcnt(6)
	v_readlane_b32 s4, v48, 10
	v_readlane_b32 s0, v53, 8
	v_cvt_scalef32_pk_f16_fp4 v32, v4, 1.0
	v_cvt_scalef32_pk_f16_fp4 v33, v4, 1.0 op_sel:[1,0,0]
	v_cvt_scalef32_pk_f16_fp4 v34, v4, 1.0 op_sel:[0,1,0]
	v_cvt_scalef32_pk_f16_fp4 v35, v4, 1.0 op_sel:[1,1,0]
	v_cvt_scalef32_pk_f16_fp4 v36, v5, 1.0
	v_cvt_scalef32_pk_f16_fp4 v37, v5, 1.0 op_sel:[1,0,0]
	v_cvt_scalef32_pk_f16_fp4 v38, v5, 1.0 op_sel:[0,1,0]
	v_cvt_scalef32_pk_f16_fp4 v39, v5, 1.0 op_sel:[1,1,0]
	v_cvt_scalef32_pk_f16_fp4 v40, v6, 1.0
	v_cvt_scalef32_pk_f16_fp4 v41, v6, 1.0 op_sel:[1,0,0]
	v_cvt_scalef32_pk_f16_fp4 v42, v6, 1.0 op_sel:[0,1,0]
	v_cvt_scalef32_pk_f16_fp4 v43, v6, 1.0 op_sel:[1,1,0]
	v_cvt_scalef32_pk_f16_fp4 v44, v7, 1.0
	v_cvt_scalef32_pk_f16_fp4 v45, v7, 1.0 op_sel:[1,0,0]
	v_cvt_scalef32_pk_f16_fp4 v46, v7, 1.0 op_sel:[0,1,0]
	v_cvt_scalef32_pk_f16_fp4 v47, v7, 1.0 op_sel:[1,1,0]
	buffer_load_dwordx4 v[0:3], v115, s[12:15], s4 offen
	v_pk_fma_f16 v124, v32, s0, v124
	v_pk_fma_f16 v123, v33, s0, v123
	v_pk_fma_f16 v121, v34, s0, v121
	v_pk_fma_f16 v120, v35, s0, v120
	v_pk_fma_f16 v119, v36, s0, v119
	v_pk_fma_f16 v118, v37, s0, v118
	v_pk_fma_f16 v117, v38, s0, v117
	v_pk_fma_f16 v116, v39, s0, v116
	v_pk_fma_f16 v113, v40, s0, v113
	v_pk_fma_f16 v112, v41, s0, v112
	v_pk_fma_f16 v67, v42, s0, v67
	v_pk_fma_f16 v66, v43, s0, v66
	v_pk_fma_f16 v65, v44, s0, v65
	v_pk_fma_f16 v64, v45, s0, v64
	v_pk_fma_f16 v125, v46, s0, v125
	v_pk_fma_f16 v122, v47, s0, v122
	s_waitcnt vmcnt(6)
	v_readlane_b32 s4, v49, 10
	v_readlane_b32 s0, v54, 8
	v_cvt_scalef32_pk_f16_fp4 v32, v8, 1.0
	v_cvt_scalef32_pk_f16_fp4 v33, v8, 1.0 op_sel:[1,0,0]
	v_cvt_scalef32_pk_f16_fp4 v34, v8, 1.0 op_sel:[0,1,0]
	v_cvt_scalef32_pk_f16_fp4 v35, v8, 1.0 op_sel:[1,1,0]
	v_cvt_scalef32_pk_f16_fp4 v36, v9, 1.0
	v_cvt_scalef32_pk_f16_fp4 v37, v9, 1.0 op_sel:[1,0,0]
	v_cvt_scalef32_pk_f16_fp4 v38, v9, 1.0 op_sel:[0,1,0]
	v_cvt_scalef32_pk_f16_fp4 v39, v9, 1.0 op_sel:[1,1,0]
	v_cvt_scalef32_pk_f16_fp4 v40, v10, 1.0
	v_cvt_scalef32_pk_f16_fp4 v41, v10, 1.0 op_sel:[1,0,0]
	v_cvt_scalef32_pk_f16_fp4 v42, v10, 1.0 op_sel:[0,1,0]
	v_cvt_scalef32_pk_f16_fp4 v43, v10, 1.0 op_sel:[1,1,0]
	v_cvt_scalef32_pk_f16_fp4 v44, v11, 1.0
	v_cvt_scalef32_pk_f16_fp4 v45, v11, 1.0 op_sel:[1,0,0]
	v_cvt_scalef32_pk_f16_fp4 v46, v11, 1.0 op_sel:[0,1,0]
	v_cvt_scalef32_pk_f16_fp4 v47, v11, 1.0 op_sel:[1,1,0]
	buffer_load_dwordx4 v[4:7], v115, s[12:15], s4 offen
	v_pk_fma_f16 v74, v32, s0, v74
	v_pk_fma_f16 v73, v33, s0, v73
	v_pk_fma_f16 v71, v34, s0, v71
	v_pk_fma_f16 v70, v35, s0, v70
	v_pk_fma_f16 v69, v36, s0, v69
	v_pk_fma_f16 v68, v37, s0, v68
	v_pk_fma_f16 v63, v38, s0, v63
	v_pk_fma_f16 v62, v39, s0, v62
	v_pk_fma_f16 v61, v40, s0, v61
	v_pk_fma_f16 v60, v41, s0, v60
	v_pk_fma_f16 v59, v42, s0, v59
	v_pk_fma_f16 v58, v43, s0, v58
	v_pk_fma_f16 v57, v44, s0, v57
	v_pk_fma_f16 v56, v45, s0, v56
	v_pk_fma_f16 v75, v46, s0, v75
	v_pk_fma_f16 v72, v47, s0, v72
	s_waitcnt vmcnt(6)
	v_readlane_b32 s4, v50, 10
	v_readlane_b32 s0, v55, 8
	v_cvt_scalef32_pk_f16_fp4 v32, v12, 1.0
	v_cvt_scalef32_pk_f16_fp4 v33, v12, 1.0 op_sel:[1,0,0]
	v_cvt_scalef32_pk_f16_fp4 v34, v12, 1.0 op_sel:[0,1,0]
	v_cvt_scalef32_pk_f16_fp4 v35, v12, 1.0 op_sel:[1,1,0]
	v_cvt_scalef32_pk_f16_fp4 v36, v13, 1.0
	v_cvt_scalef32_pk_f16_fp4 v37, v13, 1.0 op_sel:[1,0,0]
	v_cvt_scalef32_pk_f16_fp4 v38, v13, 1.0 op_sel:[0,1,0]
	v_cvt_scalef32_pk_f16_fp4 v39, v13, 1.0 op_sel:[1,1,0]
	v_cvt_scalef32_pk_f16_fp4 v40, v14, 1.0
	v_cvt_scalef32_pk_f16_fp4 v41, v14, 1.0 op_sel:[1,0,0]
	v_cvt_scalef32_pk_f16_fp4 v42, v14, 1.0 op_sel:[0,1,0]
	v_cvt_scalef32_pk_f16_fp4 v43, v14, 1.0 op_sel:[1,1,0]
	v_cvt_scalef32_pk_f16_fp4 v44, v15, 1.0
	v_cvt_scalef32_pk_f16_fp4 v45, v15, 1.0 op_sel:[1,0,0]
	v_cvt_scalef32_pk_f16_fp4 v46, v15, 1.0 op_sel:[0,1,0]
	v_cvt_scalef32_pk_f16_fp4 v47, v15, 1.0 op_sel:[1,1,0]
	buffer_load_dwordx4 v[8:11], v115, s[12:15], s4 offen
	v_pk_fma_f16 v162, v32, s0, v162
	v_pk_fma_f16 v161, v33, s0, v161
	v_pk_fma_f16 v160, v34, s0, v160
	v_pk_fma_f16 v159, v35, s0, v159
	v_pk_fma_f16 v158, v36, s0, v158
	v_pk_fma_f16 v157, v37, s0, v157
	v_pk_fma_f16 v156, v38, s0, v156
	v_pk_fma_f16 v147, v39, s0, v147
	v_pk_fma_f16 v146, v40, s0, v146
	v_pk_fma_f16 v145, v41, s0, v145
	v_pk_fma_f16 v144, v42, s0, v144
	v_pk_fma_f16 v143, v43, s0, v143
	v_pk_fma_f16 v142, v44, s0, v142
	v_pk_fma_f16 v141, v45, s0, v141
	v_pk_fma_f16 v149, v46, s0, v149
	v_pk_fma_f16 v148, v47, s0, v148
	s_waitcnt vmcnt(6)
	v_readlane_b32 s4, v51, 10
	v_readlane_b32 s0, v52, 9
	v_cvt_scalef32_pk_f16_fp4 v32, v16, 1.0
	v_cvt_scalef32_pk_f16_fp4 v33, v16, 1.0 op_sel:[1,0,0]
	v_cvt_scalef32_pk_f16_fp4 v34, v16, 1.0 op_sel:[0,1,0]
	v_cvt_scalef32_pk_f16_fp4 v35, v16, 1.0 op_sel:[1,1,0]
	v_cvt_scalef32_pk_f16_fp4 v36, v17, 1.0
	v_cvt_scalef32_pk_f16_fp4 v37, v17, 1.0 op_sel:[1,0,0]
	v_cvt_scalef32_pk_f16_fp4 v38, v17, 1.0 op_sel:[0,1,0]
	v_cvt_scalef32_pk_f16_fp4 v39, v17, 1.0 op_sel:[1,1,0]
	v_cvt_scalef32_pk_f16_fp4 v40, v18, 1.0
	v_cvt_scalef32_pk_f16_fp4 v41, v18, 1.0 op_sel:[1,0,0]
	v_cvt_scalef32_pk_f16_fp4 v42, v18, 1.0 op_sel:[0,1,0]
	v_cvt_scalef32_pk_f16_fp4 v43, v18, 1.0 op_sel:[1,1,0]
	v_cvt_scalef32_pk_f16_fp4 v44, v19, 1.0
	v_cvt_scalef32_pk_f16_fp4 v45, v19, 1.0 op_sel:[1,0,0]
	v_cvt_scalef32_pk_f16_fp4 v46, v19, 1.0 op_sel:[0,1,0]
	v_cvt_scalef32_pk_f16_fp4 v47, v19, 1.0 op_sel:[1,1,0]
	buffer_load_dwordx4 v[12:15], v115, s[12:15], s4 offen
	v_pk_fma_f16 v139, v32, s0, v139
	v_pk_fma_f16 v138, v33, s0, v138
	v_pk_fma_f16 v136, v34, s0, v136
	v_pk_fma_f16 v135, v35, s0, v135
	v_pk_fma_f16 v134, v36, s0, v134
	v_pk_fma_f16 v133, v37, s0, v133
	v_pk_fma_f16 v132, v38, s0, v132
	v_pk_fma_f16 v131, v39, s0, v131
	v_pk_fma_f16 v130, v40, s0, v130
	v_pk_fma_f16 v129, v41, s0, v129
	v_pk_fma_f16 v128, v42, s0, v128
	v_pk_fma_f16 v127, v43, s0, v127
	v_pk_fma_f16 v126, v44, s0, v126
	v_pk_fma_f16 v114, v45, s0, v114
	v_pk_fma_f16 v140, v46, s0, v140
	v_pk_fma_f16 v137, v47, s0, v137
	s_waitcnt vmcnt(6)
	v_readlane_b32 s4, v48, 11
	v_readlane_b32 s0, v53, 9
	v_cvt_scalef32_pk_f16_fp4 v32, v20, 1.0
	v_cvt_scalef32_pk_f16_fp4 v33, v20, 1.0 op_sel:[1,0,0]
	v_cvt_scalef32_pk_f16_fp4 v34, v20, 1.0 op_sel:[0,1,0]
	v_cvt_scalef32_pk_f16_fp4 v35, v20, 1.0 op_sel:[1,1,0]
	v_cvt_scalef32_pk_f16_fp4 v36, v21, 1.0
	v_cvt_scalef32_pk_f16_fp4 v37, v21, 1.0 op_sel:[1,0,0]
	v_cvt_scalef32_pk_f16_fp4 v38, v21, 1.0 op_sel:[0,1,0]
	v_cvt_scalef32_pk_f16_fp4 v39, v21, 1.0 op_sel:[1,1,0]
	v_cvt_scalef32_pk_f16_fp4 v40, v22, 1.0
	v_cvt_scalef32_pk_f16_fp4 v41, v22, 1.0 op_sel:[1,0,0]
	v_cvt_scalef32_pk_f16_fp4 v42, v22, 1.0 op_sel:[0,1,0]
	v_cvt_scalef32_pk_f16_fp4 v43, v22, 1.0 op_sel:[1,1,0]
	v_cvt_scalef32_pk_f16_fp4 v44, v23, 1.0
	v_cvt_scalef32_pk_f16_fp4 v45, v23, 1.0 op_sel:[1,0,0]
	v_cvt_scalef32_pk_f16_fp4 v46, v23, 1.0 op_sel:[0,1,0]
	v_cvt_scalef32_pk_f16_fp4 v47, v23, 1.0 op_sel:[1,1,0]
	buffer_load_dwordx4 v[16:19], v115, s[12:15], s4 offen
	v_pk_fma_f16 v124, v32, s0, v124
	v_pk_fma_f16 v123, v33, s0, v123
	v_pk_fma_f16 v121, v34, s0, v121
	v_pk_fma_f16 v120, v35, s0, v120
	v_pk_fma_f16 v119, v36, s0, v119
	v_pk_fma_f16 v118, v37, s0, v118
	v_pk_fma_f16 v117, v38, s0, v117
	v_pk_fma_f16 v116, v39, s0, v116
	v_pk_fma_f16 v113, v40, s0, v113
	v_pk_fma_f16 v112, v41, s0, v112
	v_pk_fma_f16 v67, v42, s0, v67
	v_pk_fma_f16 v66, v43, s0, v66
	v_pk_fma_f16 v65, v44, s0, v65
	v_pk_fma_f16 v64, v45, s0, v64
	v_pk_fma_f16 v125, v46, s0, v125
	v_pk_fma_f16 v122, v47, s0, v122
	s_waitcnt vmcnt(6)
	v_readlane_b32 s4, v49, 11
	v_readlane_b32 s0, v54, 9
	v_cvt_scalef32_pk_f16_fp4 v32, v24, 1.0
	v_cvt_scalef32_pk_f16_fp4 v33, v24, 1.0 op_sel:[1,0,0]
	v_cvt_scalef32_pk_f16_fp4 v34, v24, 1.0 op_sel:[0,1,0]
	v_cvt_scalef32_pk_f16_fp4 v35, v24, 1.0 op_sel:[1,1,0]
	v_cvt_scalef32_pk_f16_fp4 v36, v25, 1.0
	v_cvt_scalef32_pk_f16_fp4 v37, v25, 1.0 op_sel:[1,0,0]
	v_cvt_scalef32_pk_f16_fp4 v38, v25, 1.0 op_sel:[0,1,0]
	v_cvt_scalef32_pk_f16_fp4 v39, v25, 1.0 op_sel:[1,1,0]
	v_cvt_scalef32_pk_f16_fp4 v40, v26, 1.0
	v_cvt_scalef32_pk_f16_fp4 v41, v26, 1.0 op_sel:[1,0,0]
	v_cvt_scalef32_pk_f16_fp4 v42, v26, 1.0 op_sel:[0,1,0]
	v_cvt_scalef32_pk_f16_fp4 v43, v26, 1.0 op_sel:[1,1,0]
	v_cvt_scalef32_pk_f16_fp4 v44, v27, 1.0
	v_cvt_scalef32_pk_f16_fp4 v45, v27, 1.0 op_sel:[1,0,0]
	v_cvt_scalef32_pk_f16_fp4 v46, v27, 1.0 op_sel:[0,1,0]
	v_cvt_scalef32_pk_f16_fp4 v47, v27, 1.0 op_sel:[1,1,0]
	buffer_load_dwordx4 v[20:23], v115, s[12:15], s4 offen
	v_pk_fma_f16 v74, v32, s0, v74
	v_pk_fma_f16 v73, v33, s0, v73
	v_pk_fma_f16 v71, v34, s0, v71
	v_pk_fma_f16 v70, v35, s0, v70
	v_pk_fma_f16 v69, v36, s0, v69
	v_pk_fma_f16 v68, v37, s0, v68
	v_pk_fma_f16 v63, v38, s0, v63
	v_pk_fma_f16 v62, v39, s0, v62
	v_pk_fma_f16 v61, v40, s0, v61
	v_pk_fma_f16 v60, v41, s0, v60
	v_pk_fma_f16 v59, v42, s0, v59
	v_pk_fma_f16 v58, v43, s0, v58
	v_pk_fma_f16 v57, v44, s0, v57
	v_pk_fma_f16 v56, v45, s0, v56
	v_pk_fma_f16 v75, v46, s0, v75
	v_pk_fma_f16 v72, v47, s0, v72
	s_waitcnt vmcnt(6)
	v_readlane_b32 s4, v50, 11
	v_readlane_b32 s0, v55, 9
	v_cvt_scalef32_pk_f16_fp4 v32, v28, 1.0
	v_cvt_scalef32_pk_f16_fp4 v33, v28, 1.0 op_sel:[1,0,0]
	v_cvt_scalef32_pk_f16_fp4 v34, v28, 1.0 op_sel:[0,1,0]
	v_cvt_scalef32_pk_f16_fp4 v35, v28, 1.0 op_sel:[1,1,0]
	v_cvt_scalef32_pk_f16_fp4 v36, v29, 1.0
	v_cvt_scalef32_pk_f16_fp4 v37, v29, 1.0 op_sel:[1,0,0]
	v_cvt_scalef32_pk_f16_fp4 v38, v29, 1.0 op_sel:[0,1,0]
	v_cvt_scalef32_pk_f16_fp4 v39, v29, 1.0 op_sel:[1,1,0]
	v_cvt_scalef32_pk_f16_fp4 v40, v30, 1.0
	v_cvt_scalef32_pk_f16_fp4 v41, v30, 1.0 op_sel:[1,0,0]
	v_cvt_scalef32_pk_f16_fp4 v42, v30, 1.0 op_sel:[0,1,0]
	v_cvt_scalef32_pk_f16_fp4 v43, v30, 1.0 op_sel:[1,1,0]
	v_cvt_scalef32_pk_f16_fp4 v44, v31, 1.0
	v_cvt_scalef32_pk_f16_fp4 v45, v31, 1.0 op_sel:[1,0,0]
	v_cvt_scalef32_pk_f16_fp4 v46, v31, 1.0 op_sel:[0,1,0]
	v_cvt_scalef32_pk_f16_fp4 v47, v31, 1.0 op_sel:[1,1,0]
	buffer_load_dwordx4 v[24:27], v115, s[12:15], s4 offen
	v_pk_fma_f16 v162, v32, s0, v162
	v_pk_fma_f16 v161, v33, s0, v161
	v_pk_fma_f16 v160, v34, s0, v160
	v_pk_fma_f16 v159, v35, s0, v159
	v_pk_fma_f16 v158, v36, s0, v158
	v_pk_fma_f16 v157, v37, s0, v157
	v_pk_fma_f16 v156, v38, s0, v156
	v_pk_fma_f16 v147, v39, s0, v147
	v_pk_fma_f16 v146, v40, s0, v146
	v_pk_fma_f16 v145, v41, s0, v145
	v_pk_fma_f16 v144, v42, s0, v144
	v_pk_fma_f16 v143, v43, s0, v143
	v_pk_fma_f16 v142, v44, s0, v142
	v_pk_fma_f16 v141, v45, s0, v141
	v_pk_fma_f16 v149, v46, s0, v149
	v_pk_fma_f16 v148, v47, s0, v148
	s_waitcnt vmcnt(6)
	v_readlane_b32 s4, v51, 11
	v_readlane_b32 s0, v52, 10
	v_cvt_scalef32_pk_f16_fp4 v32, v0, 1.0
	v_cvt_scalef32_pk_f16_fp4 v33, v0, 1.0 op_sel:[1,0,0]
	v_cvt_scalef32_pk_f16_fp4 v34, v0, 1.0 op_sel:[0,1,0]
	v_cvt_scalef32_pk_f16_fp4 v35, v0, 1.0 op_sel:[1,1,0]
	v_cvt_scalef32_pk_f16_fp4 v36, v1, 1.0
	v_cvt_scalef32_pk_f16_fp4 v37, v1, 1.0 op_sel:[1,0,0]
	v_cvt_scalef32_pk_f16_fp4 v38, v1, 1.0 op_sel:[0,1,0]
	v_cvt_scalef32_pk_f16_fp4 v39, v1, 1.0 op_sel:[1,1,0]
	v_cvt_scalef32_pk_f16_fp4 v40, v2, 1.0
	v_cvt_scalef32_pk_f16_fp4 v41, v2, 1.0 op_sel:[1,0,0]
	v_cvt_scalef32_pk_f16_fp4 v42, v2, 1.0 op_sel:[0,1,0]
	v_cvt_scalef32_pk_f16_fp4 v43, v2, 1.0 op_sel:[1,1,0]
	v_cvt_scalef32_pk_f16_fp4 v44, v3, 1.0
	v_cvt_scalef32_pk_f16_fp4 v45, v3, 1.0 op_sel:[1,0,0]
	v_cvt_scalef32_pk_f16_fp4 v46, v3, 1.0 op_sel:[0,1,0]
	v_cvt_scalef32_pk_f16_fp4 v47, v3, 1.0 op_sel:[1,1,0]
	buffer_load_dwordx4 v[28:31], v115, s[12:15], s4 offen
	v_pk_fma_f16 v139, v32, s0, v139
	v_pk_fma_f16 v138, v33, s0, v138
	v_pk_fma_f16 v136, v34, s0, v136
	v_pk_fma_f16 v135, v35, s0, v135
	v_pk_fma_f16 v134, v36, s0, v134
	v_pk_fma_f16 v133, v37, s0, v133
	v_pk_fma_f16 v132, v38, s0, v132
	v_pk_fma_f16 v131, v39, s0, v131
	v_pk_fma_f16 v130, v40, s0, v130
	v_pk_fma_f16 v129, v41, s0, v129
	v_pk_fma_f16 v128, v42, s0, v128
	v_pk_fma_f16 v127, v43, s0, v127
	v_pk_fma_f16 v126, v44, s0, v126
	v_pk_fma_f16 v114, v45, s0, v114
	v_pk_fma_f16 v140, v46, s0, v140
	v_pk_fma_f16 v137, v47, s0, v137
	s_waitcnt vmcnt(6)
	v_readlane_b32 s4, v48, 12
	v_readlane_b32 s0, v53, 10
	v_cvt_scalef32_pk_f16_fp4 v32, v4, 1.0
	v_cvt_scalef32_pk_f16_fp4 v33, v4, 1.0 op_sel:[1,0,0]
	v_cvt_scalef32_pk_f16_fp4 v34, v4, 1.0 op_sel:[0,1,0]
	v_cvt_scalef32_pk_f16_fp4 v35, v4, 1.0 op_sel:[1,1,0]
	v_cvt_scalef32_pk_f16_fp4 v36, v5, 1.0
	v_cvt_scalef32_pk_f16_fp4 v37, v5, 1.0 op_sel:[1,0,0]
	v_cvt_scalef32_pk_f16_fp4 v38, v5, 1.0 op_sel:[0,1,0]
	v_cvt_scalef32_pk_f16_fp4 v39, v5, 1.0 op_sel:[1,1,0]
	v_cvt_scalef32_pk_f16_fp4 v40, v6, 1.0
	v_cvt_scalef32_pk_f16_fp4 v41, v6, 1.0 op_sel:[1,0,0]
	v_cvt_scalef32_pk_f16_fp4 v42, v6, 1.0 op_sel:[0,1,0]
	v_cvt_scalef32_pk_f16_fp4 v43, v6, 1.0 op_sel:[1,1,0]
	v_cvt_scalef32_pk_f16_fp4 v44, v7, 1.0
	v_cvt_scalef32_pk_f16_fp4 v45, v7, 1.0 op_sel:[1,0,0]
	v_cvt_scalef32_pk_f16_fp4 v46, v7, 1.0 op_sel:[0,1,0]
	v_cvt_scalef32_pk_f16_fp4 v47, v7, 1.0 op_sel:[1,1,0]
	buffer_load_dwordx4 v[0:3], v115, s[12:15], s4 offen
	v_pk_fma_f16 v124, v32, s0, v124
	v_pk_fma_f16 v123, v33, s0, v123
	v_pk_fma_f16 v121, v34, s0, v121
	v_pk_fma_f16 v120, v35, s0, v120
	v_pk_fma_f16 v119, v36, s0, v119
	v_pk_fma_f16 v118, v37, s0, v118
	v_pk_fma_f16 v117, v38, s0, v117
	v_pk_fma_f16 v116, v39, s0, v116
	v_pk_fma_f16 v113, v40, s0, v113
	v_pk_fma_f16 v112, v41, s0, v112
	v_pk_fma_f16 v67, v42, s0, v67
	v_pk_fma_f16 v66, v43, s0, v66
	v_pk_fma_f16 v65, v44, s0, v65
	v_pk_fma_f16 v64, v45, s0, v64
	v_pk_fma_f16 v125, v46, s0, v125
	v_pk_fma_f16 v122, v47, s0, v122
	s_waitcnt vmcnt(6)
	v_readlane_b32 s4, v49, 12
	v_readlane_b32 s0, v54, 10
	v_cvt_scalef32_pk_f16_fp4 v32, v8, 1.0
	v_cvt_scalef32_pk_f16_fp4 v33, v8, 1.0 op_sel:[1,0,0]
	v_cvt_scalef32_pk_f16_fp4 v34, v8, 1.0 op_sel:[0,1,0]
	v_cvt_scalef32_pk_f16_fp4 v35, v8, 1.0 op_sel:[1,1,0]
	v_cvt_scalef32_pk_f16_fp4 v36, v9, 1.0
	v_cvt_scalef32_pk_f16_fp4 v37, v9, 1.0 op_sel:[1,0,0]
	v_cvt_scalef32_pk_f16_fp4 v38, v9, 1.0 op_sel:[0,1,0]
	v_cvt_scalef32_pk_f16_fp4 v39, v9, 1.0 op_sel:[1,1,0]
	v_cvt_scalef32_pk_f16_fp4 v40, v10, 1.0
	v_cvt_scalef32_pk_f16_fp4 v41, v10, 1.0 op_sel:[1,0,0]
	v_cvt_scalef32_pk_f16_fp4 v42, v10, 1.0 op_sel:[0,1,0]
	v_cvt_scalef32_pk_f16_fp4 v43, v10, 1.0 op_sel:[1,1,0]
	v_cvt_scalef32_pk_f16_fp4 v44, v11, 1.0
	v_cvt_scalef32_pk_f16_fp4 v45, v11, 1.0 op_sel:[1,0,0]
	v_cvt_scalef32_pk_f16_fp4 v46, v11, 1.0 op_sel:[0,1,0]
	v_cvt_scalef32_pk_f16_fp4 v47, v11, 1.0 op_sel:[1,1,0]
	buffer_load_dwordx4 v[4:7], v115, s[12:15], s4 offen
	v_pk_fma_f16 v74, v32, s0, v74
	v_pk_fma_f16 v73, v33, s0, v73
	v_pk_fma_f16 v71, v34, s0, v71
	v_pk_fma_f16 v70, v35, s0, v70
	v_pk_fma_f16 v69, v36, s0, v69
	v_pk_fma_f16 v68, v37, s0, v68
	v_pk_fma_f16 v63, v38, s0, v63
	v_pk_fma_f16 v62, v39, s0, v62
	v_pk_fma_f16 v61, v40, s0, v61
	v_pk_fma_f16 v60, v41, s0, v60
	v_pk_fma_f16 v59, v42, s0, v59
	v_pk_fma_f16 v58, v43, s0, v58
	v_pk_fma_f16 v57, v44, s0, v57
	v_pk_fma_f16 v56, v45, s0, v56
	v_pk_fma_f16 v75, v46, s0, v75
	v_pk_fma_f16 v72, v47, s0, v72
	s_waitcnt vmcnt(6)
	v_readlane_b32 s4, v50, 12
	v_readlane_b32 s0, v55, 10
	v_cvt_scalef32_pk_f16_fp4 v32, v12, 1.0
	v_cvt_scalef32_pk_f16_fp4 v33, v12, 1.0 op_sel:[1,0,0]
	v_cvt_scalef32_pk_f16_fp4 v34, v12, 1.0 op_sel:[0,1,0]
	v_cvt_scalef32_pk_f16_fp4 v35, v12, 1.0 op_sel:[1,1,0]
	v_cvt_scalef32_pk_f16_fp4 v36, v13, 1.0
	v_cvt_scalef32_pk_f16_fp4 v37, v13, 1.0 op_sel:[1,0,0]
	v_cvt_scalef32_pk_f16_fp4 v38, v13, 1.0 op_sel:[0,1,0]
	v_cvt_scalef32_pk_f16_fp4 v39, v13, 1.0 op_sel:[1,1,0]
	v_cvt_scalef32_pk_f16_fp4 v40, v14, 1.0
	v_cvt_scalef32_pk_f16_fp4 v41, v14, 1.0 op_sel:[1,0,0]
	v_cvt_scalef32_pk_f16_fp4 v42, v14, 1.0 op_sel:[0,1,0]
	v_cvt_scalef32_pk_f16_fp4 v43, v14, 1.0 op_sel:[1,1,0]
	v_cvt_scalef32_pk_f16_fp4 v44, v15, 1.0
	v_cvt_scalef32_pk_f16_fp4 v45, v15, 1.0 op_sel:[1,0,0]
	v_cvt_scalef32_pk_f16_fp4 v46, v15, 1.0 op_sel:[0,1,0]
	v_cvt_scalef32_pk_f16_fp4 v47, v15, 1.0 op_sel:[1,1,0]
	buffer_load_dwordx4 v[8:11], v115, s[12:15], s4 offen
	v_pk_fma_f16 v162, v32, s0, v162
	v_pk_fma_f16 v161, v33, s0, v161
	v_pk_fma_f16 v160, v34, s0, v160
	v_pk_fma_f16 v159, v35, s0, v159
	v_pk_fma_f16 v158, v36, s0, v158
	v_pk_fma_f16 v157, v37, s0, v157
	v_pk_fma_f16 v156, v38, s0, v156
	v_pk_fma_f16 v147, v39, s0, v147
	v_pk_fma_f16 v146, v40, s0, v146
	v_pk_fma_f16 v145, v41, s0, v145
	v_pk_fma_f16 v144, v42, s0, v144
	v_pk_fma_f16 v143, v43, s0, v143
	v_pk_fma_f16 v142, v44, s0, v142
	v_pk_fma_f16 v141, v45, s0, v141
	v_pk_fma_f16 v149, v46, s0, v149
	v_pk_fma_f16 v148, v47, s0, v148
	s_waitcnt vmcnt(6)
	v_readlane_b32 s4, v51, 12
	v_readlane_b32 s0, v52, 11
	v_cvt_scalef32_pk_f16_fp4 v32, v16, 1.0
	v_cvt_scalef32_pk_f16_fp4 v33, v16, 1.0 op_sel:[1,0,0]
	v_cvt_scalef32_pk_f16_fp4 v34, v16, 1.0 op_sel:[0,1,0]
	v_cvt_scalef32_pk_f16_fp4 v35, v16, 1.0 op_sel:[1,1,0]
	v_cvt_scalef32_pk_f16_fp4 v36, v17, 1.0
	v_cvt_scalef32_pk_f16_fp4 v37, v17, 1.0 op_sel:[1,0,0]
	v_cvt_scalef32_pk_f16_fp4 v38, v17, 1.0 op_sel:[0,1,0]
	v_cvt_scalef32_pk_f16_fp4 v39, v17, 1.0 op_sel:[1,1,0]
	v_cvt_scalef32_pk_f16_fp4 v40, v18, 1.0
	v_cvt_scalef32_pk_f16_fp4 v41, v18, 1.0 op_sel:[1,0,0]
	v_cvt_scalef32_pk_f16_fp4 v42, v18, 1.0 op_sel:[0,1,0]
	v_cvt_scalef32_pk_f16_fp4 v43, v18, 1.0 op_sel:[1,1,0]
	v_cvt_scalef32_pk_f16_fp4 v44, v19, 1.0
	v_cvt_scalef32_pk_f16_fp4 v45, v19, 1.0 op_sel:[1,0,0]
	v_cvt_scalef32_pk_f16_fp4 v46, v19, 1.0 op_sel:[0,1,0]
	v_cvt_scalef32_pk_f16_fp4 v47, v19, 1.0 op_sel:[1,1,0]
	buffer_load_dwordx4 v[12:15], v115, s[12:15], s4 offen
	v_pk_fma_f16 v139, v32, s0, v139
	v_pk_fma_f16 v138, v33, s0, v138
	v_pk_fma_f16 v136, v34, s0, v136
	v_pk_fma_f16 v135, v35, s0, v135
	v_pk_fma_f16 v134, v36, s0, v134
	v_pk_fma_f16 v133, v37, s0, v133
	v_pk_fma_f16 v132, v38, s0, v132
	v_pk_fma_f16 v131, v39, s0, v131
	v_pk_fma_f16 v130, v40, s0, v130
	v_pk_fma_f16 v129, v41, s0, v129
	v_pk_fma_f16 v128, v42, s0, v128
	v_pk_fma_f16 v127, v43, s0, v127
	v_pk_fma_f16 v126, v44, s0, v126
	v_pk_fma_f16 v114, v45, s0, v114
	v_pk_fma_f16 v140, v46, s0, v140
	v_pk_fma_f16 v137, v47, s0, v137
	s_waitcnt vmcnt(6)
	v_readlane_b32 s4, v48, 13
	v_readlane_b32 s0, v53, 11
	v_cvt_scalef32_pk_f16_fp4 v32, v20, 1.0
	v_cvt_scalef32_pk_f16_fp4 v33, v20, 1.0 op_sel:[1,0,0]
	v_cvt_scalef32_pk_f16_fp4 v34, v20, 1.0 op_sel:[0,1,0]
	v_cvt_scalef32_pk_f16_fp4 v35, v20, 1.0 op_sel:[1,1,0]
	v_cvt_scalef32_pk_f16_fp4 v36, v21, 1.0
	v_cvt_scalef32_pk_f16_fp4 v37, v21, 1.0 op_sel:[1,0,0]
	v_cvt_scalef32_pk_f16_fp4 v38, v21, 1.0 op_sel:[0,1,0]
	v_cvt_scalef32_pk_f16_fp4 v39, v21, 1.0 op_sel:[1,1,0]
	v_cvt_scalef32_pk_f16_fp4 v40, v22, 1.0
	v_cvt_scalef32_pk_f16_fp4 v41, v22, 1.0 op_sel:[1,0,0]
	v_cvt_scalef32_pk_f16_fp4 v42, v22, 1.0 op_sel:[0,1,0]
	v_cvt_scalef32_pk_f16_fp4 v43, v22, 1.0 op_sel:[1,1,0]
	v_cvt_scalef32_pk_f16_fp4 v44, v23, 1.0
	v_cvt_scalef32_pk_f16_fp4 v45, v23, 1.0 op_sel:[1,0,0]
	v_cvt_scalef32_pk_f16_fp4 v46, v23, 1.0 op_sel:[0,1,0]
	v_cvt_scalef32_pk_f16_fp4 v47, v23, 1.0 op_sel:[1,1,0]
	buffer_load_dwordx4 v[16:19], v115, s[12:15], s4 offen
	v_pk_fma_f16 v124, v32, s0, v124
	v_pk_fma_f16 v123, v33, s0, v123
	v_pk_fma_f16 v121, v34, s0, v121
	v_pk_fma_f16 v120, v35, s0, v120
	v_pk_fma_f16 v119, v36, s0, v119
	v_pk_fma_f16 v118, v37, s0, v118
	v_pk_fma_f16 v117, v38, s0, v117
	v_pk_fma_f16 v116, v39, s0, v116
	v_pk_fma_f16 v113, v40, s0, v113
	v_pk_fma_f16 v112, v41, s0, v112
	v_pk_fma_f16 v67, v42, s0, v67
	v_pk_fma_f16 v66, v43, s0, v66
	v_pk_fma_f16 v65, v44, s0, v65
	v_pk_fma_f16 v64, v45, s0, v64
	v_pk_fma_f16 v125, v46, s0, v125
	v_pk_fma_f16 v122, v47, s0, v122
	s_waitcnt vmcnt(6)
	v_readlane_b32 s4, v49, 13
	v_readlane_b32 s0, v54, 11
	v_cvt_scalef32_pk_f16_fp4 v32, v24, 1.0
	v_cvt_scalef32_pk_f16_fp4 v33, v24, 1.0 op_sel:[1,0,0]
	v_cvt_scalef32_pk_f16_fp4 v34, v24, 1.0 op_sel:[0,1,0]
	v_cvt_scalef32_pk_f16_fp4 v35, v24, 1.0 op_sel:[1,1,0]
	v_cvt_scalef32_pk_f16_fp4 v36, v25, 1.0
	v_cvt_scalef32_pk_f16_fp4 v37, v25, 1.0 op_sel:[1,0,0]
	v_cvt_scalef32_pk_f16_fp4 v38, v25, 1.0 op_sel:[0,1,0]
	v_cvt_scalef32_pk_f16_fp4 v39, v25, 1.0 op_sel:[1,1,0]
	v_cvt_scalef32_pk_f16_fp4 v40, v26, 1.0
	v_cvt_scalef32_pk_f16_fp4 v41, v26, 1.0 op_sel:[1,0,0]
	v_cvt_scalef32_pk_f16_fp4 v42, v26, 1.0 op_sel:[0,1,0]
	v_cvt_scalef32_pk_f16_fp4 v43, v26, 1.0 op_sel:[1,1,0]
	v_cvt_scalef32_pk_f16_fp4 v44, v27, 1.0
	v_cvt_scalef32_pk_f16_fp4 v45, v27, 1.0 op_sel:[1,0,0]
	v_cvt_scalef32_pk_f16_fp4 v46, v27, 1.0 op_sel:[0,1,0]
	v_cvt_scalef32_pk_f16_fp4 v47, v27, 1.0 op_sel:[1,1,0]
	buffer_load_dwordx4 v[20:23], v115, s[12:15], s4 offen
	v_pk_fma_f16 v74, v32, s0, v74
	v_pk_fma_f16 v73, v33, s0, v73
	v_pk_fma_f16 v71, v34, s0, v71
	v_pk_fma_f16 v70, v35, s0, v70
	v_pk_fma_f16 v69, v36, s0, v69
	v_pk_fma_f16 v68, v37, s0, v68
	v_pk_fma_f16 v63, v38, s0, v63
	v_pk_fma_f16 v62, v39, s0, v62
	v_pk_fma_f16 v61, v40, s0, v61
	v_pk_fma_f16 v60, v41, s0, v60
	v_pk_fma_f16 v59, v42, s0, v59
	v_pk_fma_f16 v58, v43, s0, v58
	v_pk_fma_f16 v57, v44, s0, v57
	v_pk_fma_f16 v56, v45, s0, v56
	v_pk_fma_f16 v75, v46, s0, v75
	v_pk_fma_f16 v72, v47, s0, v72
	s_waitcnt vmcnt(6)
	v_readlane_b32 s4, v50, 13
	v_readlane_b32 s0, v55, 11
	v_cvt_scalef32_pk_f16_fp4 v32, v28, 1.0
	v_cvt_scalef32_pk_f16_fp4 v33, v28, 1.0 op_sel:[1,0,0]
	v_cvt_scalef32_pk_f16_fp4 v34, v28, 1.0 op_sel:[0,1,0]
	v_cvt_scalef32_pk_f16_fp4 v35, v28, 1.0 op_sel:[1,1,0]
	v_cvt_scalef32_pk_f16_fp4 v36, v29, 1.0
	v_cvt_scalef32_pk_f16_fp4 v37, v29, 1.0 op_sel:[1,0,0]
	v_cvt_scalef32_pk_f16_fp4 v38, v29, 1.0 op_sel:[0,1,0]
	v_cvt_scalef32_pk_f16_fp4 v39, v29, 1.0 op_sel:[1,1,0]
	v_cvt_scalef32_pk_f16_fp4 v40, v30, 1.0
	v_cvt_scalef32_pk_f16_fp4 v41, v30, 1.0 op_sel:[1,0,0]
	v_cvt_scalef32_pk_f16_fp4 v42, v30, 1.0 op_sel:[0,1,0]
	v_cvt_scalef32_pk_f16_fp4 v43, v30, 1.0 op_sel:[1,1,0]
	v_cvt_scalef32_pk_f16_fp4 v44, v31, 1.0
	v_cvt_scalef32_pk_f16_fp4 v45, v31, 1.0 op_sel:[1,0,0]
	v_cvt_scalef32_pk_f16_fp4 v46, v31, 1.0 op_sel:[0,1,0]
	v_cvt_scalef32_pk_f16_fp4 v47, v31, 1.0 op_sel:[1,1,0]
	buffer_load_dwordx4 v[24:27], v115, s[12:15], s4 offen
	v_pk_fma_f16 v162, v32, s0, v162
	v_pk_fma_f16 v161, v33, s0, v161
	v_pk_fma_f16 v160, v34, s0, v160
	v_pk_fma_f16 v159, v35, s0, v159
	v_pk_fma_f16 v158, v36, s0, v158
	v_pk_fma_f16 v157, v37, s0, v157
	v_pk_fma_f16 v156, v38, s0, v156
	v_pk_fma_f16 v147, v39, s0, v147
	v_pk_fma_f16 v146, v40, s0, v146
	v_pk_fma_f16 v145, v41, s0, v145
	v_pk_fma_f16 v144, v42, s0, v144
	v_pk_fma_f16 v143, v43, s0, v143
	v_pk_fma_f16 v142, v44, s0, v142
	v_pk_fma_f16 v141, v45, s0, v141
	v_pk_fma_f16 v149, v46, s0, v149
	v_pk_fma_f16 v148, v47, s0, v148
	s_waitcnt vmcnt(6)
	v_readlane_b32 s4, v51, 13
	v_readlane_b32 s0, v52, 12
	v_cvt_scalef32_pk_f16_fp4 v32, v0, 1.0
	v_cvt_scalef32_pk_f16_fp4 v33, v0, 1.0 op_sel:[1,0,0]
	v_cvt_scalef32_pk_f16_fp4 v34, v0, 1.0 op_sel:[0,1,0]
	v_cvt_scalef32_pk_f16_fp4 v35, v0, 1.0 op_sel:[1,1,0]
	v_cvt_scalef32_pk_f16_fp4 v36, v1, 1.0
	v_cvt_scalef32_pk_f16_fp4 v37, v1, 1.0 op_sel:[1,0,0]
	v_cvt_scalef32_pk_f16_fp4 v38, v1, 1.0 op_sel:[0,1,0]
	v_cvt_scalef32_pk_f16_fp4 v39, v1, 1.0 op_sel:[1,1,0]
	v_cvt_scalef32_pk_f16_fp4 v40, v2, 1.0
	v_cvt_scalef32_pk_f16_fp4 v41, v2, 1.0 op_sel:[1,0,0]
	v_cvt_scalef32_pk_f16_fp4 v42, v2, 1.0 op_sel:[0,1,0]
	v_cvt_scalef32_pk_f16_fp4 v43, v2, 1.0 op_sel:[1,1,0]
	v_cvt_scalef32_pk_f16_fp4 v44, v3, 1.0
	v_cvt_scalef32_pk_f16_fp4 v45, v3, 1.0 op_sel:[1,0,0]
	v_cvt_scalef32_pk_f16_fp4 v46, v3, 1.0 op_sel:[0,1,0]
	v_cvt_scalef32_pk_f16_fp4 v47, v3, 1.0 op_sel:[1,1,0]
	buffer_load_dwordx4 v[28:31], v115, s[12:15], s4 offen
	v_pk_fma_f16 v139, v32, s0, v139
	v_pk_fma_f16 v138, v33, s0, v138
	v_pk_fma_f16 v136, v34, s0, v136
	v_pk_fma_f16 v135, v35, s0, v135
	v_pk_fma_f16 v134, v36, s0, v134
	v_pk_fma_f16 v133, v37, s0, v133
	v_pk_fma_f16 v132, v38, s0, v132
	v_pk_fma_f16 v131, v39, s0, v131
	v_pk_fma_f16 v130, v40, s0, v130
	v_pk_fma_f16 v129, v41, s0, v129
	v_pk_fma_f16 v128, v42, s0, v128
	v_pk_fma_f16 v127, v43, s0, v127
	v_pk_fma_f16 v126, v44, s0, v126
	v_pk_fma_f16 v114, v45, s0, v114
	v_pk_fma_f16 v140, v46, s0, v140
	v_pk_fma_f16 v137, v47, s0, v137
	s_waitcnt vmcnt(6)
	v_readlane_b32 s4, v48, 14
	v_readlane_b32 s0, v53, 12
	v_cvt_scalef32_pk_f16_fp4 v32, v4, 1.0
	v_cvt_scalef32_pk_f16_fp4 v33, v4, 1.0 op_sel:[1,0,0]
	v_cvt_scalef32_pk_f16_fp4 v34, v4, 1.0 op_sel:[0,1,0]
	v_cvt_scalef32_pk_f16_fp4 v35, v4, 1.0 op_sel:[1,1,0]
	v_cvt_scalef32_pk_f16_fp4 v36, v5, 1.0
	v_cvt_scalef32_pk_f16_fp4 v37, v5, 1.0 op_sel:[1,0,0]
	v_cvt_scalef32_pk_f16_fp4 v38, v5, 1.0 op_sel:[0,1,0]
	v_cvt_scalef32_pk_f16_fp4 v39, v5, 1.0 op_sel:[1,1,0]
	v_cvt_scalef32_pk_f16_fp4 v40, v6, 1.0
	v_cvt_scalef32_pk_f16_fp4 v41, v6, 1.0 op_sel:[1,0,0]
	v_cvt_scalef32_pk_f16_fp4 v42, v6, 1.0 op_sel:[0,1,0]
	v_cvt_scalef32_pk_f16_fp4 v43, v6, 1.0 op_sel:[1,1,0]
	v_cvt_scalef32_pk_f16_fp4 v44, v7, 1.0
	v_cvt_scalef32_pk_f16_fp4 v45, v7, 1.0 op_sel:[1,0,0]
	v_cvt_scalef32_pk_f16_fp4 v46, v7, 1.0 op_sel:[0,1,0]
	v_cvt_scalef32_pk_f16_fp4 v47, v7, 1.0 op_sel:[1,1,0]
	buffer_load_dwordx4 v[0:3], v115, s[12:15], s4 offen
	v_pk_fma_f16 v124, v32, s0, v124
	v_pk_fma_f16 v123, v33, s0, v123
	v_pk_fma_f16 v121, v34, s0, v121
	v_pk_fma_f16 v120, v35, s0, v120
	v_pk_fma_f16 v119, v36, s0, v119
	v_pk_fma_f16 v118, v37, s0, v118
	v_pk_fma_f16 v117, v38, s0, v117
	v_pk_fma_f16 v116, v39, s0, v116
	v_pk_fma_f16 v113, v40, s0, v113
	v_pk_fma_f16 v112, v41, s0, v112
	v_pk_fma_f16 v67, v42, s0, v67
	v_pk_fma_f16 v66, v43, s0, v66
	v_pk_fma_f16 v65, v44, s0, v65
	v_pk_fma_f16 v64, v45, s0, v64
	v_pk_fma_f16 v125, v46, s0, v125
	v_pk_fma_f16 v122, v47, s0, v122
	s_waitcnt vmcnt(6)
	v_readlane_b32 s4, v49, 14
	v_readlane_b32 s0, v54, 12
	v_cvt_scalef32_pk_f16_fp4 v32, v8, 1.0
	v_cvt_scalef32_pk_f16_fp4 v33, v8, 1.0 op_sel:[1,0,0]
	v_cvt_scalef32_pk_f16_fp4 v34, v8, 1.0 op_sel:[0,1,0]
	v_cvt_scalef32_pk_f16_fp4 v35, v8, 1.0 op_sel:[1,1,0]
	v_cvt_scalef32_pk_f16_fp4 v36, v9, 1.0
	v_cvt_scalef32_pk_f16_fp4 v37, v9, 1.0 op_sel:[1,0,0]
	v_cvt_scalef32_pk_f16_fp4 v38, v9, 1.0 op_sel:[0,1,0]
	v_cvt_scalef32_pk_f16_fp4 v39, v9, 1.0 op_sel:[1,1,0]
	v_cvt_scalef32_pk_f16_fp4 v40, v10, 1.0
	v_cvt_scalef32_pk_f16_fp4 v41, v10, 1.0 op_sel:[1,0,0]
	v_cvt_scalef32_pk_f16_fp4 v42, v10, 1.0 op_sel:[0,1,0]
	v_cvt_scalef32_pk_f16_fp4 v43, v10, 1.0 op_sel:[1,1,0]
	v_cvt_scalef32_pk_f16_fp4 v44, v11, 1.0
	v_cvt_scalef32_pk_f16_fp4 v45, v11, 1.0 op_sel:[1,0,0]
	v_cvt_scalef32_pk_f16_fp4 v46, v11, 1.0 op_sel:[0,1,0]
	v_cvt_scalef32_pk_f16_fp4 v47, v11, 1.0 op_sel:[1,1,0]
	buffer_load_dwordx4 v[4:7], v115, s[12:15], s4 offen
	v_pk_fma_f16 v74, v32, s0, v74
	v_pk_fma_f16 v73, v33, s0, v73
	v_pk_fma_f16 v71, v34, s0, v71
	v_pk_fma_f16 v70, v35, s0, v70
	v_pk_fma_f16 v69, v36, s0, v69
	v_pk_fma_f16 v68, v37, s0, v68
	v_pk_fma_f16 v63, v38, s0, v63
	v_pk_fma_f16 v62, v39, s0, v62
	v_pk_fma_f16 v61, v40, s0, v61
	v_pk_fma_f16 v60, v41, s0, v60
	v_pk_fma_f16 v59, v42, s0, v59
	v_pk_fma_f16 v58, v43, s0, v58
	v_pk_fma_f16 v57, v44, s0, v57
	v_pk_fma_f16 v56, v45, s0, v56
	v_pk_fma_f16 v75, v46, s0, v75
	v_pk_fma_f16 v72, v47, s0, v72
	s_waitcnt vmcnt(6)
	v_readlane_b32 s4, v50, 14
	v_readlane_b32 s0, v55, 12
	v_cvt_scalef32_pk_f16_fp4 v32, v12, 1.0
	v_cvt_scalef32_pk_f16_fp4 v33, v12, 1.0 op_sel:[1,0,0]
	v_cvt_scalef32_pk_f16_fp4 v34, v12, 1.0 op_sel:[0,1,0]
	v_cvt_scalef32_pk_f16_fp4 v35, v12, 1.0 op_sel:[1,1,0]
	v_cvt_scalef32_pk_f16_fp4 v36, v13, 1.0
	v_cvt_scalef32_pk_f16_fp4 v37, v13, 1.0 op_sel:[1,0,0]
	v_cvt_scalef32_pk_f16_fp4 v38, v13, 1.0 op_sel:[0,1,0]
	v_cvt_scalef32_pk_f16_fp4 v39, v13, 1.0 op_sel:[1,1,0]
	v_cvt_scalef32_pk_f16_fp4 v40, v14, 1.0
	v_cvt_scalef32_pk_f16_fp4 v41, v14, 1.0 op_sel:[1,0,0]
	v_cvt_scalef32_pk_f16_fp4 v42, v14, 1.0 op_sel:[0,1,0]
	v_cvt_scalef32_pk_f16_fp4 v43, v14, 1.0 op_sel:[1,1,0]
	v_cvt_scalef32_pk_f16_fp4 v44, v15, 1.0
	v_cvt_scalef32_pk_f16_fp4 v45, v15, 1.0 op_sel:[1,0,0]
	v_cvt_scalef32_pk_f16_fp4 v46, v15, 1.0 op_sel:[0,1,0]
	v_cvt_scalef32_pk_f16_fp4 v47, v15, 1.0 op_sel:[1,1,0]
	buffer_load_dwordx4 v[8:11], v115, s[12:15], s4 offen
	v_pk_fma_f16 v162, v32, s0, v162
	v_pk_fma_f16 v161, v33, s0, v161
	v_pk_fma_f16 v160, v34, s0, v160
	v_pk_fma_f16 v159, v35, s0, v159
	v_pk_fma_f16 v158, v36, s0, v158
	v_pk_fma_f16 v157, v37, s0, v157
	v_pk_fma_f16 v156, v38, s0, v156
	v_pk_fma_f16 v147, v39, s0, v147
	v_pk_fma_f16 v146, v40, s0, v146
	v_pk_fma_f16 v145, v41, s0, v145
	v_pk_fma_f16 v144, v42, s0, v144
	v_pk_fma_f16 v143, v43, s0, v143
	v_pk_fma_f16 v142, v44, s0, v142
	v_pk_fma_f16 v141, v45, s0, v141
	v_pk_fma_f16 v149, v46, s0, v149
	v_pk_fma_f16 v148, v47, s0, v148
	s_waitcnt vmcnt(6)
	v_readlane_b32 s4, v51, 14
	v_readlane_b32 s0, v52, 13
	v_cvt_scalef32_pk_f16_fp4 v32, v16, 1.0
	v_cvt_scalef32_pk_f16_fp4 v33, v16, 1.0 op_sel:[1,0,0]
	v_cvt_scalef32_pk_f16_fp4 v34, v16, 1.0 op_sel:[0,1,0]
	v_cvt_scalef32_pk_f16_fp4 v35, v16, 1.0 op_sel:[1,1,0]
	v_cvt_scalef32_pk_f16_fp4 v36, v17, 1.0
	v_cvt_scalef32_pk_f16_fp4 v37, v17, 1.0 op_sel:[1,0,0]
	v_cvt_scalef32_pk_f16_fp4 v38, v17, 1.0 op_sel:[0,1,0]
	v_cvt_scalef32_pk_f16_fp4 v39, v17, 1.0 op_sel:[1,1,0]
	v_cvt_scalef32_pk_f16_fp4 v40, v18, 1.0
	v_cvt_scalef32_pk_f16_fp4 v41, v18, 1.0 op_sel:[1,0,0]
	v_cvt_scalef32_pk_f16_fp4 v42, v18, 1.0 op_sel:[0,1,0]
	v_cvt_scalef32_pk_f16_fp4 v43, v18, 1.0 op_sel:[1,1,0]
	v_cvt_scalef32_pk_f16_fp4 v44, v19, 1.0
	v_cvt_scalef32_pk_f16_fp4 v45, v19, 1.0 op_sel:[1,0,0]
	v_cvt_scalef32_pk_f16_fp4 v46, v19, 1.0 op_sel:[0,1,0]
	v_cvt_scalef32_pk_f16_fp4 v47, v19, 1.0 op_sel:[1,1,0]
	buffer_load_dwordx4 v[12:15], v115, s[12:15], s4 offen
	v_pk_fma_f16 v139, v32, s0, v139
	v_pk_fma_f16 v138, v33, s0, v138
	v_pk_fma_f16 v136, v34, s0, v136
	v_pk_fma_f16 v135, v35, s0, v135
	v_pk_fma_f16 v134, v36, s0, v134
	v_pk_fma_f16 v133, v37, s0, v133
	v_pk_fma_f16 v132, v38, s0, v132
	v_pk_fma_f16 v131, v39, s0, v131
	v_pk_fma_f16 v130, v40, s0, v130
	v_pk_fma_f16 v129, v41, s0, v129
	v_pk_fma_f16 v128, v42, s0, v128
	v_pk_fma_f16 v127, v43, s0, v127
	v_pk_fma_f16 v126, v44, s0, v126
	v_pk_fma_f16 v114, v45, s0, v114
	v_pk_fma_f16 v140, v46, s0, v140
	v_pk_fma_f16 v137, v47, s0, v137
	s_waitcnt vmcnt(6)
	v_readlane_b32 s4, v48, 15
	v_readlane_b32 s0, v53, 13
	v_cvt_scalef32_pk_f16_fp4 v32, v20, 1.0
	v_cvt_scalef32_pk_f16_fp4 v33, v20, 1.0 op_sel:[1,0,0]
	v_cvt_scalef32_pk_f16_fp4 v34, v20, 1.0 op_sel:[0,1,0]
	v_cvt_scalef32_pk_f16_fp4 v35, v20, 1.0 op_sel:[1,1,0]
	v_cvt_scalef32_pk_f16_fp4 v36, v21, 1.0
	v_cvt_scalef32_pk_f16_fp4 v37, v21, 1.0 op_sel:[1,0,0]
	v_cvt_scalef32_pk_f16_fp4 v38, v21, 1.0 op_sel:[0,1,0]
	v_cvt_scalef32_pk_f16_fp4 v39, v21, 1.0 op_sel:[1,1,0]
	v_cvt_scalef32_pk_f16_fp4 v40, v22, 1.0
	v_cvt_scalef32_pk_f16_fp4 v41, v22, 1.0 op_sel:[1,0,0]
	v_cvt_scalef32_pk_f16_fp4 v42, v22, 1.0 op_sel:[0,1,0]
	v_cvt_scalef32_pk_f16_fp4 v43, v22, 1.0 op_sel:[1,1,0]
	v_cvt_scalef32_pk_f16_fp4 v44, v23, 1.0
	v_cvt_scalef32_pk_f16_fp4 v45, v23, 1.0 op_sel:[1,0,0]
	v_cvt_scalef32_pk_f16_fp4 v46, v23, 1.0 op_sel:[0,1,0]
	v_cvt_scalef32_pk_f16_fp4 v47, v23, 1.0 op_sel:[1,1,0]
	buffer_load_dwordx4 v[16:19], v115, s[12:15], s4 offen
	v_pk_fma_f16 v124, v32, s0, v124
	v_pk_fma_f16 v123, v33, s0, v123
	v_pk_fma_f16 v121, v34, s0, v121
	v_pk_fma_f16 v120, v35, s0, v120
	v_pk_fma_f16 v119, v36, s0, v119
	v_pk_fma_f16 v118, v37, s0, v118
	v_pk_fma_f16 v117, v38, s0, v117
	v_pk_fma_f16 v116, v39, s0, v116
	v_pk_fma_f16 v113, v40, s0, v113
	v_pk_fma_f16 v112, v41, s0, v112
	v_pk_fma_f16 v67, v42, s0, v67
	v_pk_fma_f16 v66, v43, s0, v66
	v_pk_fma_f16 v65, v44, s0, v65
	v_pk_fma_f16 v64, v45, s0, v64
	v_pk_fma_f16 v125, v46, s0, v125
	v_pk_fma_f16 v122, v47, s0, v122
	s_waitcnt vmcnt(6)
	v_readlane_b32 s4, v49, 15
	v_readlane_b32 s0, v54, 13
	v_cvt_scalef32_pk_f16_fp4 v32, v24, 1.0
	v_cvt_scalef32_pk_f16_fp4 v33, v24, 1.0 op_sel:[1,0,0]
	v_cvt_scalef32_pk_f16_fp4 v34, v24, 1.0 op_sel:[0,1,0]
	v_cvt_scalef32_pk_f16_fp4 v35, v24, 1.0 op_sel:[1,1,0]
	v_cvt_scalef32_pk_f16_fp4 v36, v25, 1.0
	v_cvt_scalef32_pk_f16_fp4 v37, v25, 1.0 op_sel:[1,0,0]
	v_cvt_scalef32_pk_f16_fp4 v38, v25, 1.0 op_sel:[0,1,0]
	v_cvt_scalef32_pk_f16_fp4 v39, v25, 1.0 op_sel:[1,1,0]
	v_cvt_scalef32_pk_f16_fp4 v40, v26, 1.0
	v_cvt_scalef32_pk_f16_fp4 v41, v26, 1.0 op_sel:[1,0,0]
	v_cvt_scalef32_pk_f16_fp4 v42, v26, 1.0 op_sel:[0,1,0]
	v_cvt_scalef32_pk_f16_fp4 v43, v26, 1.0 op_sel:[1,1,0]
	v_cvt_scalef32_pk_f16_fp4 v44, v27, 1.0
	v_cvt_scalef32_pk_f16_fp4 v45, v27, 1.0 op_sel:[1,0,0]
	v_cvt_scalef32_pk_f16_fp4 v46, v27, 1.0 op_sel:[0,1,0]
	v_cvt_scalef32_pk_f16_fp4 v47, v27, 1.0 op_sel:[1,1,0]
	buffer_load_dwordx4 v[20:23], v115, s[12:15], s4 offen
	v_pk_fma_f16 v74, v32, s0, v74
	v_pk_fma_f16 v73, v33, s0, v73
	v_pk_fma_f16 v71, v34, s0, v71
	v_pk_fma_f16 v70, v35, s0, v70
	v_pk_fma_f16 v69, v36, s0, v69
	v_pk_fma_f16 v68, v37, s0, v68
	v_pk_fma_f16 v63, v38, s0, v63
	v_pk_fma_f16 v62, v39, s0, v62
	v_pk_fma_f16 v61, v40, s0, v61
	v_pk_fma_f16 v60, v41, s0, v60
	v_pk_fma_f16 v59, v42, s0, v59
	v_pk_fma_f16 v58, v43, s0, v58
	v_pk_fma_f16 v57, v44, s0, v57
	v_pk_fma_f16 v56, v45, s0, v56
	v_pk_fma_f16 v75, v46, s0, v75
	v_pk_fma_f16 v72, v47, s0, v72
	s_waitcnt vmcnt(6)
	v_readlane_b32 s4, v50, 15
	v_readlane_b32 s0, v55, 13
	v_cvt_scalef32_pk_f16_fp4 v32, v28, 1.0
	v_cvt_scalef32_pk_f16_fp4 v33, v28, 1.0 op_sel:[1,0,0]
	v_cvt_scalef32_pk_f16_fp4 v34, v28, 1.0 op_sel:[0,1,0]
	v_cvt_scalef32_pk_f16_fp4 v35, v28, 1.0 op_sel:[1,1,0]
	v_cvt_scalef32_pk_f16_fp4 v36, v29, 1.0
	v_cvt_scalef32_pk_f16_fp4 v37, v29, 1.0 op_sel:[1,0,0]
	v_cvt_scalef32_pk_f16_fp4 v38, v29, 1.0 op_sel:[0,1,0]
	v_cvt_scalef32_pk_f16_fp4 v39, v29, 1.0 op_sel:[1,1,0]
	v_cvt_scalef32_pk_f16_fp4 v40, v30, 1.0
	v_cvt_scalef32_pk_f16_fp4 v41, v30, 1.0 op_sel:[1,0,0]
	v_cvt_scalef32_pk_f16_fp4 v42, v30, 1.0 op_sel:[0,1,0]
	v_cvt_scalef32_pk_f16_fp4 v43, v30, 1.0 op_sel:[1,1,0]
	v_cvt_scalef32_pk_f16_fp4 v44, v31, 1.0
	v_cvt_scalef32_pk_f16_fp4 v45, v31, 1.0 op_sel:[1,0,0]
	v_cvt_scalef32_pk_f16_fp4 v46, v31, 1.0 op_sel:[0,1,0]
	v_cvt_scalef32_pk_f16_fp4 v47, v31, 1.0 op_sel:[1,1,0]
	buffer_load_dwordx4 v[24:27], v115, s[12:15], s4 offen
	v_pk_fma_f16 v162, v32, s0, v162
	v_pk_fma_f16 v161, v33, s0, v161
	v_pk_fma_f16 v160, v34, s0, v160
	v_pk_fma_f16 v159, v35, s0, v159
	v_pk_fma_f16 v158, v36, s0, v158
	v_pk_fma_f16 v157, v37, s0, v157
	v_pk_fma_f16 v156, v38, s0, v156
	v_pk_fma_f16 v147, v39, s0, v147
	v_pk_fma_f16 v146, v40, s0, v146
	v_pk_fma_f16 v145, v41, s0, v145
	v_pk_fma_f16 v144, v42, s0, v144
	v_pk_fma_f16 v143, v43, s0, v143
	v_pk_fma_f16 v142, v44, s0, v142
	v_pk_fma_f16 v141, v45, s0, v141
	v_pk_fma_f16 v149, v46, s0, v149
	v_pk_fma_f16 v148, v47, s0, v148
	s_waitcnt vmcnt(6)
	v_readlane_b32 s4, v51, 15
	v_readlane_b32 s0, v52, 14
	v_cvt_scalef32_pk_f16_fp4 v32, v0, 1.0
	v_cvt_scalef32_pk_f16_fp4 v33, v0, 1.0 op_sel:[1,0,0]
	v_cvt_scalef32_pk_f16_fp4 v34, v0, 1.0 op_sel:[0,1,0]
	v_cvt_scalef32_pk_f16_fp4 v35, v0, 1.0 op_sel:[1,1,0]
	v_cvt_scalef32_pk_f16_fp4 v36, v1, 1.0
	v_cvt_scalef32_pk_f16_fp4 v37, v1, 1.0 op_sel:[1,0,0]
	v_cvt_scalef32_pk_f16_fp4 v38, v1, 1.0 op_sel:[0,1,0]
	v_cvt_scalef32_pk_f16_fp4 v39, v1, 1.0 op_sel:[1,1,0]
	v_cvt_scalef32_pk_f16_fp4 v40, v2, 1.0
	v_cvt_scalef32_pk_f16_fp4 v41, v2, 1.0 op_sel:[1,0,0]
	v_cvt_scalef32_pk_f16_fp4 v42, v2, 1.0 op_sel:[0,1,0]
	v_cvt_scalef32_pk_f16_fp4 v43, v2, 1.0 op_sel:[1,1,0]
	v_cvt_scalef32_pk_f16_fp4 v44, v3, 1.0
	v_cvt_scalef32_pk_f16_fp4 v45, v3, 1.0 op_sel:[1,0,0]
	v_cvt_scalef32_pk_f16_fp4 v46, v3, 1.0 op_sel:[0,1,0]
	v_cvt_scalef32_pk_f16_fp4 v47, v3, 1.0 op_sel:[1,1,0]
	buffer_load_dwordx4 v[28:31], v115, s[12:15], s4 offen
	v_pk_fma_f16 v139, v32, s0, v139
	v_pk_fma_f16 v138, v33, s0, v138
	v_pk_fma_f16 v136, v34, s0, v136
	v_pk_fma_f16 v135, v35, s0, v135
	v_pk_fma_f16 v134, v36, s0, v134
	v_pk_fma_f16 v133, v37, s0, v133
	v_pk_fma_f16 v132, v38, s0, v132
	v_pk_fma_f16 v131, v39, s0, v131
	v_pk_fma_f16 v130, v40, s0, v130
	v_pk_fma_f16 v129, v41, s0, v129
	v_pk_fma_f16 v128, v42, s0, v128
	v_pk_fma_f16 v127, v43, s0, v127
	v_pk_fma_f16 v126, v44, s0, v126
	v_pk_fma_f16 v114, v45, s0, v114
	v_pk_fma_f16 v140, v46, s0, v140
	v_pk_fma_f16 v137, v47, s0, v137
	s_waitcnt vmcnt(6)
	v_readlane_b32 s4, v48, 16
	v_readlane_b32 s0, v53, 14
	v_cvt_scalef32_pk_f16_fp4 v32, v4, 1.0
	v_cvt_scalef32_pk_f16_fp4 v33, v4, 1.0 op_sel:[1,0,0]
	v_cvt_scalef32_pk_f16_fp4 v34, v4, 1.0 op_sel:[0,1,0]
	v_cvt_scalef32_pk_f16_fp4 v35, v4, 1.0 op_sel:[1,1,0]
	v_cvt_scalef32_pk_f16_fp4 v36, v5, 1.0
	v_cvt_scalef32_pk_f16_fp4 v37, v5, 1.0 op_sel:[1,0,0]
	v_cvt_scalef32_pk_f16_fp4 v38, v5, 1.0 op_sel:[0,1,0]
	v_cvt_scalef32_pk_f16_fp4 v39, v5, 1.0 op_sel:[1,1,0]
	v_cvt_scalef32_pk_f16_fp4 v40, v6, 1.0
	v_cvt_scalef32_pk_f16_fp4 v41, v6, 1.0 op_sel:[1,0,0]
	v_cvt_scalef32_pk_f16_fp4 v42, v6, 1.0 op_sel:[0,1,0]
	v_cvt_scalef32_pk_f16_fp4 v43, v6, 1.0 op_sel:[1,1,0]
	v_cvt_scalef32_pk_f16_fp4 v44, v7, 1.0
	v_cvt_scalef32_pk_f16_fp4 v45, v7, 1.0 op_sel:[1,0,0]
	v_cvt_scalef32_pk_f16_fp4 v46, v7, 1.0 op_sel:[0,1,0]
	v_cvt_scalef32_pk_f16_fp4 v47, v7, 1.0 op_sel:[1,1,0]
	buffer_load_dwordx4 v[0:3], v115, s[12:15], s4 offen
	v_pk_fma_f16 v124, v32, s0, v124
	v_pk_fma_f16 v123, v33, s0, v123
	v_pk_fma_f16 v121, v34, s0, v121
	v_pk_fma_f16 v120, v35, s0, v120
	v_pk_fma_f16 v119, v36, s0, v119
	v_pk_fma_f16 v118, v37, s0, v118
	v_pk_fma_f16 v117, v38, s0, v117
	v_pk_fma_f16 v116, v39, s0, v116
	v_pk_fma_f16 v113, v40, s0, v113
	v_pk_fma_f16 v112, v41, s0, v112
	v_pk_fma_f16 v67, v42, s0, v67
	v_pk_fma_f16 v66, v43, s0, v66
	v_pk_fma_f16 v65, v44, s0, v65
	v_pk_fma_f16 v64, v45, s0, v64
	v_pk_fma_f16 v125, v46, s0, v125
	v_pk_fma_f16 v122, v47, s0, v122
	s_waitcnt vmcnt(6)
	v_readlane_b32 s4, v49, 16
	v_readlane_b32 s0, v54, 14
	v_cvt_scalef32_pk_f16_fp4 v32, v8, 1.0
	v_cvt_scalef32_pk_f16_fp4 v33, v8, 1.0 op_sel:[1,0,0]
	v_cvt_scalef32_pk_f16_fp4 v34, v8, 1.0 op_sel:[0,1,0]
	v_cvt_scalef32_pk_f16_fp4 v35, v8, 1.0 op_sel:[1,1,0]
	v_cvt_scalef32_pk_f16_fp4 v36, v9, 1.0
	v_cvt_scalef32_pk_f16_fp4 v37, v9, 1.0 op_sel:[1,0,0]
	v_cvt_scalef32_pk_f16_fp4 v38, v9, 1.0 op_sel:[0,1,0]
	v_cvt_scalef32_pk_f16_fp4 v39, v9, 1.0 op_sel:[1,1,0]
	v_cvt_scalef32_pk_f16_fp4 v40, v10, 1.0
	v_cvt_scalef32_pk_f16_fp4 v41, v10, 1.0 op_sel:[1,0,0]
	v_cvt_scalef32_pk_f16_fp4 v42, v10, 1.0 op_sel:[0,1,0]
	v_cvt_scalef32_pk_f16_fp4 v43, v10, 1.0 op_sel:[1,1,0]
	v_cvt_scalef32_pk_f16_fp4 v44, v11, 1.0
	v_cvt_scalef32_pk_f16_fp4 v45, v11, 1.0 op_sel:[1,0,0]
	v_cvt_scalef32_pk_f16_fp4 v46, v11, 1.0 op_sel:[0,1,0]
	v_cvt_scalef32_pk_f16_fp4 v47, v11, 1.0 op_sel:[1,1,0]
	buffer_load_dwordx4 v[4:7], v115, s[12:15], s4 offen
	v_pk_fma_f16 v74, v32, s0, v74
	v_pk_fma_f16 v73, v33, s0, v73
	v_pk_fma_f16 v71, v34, s0, v71
	v_pk_fma_f16 v70, v35, s0, v70
	v_pk_fma_f16 v69, v36, s0, v69
	v_pk_fma_f16 v68, v37, s0, v68
	v_pk_fma_f16 v63, v38, s0, v63
	v_pk_fma_f16 v62, v39, s0, v62
	v_pk_fma_f16 v61, v40, s0, v61
	v_pk_fma_f16 v60, v41, s0, v60
	v_pk_fma_f16 v59, v42, s0, v59
	v_pk_fma_f16 v58, v43, s0, v58
	v_pk_fma_f16 v57, v44, s0, v57
	v_pk_fma_f16 v56, v45, s0, v56
	v_pk_fma_f16 v75, v46, s0, v75
	v_pk_fma_f16 v72, v47, s0, v72
	s_waitcnt vmcnt(6)
	v_readlane_b32 s4, v50, 16
	v_readlane_b32 s0, v55, 14
	v_cvt_scalef32_pk_f16_fp4 v32, v12, 1.0
	v_cvt_scalef32_pk_f16_fp4 v33, v12, 1.0 op_sel:[1,0,0]
	v_cvt_scalef32_pk_f16_fp4 v34, v12, 1.0 op_sel:[0,1,0]
	v_cvt_scalef32_pk_f16_fp4 v35, v12, 1.0 op_sel:[1,1,0]
	v_cvt_scalef32_pk_f16_fp4 v36, v13, 1.0
	v_cvt_scalef32_pk_f16_fp4 v37, v13, 1.0 op_sel:[1,0,0]
	v_cvt_scalef32_pk_f16_fp4 v38, v13, 1.0 op_sel:[0,1,0]
	v_cvt_scalef32_pk_f16_fp4 v39, v13, 1.0 op_sel:[1,1,0]
	v_cvt_scalef32_pk_f16_fp4 v40, v14, 1.0
	v_cvt_scalef32_pk_f16_fp4 v41, v14, 1.0 op_sel:[1,0,0]
	v_cvt_scalef32_pk_f16_fp4 v42, v14, 1.0 op_sel:[0,1,0]
	v_cvt_scalef32_pk_f16_fp4 v43, v14, 1.0 op_sel:[1,1,0]
	v_cvt_scalef32_pk_f16_fp4 v44, v15, 1.0
	v_cvt_scalef32_pk_f16_fp4 v45, v15, 1.0 op_sel:[1,0,0]
	v_cvt_scalef32_pk_f16_fp4 v46, v15, 1.0 op_sel:[0,1,0]
	v_cvt_scalef32_pk_f16_fp4 v47, v15, 1.0 op_sel:[1,1,0]
	buffer_load_dwordx4 v[8:11], v115, s[12:15], s4 offen
	v_pk_fma_f16 v162, v32, s0, v162
	v_pk_fma_f16 v161, v33, s0, v161
	v_pk_fma_f16 v160, v34, s0, v160
	v_pk_fma_f16 v159, v35, s0, v159
	v_pk_fma_f16 v158, v36, s0, v158
	v_pk_fma_f16 v157, v37, s0, v157
	v_pk_fma_f16 v156, v38, s0, v156
	v_pk_fma_f16 v147, v39, s0, v147
	v_pk_fma_f16 v146, v40, s0, v146
	v_pk_fma_f16 v145, v41, s0, v145
	v_pk_fma_f16 v144, v42, s0, v144
	v_pk_fma_f16 v143, v43, s0, v143
	v_pk_fma_f16 v142, v44, s0, v142
	v_pk_fma_f16 v141, v45, s0, v141
	v_pk_fma_f16 v149, v46, s0, v149
	v_pk_fma_f16 v148, v47, s0, v148
	s_waitcnt vmcnt(6)
	v_readlane_b32 s4, v51, 16
	v_readlane_b32 s0, v52, 15
	v_cvt_scalef32_pk_f16_fp4 v32, v16, 1.0
	v_cvt_scalef32_pk_f16_fp4 v33, v16, 1.0 op_sel:[1,0,0]
	v_cvt_scalef32_pk_f16_fp4 v34, v16, 1.0 op_sel:[0,1,0]
	v_cvt_scalef32_pk_f16_fp4 v35, v16, 1.0 op_sel:[1,1,0]
	v_cvt_scalef32_pk_f16_fp4 v36, v17, 1.0
	v_cvt_scalef32_pk_f16_fp4 v37, v17, 1.0 op_sel:[1,0,0]
	v_cvt_scalef32_pk_f16_fp4 v38, v17, 1.0 op_sel:[0,1,0]
	v_cvt_scalef32_pk_f16_fp4 v39, v17, 1.0 op_sel:[1,1,0]
	v_cvt_scalef32_pk_f16_fp4 v40, v18, 1.0
	v_cvt_scalef32_pk_f16_fp4 v41, v18, 1.0 op_sel:[1,0,0]
	v_cvt_scalef32_pk_f16_fp4 v42, v18, 1.0 op_sel:[0,1,0]
	v_cvt_scalef32_pk_f16_fp4 v43, v18, 1.0 op_sel:[1,1,0]
	v_cvt_scalef32_pk_f16_fp4 v44, v19, 1.0
	v_cvt_scalef32_pk_f16_fp4 v45, v19, 1.0 op_sel:[1,0,0]
	v_cvt_scalef32_pk_f16_fp4 v46, v19, 1.0 op_sel:[0,1,0]
	v_cvt_scalef32_pk_f16_fp4 v47, v19, 1.0 op_sel:[1,1,0]
	buffer_load_dwordx4 v[12:15], v115, s[12:15], s4 offen
	v_pk_fma_f16 v139, v32, s0, v139
	v_pk_fma_f16 v138, v33, s0, v138
	v_pk_fma_f16 v136, v34, s0, v136
	v_pk_fma_f16 v135, v35, s0, v135
	v_pk_fma_f16 v134, v36, s0, v134
	v_pk_fma_f16 v133, v37, s0, v133
	v_pk_fma_f16 v132, v38, s0, v132
	v_pk_fma_f16 v131, v39, s0, v131
	v_pk_fma_f16 v130, v40, s0, v130
	v_pk_fma_f16 v129, v41, s0, v129
	v_pk_fma_f16 v128, v42, s0, v128
	v_pk_fma_f16 v127, v43, s0, v127
	v_pk_fma_f16 v126, v44, s0, v126
	v_pk_fma_f16 v114, v45, s0, v114
	v_pk_fma_f16 v140, v46, s0, v140
	v_pk_fma_f16 v137, v47, s0, v137
	s_waitcnt vmcnt(6)
	v_readlane_b32 s4, v48, 17
	v_readlane_b32 s0, v53, 15
	v_cvt_scalef32_pk_f16_fp4 v32, v20, 1.0
	v_cvt_scalef32_pk_f16_fp4 v33, v20, 1.0 op_sel:[1,0,0]
	v_cvt_scalef32_pk_f16_fp4 v34, v20, 1.0 op_sel:[0,1,0]
	v_cvt_scalef32_pk_f16_fp4 v35, v20, 1.0 op_sel:[1,1,0]
	v_cvt_scalef32_pk_f16_fp4 v36, v21, 1.0
	v_cvt_scalef32_pk_f16_fp4 v37, v21, 1.0 op_sel:[1,0,0]
	v_cvt_scalef32_pk_f16_fp4 v38, v21, 1.0 op_sel:[0,1,0]
	v_cvt_scalef32_pk_f16_fp4 v39, v21, 1.0 op_sel:[1,1,0]
	v_cvt_scalef32_pk_f16_fp4 v40, v22, 1.0
	v_cvt_scalef32_pk_f16_fp4 v41, v22, 1.0 op_sel:[1,0,0]
	v_cvt_scalef32_pk_f16_fp4 v42, v22, 1.0 op_sel:[0,1,0]
	v_cvt_scalef32_pk_f16_fp4 v43, v22, 1.0 op_sel:[1,1,0]
	v_cvt_scalef32_pk_f16_fp4 v44, v23, 1.0
	v_cvt_scalef32_pk_f16_fp4 v45, v23, 1.0 op_sel:[1,0,0]
	v_cvt_scalef32_pk_f16_fp4 v46, v23, 1.0 op_sel:[0,1,0]
	v_cvt_scalef32_pk_f16_fp4 v47, v23, 1.0 op_sel:[1,1,0]
	buffer_load_dwordx4 v[16:19], v115, s[12:15], s4 offen
	v_pk_fma_f16 v124, v32, s0, v124
	v_pk_fma_f16 v123, v33, s0, v123
	v_pk_fma_f16 v121, v34, s0, v121
	v_pk_fma_f16 v120, v35, s0, v120
	v_pk_fma_f16 v119, v36, s0, v119
	v_pk_fma_f16 v118, v37, s0, v118
	v_pk_fma_f16 v117, v38, s0, v117
	v_pk_fma_f16 v116, v39, s0, v116
	v_pk_fma_f16 v113, v40, s0, v113
	v_pk_fma_f16 v112, v41, s0, v112
	v_pk_fma_f16 v67, v42, s0, v67
	v_pk_fma_f16 v66, v43, s0, v66
	v_pk_fma_f16 v65, v44, s0, v65
	v_pk_fma_f16 v64, v45, s0, v64
	v_pk_fma_f16 v125, v46, s0, v125
	v_pk_fma_f16 v122, v47, s0, v122
	s_waitcnt vmcnt(6)
	v_readlane_b32 s4, v49, 17
	v_readlane_b32 s0, v54, 15
	v_cvt_scalef32_pk_f16_fp4 v32, v24, 1.0
	v_cvt_scalef32_pk_f16_fp4 v33, v24, 1.0 op_sel:[1,0,0]
	v_cvt_scalef32_pk_f16_fp4 v34, v24, 1.0 op_sel:[0,1,0]
	v_cvt_scalef32_pk_f16_fp4 v35, v24, 1.0 op_sel:[1,1,0]
	v_cvt_scalef32_pk_f16_fp4 v36, v25, 1.0
	v_cvt_scalef32_pk_f16_fp4 v37, v25, 1.0 op_sel:[1,0,0]
	v_cvt_scalef32_pk_f16_fp4 v38, v25, 1.0 op_sel:[0,1,0]
	v_cvt_scalef32_pk_f16_fp4 v39, v25, 1.0 op_sel:[1,1,0]
	v_cvt_scalef32_pk_f16_fp4 v40, v26, 1.0
	v_cvt_scalef32_pk_f16_fp4 v41, v26, 1.0 op_sel:[1,0,0]
	v_cvt_scalef32_pk_f16_fp4 v42, v26, 1.0 op_sel:[0,1,0]
	v_cvt_scalef32_pk_f16_fp4 v43, v26, 1.0 op_sel:[1,1,0]
	v_cvt_scalef32_pk_f16_fp4 v44, v27, 1.0
	v_cvt_scalef32_pk_f16_fp4 v45, v27, 1.0 op_sel:[1,0,0]
	v_cvt_scalef32_pk_f16_fp4 v46, v27, 1.0 op_sel:[0,1,0]
	v_cvt_scalef32_pk_f16_fp4 v47, v27, 1.0 op_sel:[1,1,0]
	buffer_load_dwordx4 v[20:23], v115, s[12:15], s4 offen
	v_pk_fma_f16 v74, v32, s0, v74
	v_pk_fma_f16 v73, v33, s0, v73
	v_pk_fma_f16 v71, v34, s0, v71
	v_pk_fma_f16 v70, v35, s0, v70
	v_pk_fma_f16 v69, v36, s0, v69
	v_pk_fma_f16 v68, v37, s0, v68
	v_pk_fma_f16 v63, v38, s0, v63
	v_pk_fma_f16 v62, v39, s0, v62
	v_pk_fma_f16 v61, v40, s0, v61
	v_pk_fma_f16 v60, v41, s0, v60
	v_pk_fma_f16 v59, v42, s0, v59
	v_pk_fma_f16 v58, v43, s0, v58
	v_pk_fma_f16 v57, v44, s0, v57
	v_pk_fma_f16 v56, v45, s0, v56
	v_pk_fma_f16 v75, v46, s0, v75
	v_pk_fma_f16 v72, v47, s0, v72
	s_waitcnt vmcnt(6)
	v_readlane_b32 s4, v50, 17
	v_readlane_b32 s0, v55, 15
	v_cvt_scalef32_pk_f16_fp4 v32, v28, 1.0
	v_cvt_scalef32_pk_f16_fp4 v33, v28, 1.0 op_sel:[1,0,0]
	v_cvt_scalef32_pk_f16_fp4 v34, v28, 1.0 op_sel:[0,1,0]
	v_cvt_scalef32_pk_f16_fp4 v35, v28, 1.0 op_sel:[1,1,0]
	v_cvt_scalef32_pk_f16_fp4 v36, v29, 1.0
	v_cvt_scalef32_pk_f16_fp4 v37, v29, 1.0 op_sel:[1,0,0]
	v_cvt_scalef32_pk_f16_fp4 v38, v29, 1.0 op_sel:[0,1,0]
	v_cvt_scalef32_pk_f16_fp4 v39, v29, 1.0 op_sel:[1,1,0]
	v_cvt_scalef32_pk_f16_fp4 v40, v30, 1.0
	v_cvt_scalef32_pk_f16_fp4 v41, v30, 1.0 op_sel:[1,0,0]
	v_cvt_scalef32_pk_f16_fp4 v42, v30, 1.0 op_sel:[0,1,0]
	v_cvt_scalef32_pk_f16_fp4 v43, v30, 1.0 op_sel:[1,1,0]
	v_cvt_scalef32_pk_f16_fp4 v44, v31, 1.0
	v_cvt_scalef32_pk_f16_fp4 v45, v31, 1.0 op_sel:[1,0,0]
	v_cvt_scalef32_pk_f16_fp4 v46, v31, 1.0 op_sel:[0,1,0]
	v_cvt_scalef32_pk_f16_fp4 v47, v31, 1.0 op_sel:[1,1,0]
	buffer_load_dwordx4 v[24:27], v115, s[12:15], s4 offen
	v_pk_fma_f16 v162, v32, s0, v162
	v_pk_fma_f16 v161, v33, s0, v161
	v_pk_fma_f16 v160, v34, s0, v160
	v_pk_fma_f16 v159, v35, s0, v159
	v_pk_fma_f16 v158, v36, s0, v158
	v_pk_fma_f16 v157, v37, s0, v157
	v_pk_fma_f16 v156, v38, s0, v156
	v_pk_fma_f16 v147, v39, s0, v147
	v_pk_fma_f16 v146, v40, s0, v146
	v_pk_fma_f16 v145, v41, s0, v145
	v_pk_fma_f16 v144, v42, s0, v144
	v_pk_fma_f16 v143, v43, s0, v143
	v_pk_fma_f16 v142, v44, s0, v142
	v_pk_fma_f16 v141, v45, s0, v141
	v_pk_fma_f16 v149, v46, s0, v149
	v_pk_fma_f16 v148, v47, s0, v148
	v_add_u32_e32 v111, 64, v111
	s_add_i32 s11, s11, 1
	s_cmp_eq_u32 s11, 8
	s_cbranch_scc0 .Lmy_lblk
	s_waitcnt vmcnt(0) lgkmcnt(0)
	s_movk_i32 s12, 0x1000
	s_lshr_b32 s1, s26, 14
	s_cmp_lt_u32 s1, 4
	s_cbranch_scc1 .Lmy_ap_ln2
	s_cmp_lg_u32 s100, 0
	s_cbranch_scc1 .Lmy_ap_ln2
	s_lshl_b32 s1, s22, 11
	s_add_u32 s24, s72, 0xab00000
	s_addc_u32 s25, s73, 0
	s_add_u32 s24, s24, s1
	s_addc_u32 s25, s25, 0
	v_lshlrev_b32_e32 v236, 2, v78
	v_add_u32_e32 v237, 0x1000, v236
	v_add_u32_e32 v238, 0x2000, v236
	v_add_u32_e32 v239, 0x3000, v236
	global_store_dword v236, v139, s[24:25] offset:0
	global_store_dword v236, v138, s[24:25] offset:256
	global_store_dword v236, v136, s[24:25] offset:512
	global_store_dword v236, v135, s[24:25] offset:768
	global_store_dword v236, v134, s[24:25] offset:1024
	global_store_dword v236, v133, s[24:25] offset:1280
	global_store_dword v236, v132, s[24:25] offset:1536
	global_store_dword v236, v131, s[24:25] offset:1792
	global_store_dword v236, v130, s[24:25] offset:2048
	global_store_dword v236, v129, s[24:25] offset:2304
	global_store_dword v236, v128, s[24:25] offset:2560
	global_store_dword v236, v127, s[24:25] offset:2816
	global_store_dword v236, v126, s[24:25] offset:3072
	global_store_dword v236, v114, s[24:25] offset:3328
	global_store_dword v236, v140, s[24:25] offset:3584
	global_store_dword v236, v137, s[24:25] offset:3840
	global_store_dword v237, v124, s[24:25] offset:0
	global_store_dword v237, v123, s[24:25] offset:256
	global_store_dword v237, v121, s[24:25] offset:512
	global_store_dword v237, v120, s[24:25] offset:768
	global_store_dword v237, v119, s[24:25] offset:1024
	global_store_dword v237, v118, s[24:25] offset:1280
	global_store_dword v237, v117, s[24:25] offset:1536
	global_store_dword v237, v116, s[24:25] offset:1792
	global_store_dword v237, v113, s[24:25] offset:2048
	global_store_dword v237, v112, s[24:25] offset:2304
	global_store_dword v237, v67, s[24:25] offset:2560
	global_store_dword v237, v66, s[24:25] offset:2816
	global_store_dword v237, v65, s[24:25] offset:3072
	global_store_dword v237, v64, s[24:25] offset:3328
	global_store_dword v237, v125, s[24:25] offset:3584
	global_store_dword v237, v122, s[24:25] offset:3840
	global_store_dword v238, v74, s[24:25] offset:0
	global_store_dword v238, v73, s[24:25] offset:256
	global_store_dword v238, v71, s[24:25] offset:512
	global_store_dword v238, v70, s[24:25] offset:768
	global_store_dword v238, v69, s[24:25] offset:1024
	global_store_dword v238, v68, s[24:25] offset:1280
	global_store_dword v238, v63, s[24:25] offset:1536
	global_store_dword v238, v62, s[24:25] offset:1792
	global_store_dword v238, v61, s[24:25] offset:2048
	global_store_dword v238, v60, s[24:25] offset:2304
	global_store_dword v238, v59, s[24:25] offset:2560
	global_store_dword v238, v58, s[24:25] offset:2816
	global_store_dword v238, v57, s[24:25] offset:3072
	global_store_dword v238, v56, s[24:25] offset:3328
	global_store_dword v238, v75, s[24:25] offset:3584
	global_store_dword v238, v72, s[24:25] offset:3840
	global_store_dword v239, v162, s[24:25] offset:0
	global_store_dword v239, v161, s[24:25] offset:256
	global_store_dword v239, v160, s[24:25] offset:512
	global_store_dword v239, v159, s[24:25] offset:768
	global_store_dword v239, v158, s[24:25] offset:1024
	global_store_dword v239, v157, s[24:25] offset:1280
	global_store_dword v239, v156, s[24:25] offset:1536
	global_store_dword v239, v147, s[24:25] offset:1792
	global_store_dword v239, v146, s[24:25] offset:2048
	global_store_dword v239, v145, s[24:25] offset:2304
	global_store_dword v239, v144, s[24:25] offset:2560
	global_store_dword v239, v143, s[24:25] offset:2816
	global_store_dword v239, v142, s[24:25] offset:3072
	global_store_dword v239, v141, s[24:25] offset:3328
	global_store_dword v239, v149, s[24:25] offset:3584
	global_store_dword v239, v148, s[24:25] offset:3840
	s_mov_b32 s100, 1
	s_mov_b32 s10, 1
	s_mov_b64 s[0:1], 0
	s_branch .LBB0_1012
.Lmy_ap_ln2:
	v_lshlrev_b32_e32 v236, 6, v78
	v_add_u32_e32 v237, 0x1000, v236
	global_load_dwordx4 v[172:175], v236, s[16:17] offset:0
	global_load_dwordx4 v[204:207], v236, s[18:19] offset:0
	global_load_dwordx4 v[176:179], v236, s[16:17] offset:16
	global_load_dwordx4 v[208:211], v236, s[18:19] offset:16
	global_load_dwordx4 v[180:183], v236, s[16:17] offset:32
	global_load_dwordx4 v[212:215], v236, s[18:19] offset:32
	global_load_dwordx4 v[184:187], v236, s[16:17] offset:48
	global_load_dwordx4 v[216:219], v236, s[18:19] offset:48
	global_load_dwordx4 v[188:191], v237, s[16:17] offset:0
	global_load_dwordx4 v[220:223], v237, s[18:19] offset:0
	global_load_dwordx4 v[192:195], v237, s[16:17] offset:16
	global_load_dwordx4 v[224:227], v237, s[18:19] offset:16
	global_load_dwordx4 v[196:199], v237, s[16:17] offset:32
	global_load_dwordx4 v[228:231], v237, s[18:19] offset:32
	global_load_dwordx4 v[200:203], v237, s[16:17] offset:48
	global_load_dwordx4 v[232:235], v237, s[18:19] offset:48
	s_lshl_b32 s0, s10, 2
	s_waitcnt vmcnt(11)
	v_mov_b32_e32 v0, v78
	s_or_b32 s10, s0, s22
	s_waitcnt vmcnt(0) lgkmcnt(0)
	s_ashr_i32 s11, s10, 31
	s_waitcnt vmcnt(2)
	v_lshlrev_b32_e32 v42, 4, v0
	v_ashrrev_i32_e32 v43, 31, v42
	s_lshl_b64 s[0:1], s[10:11], 11
	v_lshl_add_u64 v[0:1], s[0:1], 0, v[42:43]
	v_lshlrev_b64 v[0:1], 1, v[0:1]
	v_lshl_add_u64 v[28:29], s[70:71], 0, v[0:1]
	global_load_dwordx4 v[4:7], v[28:29], off offset:2064
	v_lshl_add_u64 v[24:25], s[2:3], 0, v[0:1]
	global_load_dwordx4 v[0:3], v[24:25], off offset:2064
	global_load_dwordx4 v[8:11], v[28:29], off
	global_load_dwordx4 v[12:15], v[24:25], off
	global_load_dwordx4 v[16:19], v[28:29], off offset:16
	global_load_dwordx4 v[20:23], v[24:25], off offset:16
	s_nop 0
	global_load_dwordx4 v[24:27], v[24:25], off offset:2048
	s_nop 0
	global_load_dwordx4 v[28:31], v[28:29], off offset:2048
	v_cvt_f32_f16_sdwa v35, v139 dst_sel:DWORD dst_unused:UNUSED_PAD src0_sel:WORD_1
	v_cvt_f32_f16_e32 v34, v139
	v_cvt_f32_f16_sdwa v41, v136 dst_sel:DWORD dst_unused:UNUSED_PAD src0_sel:WORD_1
	v_cvt_f32_f16_e32 v40, v136
	v_cvt_f32_f16_sdwa v37, v138 dst_sel:DWORD dst_unused:UNUSED_PAD src0_sel:WORD_1
	v_cvt_f32_f16_e32 v36, v138
	s_waitcnt vmcnt(9)
	v_cvt_f32_f16_sdwa v45, v135 dst_sel:DWORD dst_unused:UNUSED_PAD src0_sel:WORD_1
	v_cvt_f32_f16_e32 v44, v135
	v_cvt_f32_f16_sdwa v47, v134 dst_sel:DWORD dst_unused:UNUSED_PAD src0_sel:WORD_1
	v_cvt_f32_f16_e32 v46, v134
	v_cvt_f32_f16_sdwa v49, v133 dst_sel:DWORD dst_unused:UNUSED_PAD src0_sel:WORD_1
	v_cvt_f32_f16_e32 v48, v133
	v_cvt_f32_f16_sdwa v51, v132 dst_sel:DWORD dst_unused:UNUSED_PAD src0_sel:WORD_1
	v_cvt_f32_f16_e32 v50, v132
	v_cvt_f32_f16_sdwa v39, v137 dst_sel:DWORD dst_unused:UNUSED_PAD src0_sel:WORD_1
	v_cvt_f32_f16_e32 v38, v137
	v_cvt_f32_f16_sdwa v33, v140 dst_sel:DWORD dst_unused:UNUSED_PAD src0_sel:WORD_1
	v_cvt_f32_f16_e32 v32, v140
	s_lshl_b64 s[14:15], s[10:11], 13
	s_waitcnt vmcnt(6)
	v_and_b32_e32 v55, 0xffff0000, v2
	v_lshlrev_b32_e32 v54, 16, v2
	v_and_b32_e32 v53, 0xffff0000, v6
	v_lshlrev_b32_e32 v52, 16, v6
	s_waitcnt vmcnt(5)
	v_lshlrev_b32_e32 v104, 16, v8
	v_and_b32_e32 v105, 0xffff0000, v8
	s_waitcnt vmcnt(4)
	v_lshlrev_b32_e32 v106, 16, v12
	v_and_b32_e32 v107, 0xffff0000, v12
	v_and_b32_e32 v109, 0xffff0000, v7
	v_lshlrev_b32_e32 v108, 16, v7
	v_and_b32_e32 v7, 0xffff0000, v3
	v_lshlrev_b32_e32 v6, 16, v3
	v_lshlrev_b32_e32 v2, 16, v10
	v_and_b32_e32 v3, 0xffff0000, v10
	v_lshlrev_b32_e32 v110, 16, v14
	v_and_b32_e32 v111, 0xffff0000, v14
	v_lshlrev_b32_e32 v10, 16, v11
	v_and_b32_e32 v11, 0xffff0000, v11
	v_lshlrev_b32_e32 v14, 16, v15
	v_and_b32_e32 v15, 0xffff0000, v15
	s_waitcnt vmcnt(3)
	v_lshlrev_b32_e32 v132, 16, v16
	v_and_b32_e32 v133, 0xffff0000, v16
	s_waitcnt vmcnt(2)
	v_lshlrev_b32_e32 v134, 16, v20
	v_and_b32_e32 v135, 0xffff0000, v20
	v_lshlrev_b32_e32 v16, 16, v17
	v_and_b32_e32 v17, 0xffff0000, v17
	v_lshlrev_b32_e32 v20, 16, v21
	v_and_b32_e32 v21, 0xffff0000, v21
	v_pk_fma_f32 v[52:53], v[52:53], s[6:7], v[54:55] op_sel_hi:[1,0,1]
	v_pk_fma_f32 v[54:55], v[104:105], s[6:7], v[106:107] op_sel_hi:[1,0,1]
	v_lshlrev_b32_e32 v8, 16, v9
	v_and_b32_e32 v9, 0xffff0000, v9
	v_lshlrev_b32_e32 v12, 16, v13
	v_and_b32_e32 v13, 0xffff0000, v13
	v_pk_fma_f32 v[2:3], v[2:3], s[6:7], v[110:111] op_sel_hi:[1,0,1]
	v_pk_fma_f32 v[10:11], v[10:11], s[6:7], v[14:15] op_sel_hi:[1,0,1]
	v_pk_fma_f32 v[14:15], v[16:17], s[6:7], v[20:21] op_sel_hi:[1,0,1]
	v_pk_add_f32 v[20:21], v[54:55], v[34:35]
	v_pk_fma_f32 v[8:9], v[8:9], s[6:7], v[12:13] op_sel_hi:[1,0,1]
	v_pk_add_f32 v[40:41], v[2:3], v[40:41]
	v_add_f32_e32 v2, 0, v20
	v_pk_add_f32 v[8:9], v[8:9], v[36:37]
	v_add_f32_e32 v2, v21, v2
	v_add_f32_e32 v2, v8, v2
	v_add_f32_e32 v2, v9, v2
	v_add_f32_e32 v2, v40, v2
	v_pk_add_f32 v[10:11], v[10:11], v[44:45]
	v_add_f32_e32 v2, v41, v2
	v_pk_fma_f32 v[12:13], v[132:133], s[6:7], v[134:135] op_sel_hi:[1,0,1]
	v_add_f32_e32 v2, v10, v2
	v_pk_add_f32 v[12:13], v[12:13], v[46:47]
	v_add_f32_e32 v2, v11, v2
	v_add_f32_e32 v2, v12, v2
	v_pk_add_f32 v[14:15], v[14:15], v[48:49]
	v_add_f32_e32 v2, v13, v2
	v_lshlrev_b32_e32 v136, 16, v18
	v_and_b32_e32 v137, 0xffff0000, v18
	v_lshlrev_b32_e32 v138, 16, v22
	v_pk_fma_f32 v[6:7], v[108:109], s[6:7], v[6:7] op_sel_hi:[1,0,1]
	v_add_f32_e32 v2, v14, v2
	v_and_b32_e32 v139, 0xffff0000, v22
	v_pk_add_f32 v[38:39], v[6:7], v[38:39]
	v_add_f32_e32 v6, v15, v2
	v_pk_fma_f32 v[2:3], v[136:137], s[6:7], v[138:139] op_sel_hi:[1,0,1]
	v_and_b32_e32 v7, 0xffff0000, v19
	v_pk_add_f32 v[44:45], v[2:3], v[50:51]
	v_cvt_f32_f16_sdwa v3, v131 dst_sel:DWORD dst_unused:UNUSED_PAD src0_sel:WORD_1
	v_add_f32_e32 v2, v44, v6
	v_add_f32_e32 v22, v45, v2
	v_cvt_f32_f16_e32 v2, v131
	v_lshlrev_b32_e32 v6, 16, v19
	v_lshlrev_b32_e32 v18, 16, v23
	v_and_b32_e32 v19, 0xffff0000, v23
	v_pk_fma_f32 v[6:7], v[6:7], s[6:7], v[18:19] op_sel_hi:[1,0,1]
	v_pk_add_f32 v[16:17], v[52:53], v[32:33]
	v_pk_add_f32 v[18:19], v[6:7], v[2:3]
	v_cvt_f32_f16_sdwa v3, v130 dst_sel:DWORD dst_unused:UNUSED_PAD src0_sel:WORD_1
	v_add_f32_e32 v2, v18, v22
	v_add_f32_e32 v32, v19, v2
	v_cvt_f32_f16_e32 v2, v130
	s_waitcnt vmcnt(0)
	v_lshlrev_b32_e32 v6, 16, v28
	v_and_b32_e32 v7, 0xffff0000, v28
	v_lshlrev_b32_e32 v22, 16, v24
	v_and_b32_e32 v23, 0xffff0000, v24
	v_pk_fma_f32 v[6:7], v[6:7], s[6:7], v[22:23] op_sel_hi:[1,0,1]
	v_lshlrev_b32_e32 v24, 16, v25
	v_pk_add_f32 v[22:23], v[6:7], v[2:3]
	v_cvt_f32_f16_sdwa v3, v129 dst_sel:DWORD dst_unused:UNUSED_PAD src0_sel:WORD_1
	v_add_f32_e32 v2, v22, v32
	v_add_f32_e32 v28, v23, v2
	v_cvt_f32_f16_e32 v2, v129
	v_lshlrev_b32_e32 v6, 16, v29
	v_and_b32_e32 v7, 0xffff0000, v29
	v_and_b32_e32 v25, 0xffff0000, v25
	v_pk_fma_f32 v[6:7], v[6:7], s[6:7], v[24:25] op_sel_hi:[1,0,1]
	v_and_b32_e32 v29, 0xffff0000, v26
	v_pk_add_f32 v[24:25], v[6:7], v[2:3]
	v_cvt_f32_f16_sdwa v3, v128 dst_sel:DWORD dst_unused:UNUSED_PAD src0_sel:WORD_1
	v_add_f32_e32 v2, v24, v28
	v_add_f32_e32 v32, v25, v2
	v_cvt_f32_f16_e32 v2, v128
	v_lshlrev_b32_e32 v6, 16, v30
	v_and_b32_e32 v7, 0xffff0000, v30
	v_lshlrev_b32_e32 v28, 16, v26
	v_pk_fma_f32 v[6:7], v[6:7], s[6:7], v[28:29] op_sel_hi:[1,0,1]
	v_lshlrev_b32_e32 v26, 16, v27
	v_pk_add_f32 v[28:29], v[6:7], v[2:3]
	v_cvt_f32_f16_sdwa v3, v127 dst_sel:DWORD dst_unused:UNUSED_PAD src0_sel:WORD_1
	v_add_f32_e32 v2, v28, v32
	v_add_f32_e32 v30, v29, v2
	v_cvt_f32_f16_e32 v2, v127
	v_lshlrev_b32_e32 v6, 16, v31
	v_and_b32_e32 v7, 0xffff0000, v31
	v_and_b32_e32 v27, 0xffff0000, v27
	v_pk_fma_f32 v[6:7], v[6:7], s[6:7], v[26:27] op_sel_hi:[1,0,1]
	v_and_b32_e32 v31, 0xffff0000, v0
	v_pk_add_f32 v[26:27], v[6:7], v[2:3]
	v_cvt_f32_f16_sdwa v3, v126 dst_sel:DWORD dst_unused:UNUSED_PAD src0_sel:WORD_1
	v_add_f32_e32 v2, v26, v30
	v_add_f32_e32 v32, v27, v2
	v_cvt_f32_f16_e32 v2, v126
	v_lshlrev_b32_e32 v6, 16, v4
	v_and_b32_e32 v7, 0xffff0000, v4
	v_lshlrev_b32_e32 v30, 16, v0
	v_pk_fma_f32 v[6:7], v[6:7], s[6:7], v[30:31] op_sel_hi:[1,0,1]
	v_lshlrev_b32_e32 v4, 16, v5
	v_pk_add_f32 v[30:31], v[6:7], v[2:3]
	v_cvt_f32_f16_sdwa v3, v114 dst_sel:DWORD dst_unused:UNUSED_PAD src0_sel:WORD_1
	v_cvt_f32_f16_e32 v2, v114
	v_add_f32_e32 v0, v30, v32
	v_add_f32_e32 v6, v31, v0
	v_and_b32_e32 v5, 0xffff0000, v5
	v_lshlrev_b32_e32 v0, 16, v1
	v_and_b32_e32 v1, 0xffff0000, v1
	v_pk_fma_f32 v[0:1], v[4:5], s[6:7], v[0:1] op_sel_hi:[1,0,1]
	v_lshlrev_b64 v[36:37], 2, v[42:43]
	v_pk_add_f32 v[46:47], v[0:1], v[2:3]
	v_lshl_add_u64 v[32:33], s[16:17], 0, v[36:37]
	v_add_f32_e32 v0, v46, v6
	v_add_f32_e32 v0, v47, v0
	v_add_f32_e32 v0, v16, v0
	v_add_f32_e32 v0, v17, v0
	v_add_f32_e32 v0, v38, v0
	v_add_f32_e32 v0, v39, v0
	ds_bpermute_b32 v1, v79, v0
	v_lshl_add_u64 v[34:35], s[18:19], 0, v[36:37]
	s_waitcnt lgkmcnt(0)
	v_add_f32_e32 v0, v0, v1
	ds_bpermute_b32 v1, v80, v0
	s_waitcnt lgkmcnt(0)
	v_add_f32_e32 v0, v0, v1
	ds_bpermute_b32 v1, v81, v0
	s_waitcnt lgkmcnt(0)
	v_add_f32_e32 v0, v0, v1
	ds_bpermute_b32 v1, v82, v0
	s_waitcnt lgkmcnt(0)
	v_add_f32_e32 v0, v0, v1
	ds_bpermute_b32 v1, v83, v0
	s_waitcnt lgkmcnt(0)
	v_add_f32_e32 v48, v0, v1
	ds_bpermute_b32 v49, v84, v48
	s_waitcnt lgkmcnt(0)
	v_add_f32_e32 v48, v48, v49
	v_mul_f32_e32 v48, 0x3a000000, v48
	v_pk_add_f32 v[20:21], v[20:21], v[48:49] op_sel_hi:[1,0] neg_lo:[0,1] neg_hi:[0,1]
	v_pk_add_f32 v[8:9], v[8:9], v[48:49] op_sel_hi:[1,0] neg_lo:[0,1] neg_hi:[0,1]
	v_pk_mul_f32 v[50:51], v[20:21], v[20:21]
	v_pk_mul_f32 v[52:53], v[8:9], v[8:9]
	v_add_f32_e32 v50, v50, v51
	v_pk_add_f32 v[40:41], v[40:41], v[48:49] op_sel_hi:[1,0] neg_lo:[0,1] neg_hi:[0,1]
	v_add_f32_e32 v50, v52, v50
	v_pk_mul_f32 v[54:55], v[40:41], v[40:41]
	v_add_f32_e32 v50, v53, v50
	v_pk_add_f32 v[10:11], v[10:11], v[48:49] op_sel_hi:[1,0] neg_lo:[0,1] neg_hi:[0,1]
	v_add_f32_e32 v50, v54, v50
	v_pk_mul_f32 v[104:105], v[10:11], v[10:11]
	v_add_f32_e32 v50, v55, v50
	v_pk_add_f32 v[12:13], v[12:13], v[48:49] op_sel_hi:[1,0] neg_lo:[0,1] neg_hi:[0,1]
	v_add_f32_e32 v50, v104, v50
	v_pk_mul_f32 v[106:107], v[12:13], v[12:13]
	v_add_f32_e32 v50, v105, v50
	v_pk_add_f32 v[14:15], v[14:15], v[48:49] op_sel_hi:[1,0] neg_lo:[0,1] neg_hi:[0,1]
	v_add_f32_e32 v50, v106, v50
	v_pk_mul_f32 v[108:109], v[14:15], v[14:15]
	v_add_f32_e32 v50, v107, v50
	v_pk_add_f32 v[44:45], v[44:45], v[48:49] op_sel_hi:[1,0] neg_lo:[0,1] neg_hi:[0,1]
	v_add_f32_e32 v50, v108, v50
	v_pk_mul_f32 v[110:111], v[44:45], v[44:45]
	v_add_f32_e32 v50, v109, v50
	v_pk_add_f32 v[18:19], v[18:19], v[48:49] op_sel_hi:[1,0] neg_lo:[0,1] neg_hi:[0,1]
	v_add_f32_e32 v50, v110, v50
	v_pk_mul_f32 v[114:115], v[18:19], v[18:19]
	v_add_f32_e32 v50, v111, v50
	v_pk_add_f32 v[22:23], v[22:23], v[48:49] op_sel_hi:[1,0] neg_lo:[0,1] neg_hi:[0,1]
	v_add_f32_e32 v50, v114, v50
	v_pk_mul_f32 v[126:127], v[22:23], v[22:23]
	v_add_f32_e32 v50, v115, v50
	v_pk_add_f32 v[24:25], v[24:25], v[48:49] op_sel_hi:[1,0] neg_lo:[0,1] neg_hi:[0,1]
	v_add_f32_e32 v50, v126, v50
	v_pk_mul_f32 v[128:129], v[24:25], v[24:25]
	v_add_f32_e32 v50, v127, v50
	v_pk_add_f32 v[28:29], v[28:29], v[48:49] op_sel_hi:[1,0] neg_lo:[0,1] neg_hi:[0,1]
	v_add_f32_e32 v50, v128, v50
	v_pk_mul_f32 v[130:131], v[28:29], v[28:29]
	v_add_f32_e32 v50, v129, v50
	v_pk_add_f32 v[26:27], v[26:27], v[48:49] op_sel_hi:[1,0] neg_lo:[0,1] neg_hi:[0,1]
	v_add_f32_e32 v50, v130, v50
	v_pk_mul_f32 v[132:133], v[26:27], v[26:27]
	v_add_f32_e32 v50, v131, v50
	v_pk_add_f32 v[30:31], v[30:31], v[48:49] op_sel_hi:[1,0] neg_lo:[0,1] neg_hi:[0,1]
	v_add_f32_e32 v50, v132, v50
	v_pk_mul_f32 v[134:135], v[30:31], v[30:31]
	v_add_f32_e32 v50, v133, v50
	v_pk_add_f32 v[46:47], v[46:47], v[48:49] op_sel_hi:[1,0] neg_lo:[0,1] neg_hi:[0,1]
	v_add_f32_e32 v50, v134, v50
	v_pk_mul_f32 v[136:137], v[46:47], v[46:47]
	v_add_f32_e32 v50, v135, v50
	v_pk_add_f32 v[16:17], v[16:17], v[48:49] op_sel_hi:[1,0] neg_lo:[0,1] neg_hi:[0,1]
	v_add_f32_e32 v50, v136, v50
	v_pk_add_f32 v[138:139], v[38:39], v[48:49] op_sel_hi:[1,0] neg_lo:[0,1] neg_hi:[0,1]
	v_pk_mul_f32 v[48:49], v[16:17], v[16:17]
	v_add_f32_e32 v50, v137, v50
	v_add_f32_e32 v48, v48, v50
	v_pk_mul_f32 v[38:39], v[138:139], v[138:139]
	v_add_f32_e32 v48, v49, v48
	v_add_f32_e32 v38, v38, v48
	v_add_f32_e32 v38, v39, v38
	ds_bpermute_b32 v39, v79, v38
	v_cvt_f32_f16_sdwa v105, v119 dst_sel:DWORD dst_unused:UNUSED_PAD src0_sel:WORD_1
	v_cvt_f32_f16_e32 v104, v119
	v_cvt_f32_f16_sdwa v107, v118 dst_sel:DWORD dst_unused:UNUSED_PAD src0_sel:WORD_1
	v_cvt_f32_f16_e32 v106, v118
	s_waitcnt lgkmcnt(0)
	v_add_f32_e32 v38, v38, v39
	ds_bpermute_b32 v39, v80, v38
	v_cvt_f32_f16_sdwa v119, v65 dst_sel:DWORD dst_unused:UNUSED_PAD src0_sel:WORD_1
	v_cvt_f32_f16_e32 v118, v65
	v_cvt_f32_f16_sdwa v65, v64 dst_sel:DWORD dst_unused:UNUSED_PAD src0_sel:WORD_1
	v_cvt_f32_f16_e32 v64, v64
	s_waitcnt lgkmcnt(0)
	v_add_f32_e32 v38, v38, v39
	ds_bpermute_b32 v39, v81, v38
	v_cvt_f32_f16_sdwa v55, v120 dst_sel:DWORD dst_unused:UNUSED_PAD src0_sel:WORD_1
	v_cvt_f32_f16_e32 v54, v120
	v_cvt_f32_f16_sdwa v109, v117 dst_sel:DWORD dst_unused:UNUSED_PAD src0_sel:WORD_1
	v_cvt_f32_f16_e32 v108, v117
	s_waitcnt lgkmcnt(0)
	v_add_f32_e32 v38, v38, v39
	ds_bpermute_b32 v39, v82, v38
	v_cvt_f32_f16_sdwa v111, v116 dst_sel:DWORD dst_unused:UNUSED_PAD src0_sel:WORD_1
	v_cvt_f32_f16_e32 v110, v116
	v_cvt_f32_f16_sdwa v115, v113 dst_sel:DWORD dst_unused:UNUSED_PAD src0_sel:WORD_1
	v_cvt_f32_f16_e32 v114, v113
	s_waitcnt lgkmcnt(0)
	v_add_f32_e32 v38, v38, v39
	ds_bpermute_b32 v39, v83, v38
	v_cvt_f32_f16_sdwa v113, v112 dst_sel:DWORD dst_unused:UNUSED_PAD src0_sel:WORD_1
	v_cvt_f32_f16_e32 v112, v112
	v_cvt_f32_f16_sdwa v117, v67 dst_sel:DWORD dst_unused:UNUSED_PAD src0_sel:WORD_1
	v_cvt_f32_f16_e32 v116, v67
	s_waitcnt lgkmcnt(0)
	v_add_f32_e32 v38, v38, v39
	ds_bpermute_b32 v39, v84, v38
	v_cvt_f32_f16_sdwa v67, v66 dst_sel:DWORD dst_unused:UNUSED_PAD src0_sel:WORD_1
	v_cvt_f32_f16_e32 v66, v66
	s_waitcnt lgkmcnt(0)
	v_add_f32_e32 v38, v38, v39
	v_fmamk_f32 v38, v38, 0x3a000000, v101
	v_mul_f32_e32 v39, 0x4f800000, v38
	v_cmp_gt_f32_e32 vcc, s7, v38
	s_nop 1
	v_cndmask_b32_e32 v38, v38, v39, vcc
	v_sqrt_f32_e32 v39, v38
	s_nop 0
	v_add_u32_e32 v48, -1, v39
	v_fma_f32 v49, -v48, v39, v38
	v_cmp_ge_f32_e64 s[0:1], 0, v49
	v_add_u32_e32 v49, 1, v39
	s_nop 0
	v_cndmask_b32_e64 v48, v39, v48, s[0:1]
	v_fma_f32 v39, -v49, v39, v38
	v_cmp_lt_f32_e64 s[0:1], 0, v39
	s_nop 1
	v_cndmask_b32_e64 v39, v48, v49, s[0:1]
	v_mul_f32_e32 v48, 0x37800000, v39
	v_cndmask_b32_e32 v39, v39, v48, vcc
	v_cmp_class_f32_e32 vcc, v38, v102
	s_nop 1
	v_cndmask_b32_e32 v38, v39, v38, vcc
	v_div_scale_f32 v39, s[0:1], v38, v38, 1.0
	v_rcp_f32_e32 v50, v39
	s_add_u32 s0, s20, s14
	s_addc_u32 s1, s21, s15
	v_lshl_add_u64 v[48:49], s[0:1], 0, v[36:37]
	v_fma_f32 v51, -v39, v50, 1.0
	v_fmac_f32_e32 v50, v51, v50
	v_div_scale_f32 v51, vcc, 1.0, v38, 1.0
	v_mul_f32_e32 v52, v51, v50
	v_fma_f32 v53, -v39, v52, v51
	v_fmac_f32_e32 v52, v53, v50
	v_fma_f32 v39, -v39, v52, v51
	v_div_fmas_f32 v39, v39, v50, v52
	v_div_fixup_f32 v50, v39, v38, 1.0
	v_pk_mul_f32 v[20:21], v[20:21], v[50:51] op_sel_hi:[1,0]
	v_pk_mul_f32 v[8:9], v[8:9], v[50:51] op_sel_hi:[1,0]
	v_pk_fma_f32 v[0:1], v[172:173], v[20:21], v[204:205]
	v_pk_fma_f32 v[2:3], v[174:175], v[8:9], v[206:207]
	global_store_dwordx4 v[48:49], v[0:3], off
	s_nop 1
	s_nop 0
	v_pk_mul_f32 v[8:9], v[10:11], v[50:51] op_sel_hi:[1,0]
	v_pk_mul_f32 v[10:11], v[40:41], v[50:51] op_sel_hi:[1,0]
	v_add_co_u32_e32 v38, vcc, s12, v32
	s_or_b32 s0, s10, 1
	s_nop 0
	v_addc_co_u32_e32 v39, vcc, 0, v33, vcc
	v_add_co_u32_e32 v40, vcc, s12, v34
	s_ashr_i32 s1, s0, 31
	s_nop 0
	v_addc_co_u32_e32 v41, vcc, 0, v35, vcc
	s_lshl_b64 s[14:15], s[0:1], 11
	v_cvt_f32_f16_sdwa v53, v121 dst_sel:DWORD dst_unused:UNUSED_PAD src0_sel:WORD_1
	v_cvt_f32_f16_e32 v52, v121
	s_lshl_b64 s[0:1], s[0:1], 13
	v_pk_fma_f32 v[0:1], v[176:177], v[10:11], v[208:209]
	v_pk_fma_f32 v[2:3], v[178:179], v[8:9], v[210:211]
	global_store_dwordx4 v[48:49], v[0:3], off offset:16
	s_nop 1
	s_nop 0
	v_pk_mul_f32 v[8:9], v[14:15], v[50:51] op_sel_hi:[1,0]
	v_pk_mul_f32 v[10:11], v[12:13], v[50:51] op_sel_hi:[1,0]
	v_pk_mul_f32 v[12:13], v[22:23], v[50:51] op_sel_hi:[1,0]
	v_pk_mul_f32 v[14:15], v[16:17], v[50:51] op_sel_hi:[1,0]
	v_pk_fma_f32 v[0:1], v[180:181], v[10:11], v[212:213]
	v_pk_fma_f32 v[2:3], v[182:183], v[8:9], v[214:215]
	global_store_dwordx4 v[48:49], v[0:3], off offset:32
	s_nop 1
	s_nop 0
	v_pk_mul_f32 v[8:9], v[18:19], v[50:51] op_sel_hi:[1,0]
	v_pk_mul_f32 v[10:11], v[44:45], v[50:51] op_sel_hi:[1,0]
	v_pk_fma_f32 v[2:3], v[186:187], v[8:9], v[218:219]
	v_pk_fma_f32 v[0:1], v[184:185], v[10:11], v[216:217]
	global_store_dwordx4 v[48:49], v[0:3], off offset:48
	s_nop 1
	s_nop 0
	v_add_co_u32_e32 v8, vcc, s12, v48
	v_pk_mul_f32 v[10:11], v[24:25], v[50:51] op_sel_hi:[1,0]
	s_nop 0
	v_addc_co_u32_e32 v9, vcc, 0, v49, vcc
	v_cvt_f32_f16_sdwa v49, v123 dst_sel:DWORD dst_unused:UNUSED_PAD src0_sel:WORD_1
	v_cvt_f32_f16_e32 v48, v123
	v_pk_fma_f32 v[0:1], v[188:189], v[12:13], v[220:221]
	v_pk_fma_f32 v[2:3], v[190:191], v[10:11], v[222:223]
	global_store_dwordx4 v[8:9], v[0:3], off
	s_nop 1
	s_nop 0
	v_pk_mul_f32 v[10:11], v[26:27], v[50:51] op_sel_hi:[1,0]
	v_pk_mul_f32 v[12:13], v[28:29], v[50:51] op_sel_hi:[1,0]
	v_pk_fma_f32 v[2:3], v[194:195], v[10:11], v[226:227]
	v_pk_fma_f32 v[0:1], v[192:193], v[12:13], v[224:225]
	global_store_dwordx4 v[8:9], v[0:3], off offset:16
	s_nop 1
	s_nop 0
	v_pk_mul_f32 v[10:11], v[46:47], v[50:51] op_sel_hi:[1,0]
	v_pk_mul_f32 v[12:13], v[30:31], v[50:51] op_sel_hi:[1,0]
	v_pk_fma_f32 v[2:3], v[198:199], v[10:11], v[230:231]
	v_pk_fma_f32 v[0:1], v[196:197], v[12:13], v[228:229]
	global_store_dwordx4 v[8:9], v[0:3], off offset:32
	s_nop 1
	s_nop 0
	v_lshl_add_u64 v[10:11], s[14:15], 0, v[42:43]
	v_pk_mul_f32 v[12:13], v[138:139], v[50:51] op_sel_hi:[1,0]
	v_lshlrev_b64 v[10:11], 1, v[10:11]
	v_lshl_add_u64 v[44:45], s[70:71], 0, v[10:11]
	v_lshl_add_u64 v[46:47], s[2:3], 0, v[10:11]
	v_cvt_f32_f16_sdwa v51, v122 dst_sel:DWORD dst_unused:UNUSED_PAD src0_sel:WORD_1
	v_cvt_f32_f16_e32 v50, v122
	s_add_u32 s14, s20, s0
	s_addc_u32 s15, s21, s1
	v_pk_fma_f32 v[0:1], v[200:201], v[14:15], v[232:233]
	v_pk_fma_f32 v[2:3], v[202:203], v[12:13], v[234:235]
	global_store_dwordx4 v[8:9], v[0:3], off offset:48
	s_nop 1
	global_load_dwordx4 v[4:7], v[44:45], off offset:2064
	s_nop 0
	global_load_dwordx4 v[0:3], v[46:47], off offset:2064
	global_load_dwordx4 v[28:31], v[44:45], off
	global_load_dwordx4 v[24:27], v[46:47], off
	global_load_dwordx4 v[20:23], v[44:45], off offset:16
	global_load_dwordx4 v[16:19], v[46:47], off offset:16
	global_load_dwordx4 v[12:15], v[44:45], off offset:2048
	global_load_dwordx4 v[8:11], v[46:47], off offset:2048
	v_cvt_f32_f16_sdwa v45, v125 dst_sel:DWORD dst_unused:UNUSED_PAD src0_sel:WORD_1
	v_cvt_f32_f16_e32 v44, v125
	v_cvt_f32_f16_sdwa v47, v124 dst_sel:DWORD dst_unused:UNUSED_PAD src0_sel:WORD_1
	v_cvt_f32_f16_e32 v46, v124
	s_waitcnt vmcnt(6)
	v_and_b32_e32 v123, 0xffff0000, v2
	v_lshlrev_b32_e32 v122, 16, v2
	s_waitcnt vmcnt(5)
	v_lshlrev_b32_e32 v124, 16, v28
	v_and_b32_e32 v125, 0xffff0000, v28
	s_waitcnt vmcnt(4)
	v_lshlrev_b32_e32 v126, 16, v24
	v_and_b32_e32 v121, 0xffff0000, v6
	v_lshlrev_b32_e32 v120, 16, v6
	v_and_b32_e32 v127, 0xffff0000, v24
	v_and_b32_e32 v129, 0xffff0000, v7
	v_lshlrev_b32_e32 v128, 16, v7
	v_and_b32_e32 v7, 0xffff0000, v3
	v_lshlrev_b32_e32 v6, 16, v3
	v_lshlrev_b32_e32 v2, 16, v30
	v_and_b32_e32 v3, 0xffff0000, v30
	v_lshlrev_b32_e32 v130, 16, v26
	v_and_b32_e32 v131, 0xffff0000, v26
	v_lshlrev_b32_e32 v30, 16, v31
	v_and_b32_e32 v31, 0xffff0000, v31
	v_lshlrev_b32_e32 v26, 16, v27
	v_and_b32_e32 v27, 0xffff0000, v27
	v_lshlrev_b32_e32 v166, 16, v4
	v_and_b32_e32 v167, 0xffff0000, v4
	v_lshlrev_b32_e32 v168, 16, v0
	v_and_b32_e32 v169, 0xffff0000, v0
	v_lshlrev_b32_e32 v4, 16, v5
	v_and_b32_e32 v5, 0xffff0000, v5
	v_lshlrev_b32_e32 v0, 16, v1
	v_and_b32_e32 v1, 0xffff0000, v1
	v_pk_fma_f32 v[120:121], v[120:121], s[6:7], v[122:123] op_sel_hi:[1,0,1]
	v_pk_fma_f32 v[122:123], v[124:125], s[6:7], v[126:127] op_sel_hi:[1,0,1]
	v_lshlrev_b32_e32 v28, 16, v29
	v_and_b32_e32 v29, 0xffff0000, v29
	v_lshlrev_b32_e32 v24, 16, v25
	v_and_b32_e32 v25, 0xffff0000, v25
	v_pk_fma_f32 v[6:7], v[128:129], s[6:7], v[6:7] op_sel_hi:[1,0,1]
	v_pk_fma_f32 v[26:27], v[30:31], s[6:7], v[26:27] op_sel_hi:[1,0,1]
	v_pk_fma_f32 v[0:1], v[4:5], s[6:7], v[0:1] op_sel_hi:[1,0,1]
	v_pk_add_f32 v[30:31], v[120:121], v[44:45]
	v_pk_add_f32 v[44:45], v[122:123], v[46:47]
	v_pk_fma_f32 v[24:25], v[28:29], s[6:7], v[24:25] op_sel_hi:[1,0,1]
	v_pk_add_f32 v[46:47], v[6:7], v[50:51]
	v_pk_add_f32 v[50:51], v[0:1], v[64:65]
	v_add_f32_e32 v0, 0, v44
	v_pk_add_f32 v[24:25], v[24:25], v[48:49]
	v_add_f32_e32 v0, v45, v0
	v_pk_fma_f32 v[2:3], v[2:3], s[6:7], v[130:131] op_sel_hi:[1,0,1]
	v_add_f32_e32 v0, v24, v0
	v_pk_add_f32 v[48:49], v[2:3], v[52:53]
	v_add_f32_e32 v0, v25, v0
	v_add_f32_e32 v0, v48, v0
	s_waitcnt vmcnt(3)
	v_lshlrev_b32_e32 v132, 16, v20
	v_and_b32_e32 v133, 0xffff0000, v20
	s_waitcnt vmcnt(2)
	v_lshlrev_b32_e32 v134, 16, v16
	v_and_b32_e32 v135, 0xffff0000, v16
	v_pk_add_f32 v[26:27], v[26:27], v[54:55]
	v_add_f32_e32 v0, v49, v0
	v_pk_fma_f32 v[28:29], v[132:133], s[6:7], v[134:135] op_sel_hi:[1,0,1]
	v_add_f32_e32 v0, v26, v0
	v_lshlrev_b32_e32 v20, 16, v21
	v_and_b32_e32 v21, 0xffff0000, v21
	v_lshlrev_b32_e32 v16, 16, v17
	v_and_b32_e32 v17, 0xffff0000, v17
	v_pk_add_f32 v[28:29], v[28:29], v[104:105]
	v_add_f32_e32 v0, v27, v0
	v_pk_fma_f32 v[16:17], v[20:21], s[6:7], v[16:17] op_sel_hi:[1,0,1]
	v_add_f32_e32 v0, v28, v0
	v_lshlrev_b32_e32 v136, 16, v22
	v_and_b32_e32 v137, 0xffff0000, v22
	v_lshlrev_b32_e32 v138, 16, v18
	v_and_b32_e32 v139, 0xffff0000, v18
	v_pk_add_f32 v[16:17], v[16:17], v[106:107]
	v_add_f32_e32 v0, v29, v0
	v_pk_fma_f32 v[20:21], v[136:137], s[6:7], v[138:139] op_sel_hi:[1,0,1]
	v_add_f32_e32 v0, v16, v0
	v_lshlrev_b32_e32 v22, 16, v23
	v_and_b32_e32 v23, 0xffff0000, v23
	v_lshlrev_b32_e32 v18, 16, v19
	v_and_b32_e32 v19, 0xffff0000, v19
	v_pk_add_f32 v[20:21], v[20:21], v[108:109]
	v_add_f32_e32 v0, v17, v0
	v_pk_fma_f32 v[18:19], v[22:23], s[6:7], v[18:19] op_sel_hi:[1,0,1]
	v_add_f32_e32 v0, v20, v0
	s_waitcnt vmcnt(1)
	v_lshlrev_b32_e32 v150, 16, v12
	v_and_b32_e32 v151, 0xffff0000, v12
	s_waitcnt vmcnt(0)
	v_lshlrev_b32_e32 v152, 16, v8
	v_and_b32_e32 v153, 0xffff0000, v8
	v_pk_add_f32 v[18:19], v[18:19], v[110:111]
	v_add_f32_e32 v0, v21, v0
	v_pk_fma_f32 v[22:23], v[150:151], s[6:7], v[152:153] op_sel_hi:[1,0,1]
	v_add_f32_e32 v0, v18, v0
	v_lshlrev_b32_e32 v12, 16, v13
	v_and_b32_e32 v13, 0xffff0000, v13
	v_lshlrev_b32_e32 v8, 16, v9
	v_and_b32_e32 v9, 0xffff0000, v9
	v_pk_add_f32 v[22:23], v[22:23], v[114:115]
	v_add_f32_e32 v0, v19, v0
	v_pk_fma_f32 v[8:9], v[12:13], s[6:7], v[8:9] op_sel_hi:[1,0,1]
	v_add_f32_e32 v0, v22, v0
	v_lshlrev_b32_e32 v154, 16, v14
	v_and_b32_e32 v155, 0xffff0000, v14
	v_lshlrev_b32_e32 v164, 16, v10
	v_and_b32_e32 v165, 0xffff0000, v10
	v_pk_add_f32 v[8:9], v[8:9], v[112:113]
	v_add_f32_e32 v0, v23, v0
	v_pk_fma_f32 v[12:13], v[154:155], s[6:7], v[164:165] op_sel_hi:[1,0,1]
	v_add_f32_e32 v0, v8, v0
	v_lshlrev_b32_e32 v14, 16, v15
	v_and_b32_e32 v15, 0xffff0000, v15
	v_lshlrev_b32_e32 v10, 16, v11
	v_and_b32_e32 v11, 0xffff0000, v11
	v_pk_add_f32 v[12:13], v[12:13], v[116:117]
	v_add_f32_e32 v0, v9, v0
	v_pk_fma_f32 v[10:11], v[14:15], s[6:7], v[10:11] op_sel_hi:[1,0,1]
	v_add_f32_e32 v0, v12, v0
	v_pk_add_f32 v[10:11], v[10:11], v[66:67]
	v_add_f32_e32 v0, v13, v0
	v_pk_fma_f32 v[14:15], v[166:167], s[6:7], v[168:169] op_sel_hi:[1,0,1]
	v_add_f32_e32 v0, v10, v0
	v_pk_add_f32 v[14:15], v[14:15], v[118:119]
	v_add_f32_e32 v0, v11, v0
	v_add_f32_e32 v0, v14, v0
	v_add_f32_e32 v0, v15, v0
	v_add_f32_e32 v0, v50, v0
	v_add_f32_e32 v0, v51, v0
	v_add_f32_e32 v0, v30, v0
	v_add_f32_e32 v0, v31, v0
	v_add_f32_e32 v0, v46, v0
	v_add_f32_e32 v0, v47, v0
	ds_bpermute_b32 v1, v79, v0
	s_waitcnt lgkmcnt(0)
	v_add_f32_e32 v0, v0, v1
	ds_bpermute_b32 v1, v80, v0
	s_waitcnt lgkmcnt(0)
	v_add_f32_e32 v0, v0, v1
	ds_bpermute_b32 v1, v81, v0
	s_waitcnt lgkmcnt(0)
	v_add_f32_e32 v0, v0, v1
	ds_bpermute_b32 v1, v82, v0
	s_waitcnt lgkmcnt(0)
	v_add_f32_e32 v0, v0, v1
	ds_bpermute_b32 v1, v83, v0
	s_waitcnt lgkmcnt(0)
	v_add_f32_e32 v52, v0, v1
	ds_bpermute_b32 v53, v84, v52
	s_waitcnt lgkmcnt(0)
	v_add_f32_e32 v52, v52, v53
	v_mul_f32_e32 v52, 0x3a000000, v52
	v_pk_add_f32 v[44:45], v[44:45], v[52:53] op_sel_hi:[1,0] neg_lo:[0,1] neg_hi:[0,1]
	v_pk_add_f32 v[24:25], v[24:25], v[52:53] op_sel_hi:[1,0] neg_lo:[0,1] neg_hi:[0,1]
	v_pk_add_f32 v[48:49], v[48:49], v[52:53] op_sel_hi:[1,0] neg_lo:[0,1] neg_hi:[0,1]
	v_pk_add_f32 v[26:27], v[26:27], v[52:53] op_sel_hi:[1,0] neg_lo:[0,1] neg_hi:[0,1]
	v_pk_add_f32 v[28:29], v[28:29], v[52:53] op_sel_hi:[1,0] neg_lo:[0,1] neg_hi:[0,1]
	v_pk_add_f32 v[16:17], v[16:17], v[52:53] op_sel_hi:[1,0] neg_lo:[0,1] neg_hi:[0,1]
	v_pk_add_f32 v[20:21], v[20:21], v[52:53] op_sel_hi:[1,0] neg_lo:[0,1] neg_hi:[0,1]
	v_pk_add_f32 v[18:19], v[18:19], v[52:53] op_sel_hi:[1,0] neg_lo:[0,1] neg_hi:[0,1]
	v_pk_add_f32 v[22:23], v[22:23], v[52:53] op_sel_hi:[1,0] neg_lo:[0,1] neg_hi:[0,1]
	v_pk_add_f32 v[8:9], v[8:9], v[52:53] op_sel_hi:[1,0] neg_lo:[0,1] neg_hi:[0,1]
	v_pk_add_f32 v[12:13], v[12:13], v[52:53] op_sel_hi:[1,0] neg_lo:[0,1] neg_hi:[0,1]
	v_pk_add_f32 v[10:11], v[10:11], v[52:53] op_sel_hi:[1,0] neg_lo:[0,1] neg_hi:[0,1]
	v_pk_add_f32 v[14:15], v[14:15], v[52:53] op_sel_hi:[1,0] neg_lo:[0,1] neg_hi:[0,1]
	v_pk_add_f32 v[50:51], v[50:51], v[52:53] op_sel_hi:[1,0] neg_lo:[0,1] neg_hi:[0,1]
	v_pk_add_f32 v[46:47], v[46:47], v[52:53] op_sel_hi:[1,0] neg_lo:[0,1] neg_hi:[0,1]
	v_pk_add_f32 v[30:31], v[30:31], v[52:53] op_sel_hi:[1,0] neg_lo:[0,1] neg_hi:[0,1]
	v_pk_mul_f32 v[52:53], v[44:45], v[44:45]
	v_pk_mul_f32 v[54:55], v[24:25], v[24:25]
	v_add_f32_e32 v52, v52, v53
	v_add_f32_e32 v52, v54, v52
	v_pk_mul_f32 v[64:65], v[48:49], v[48:49]
	v_add_f32_e32 v52, v55, v52
	v_add_f32_e32 v52, v64, v52
	v_pk_mul_f32 v[66:67], v[26:27], v[26:27]
	v_add_f32_e32 v52, v65, v52
	v_add_f32_e32 v52, v66, v52
	v_pk_mul_f32 v[104:105], v[28:29], v[28:29]
	v_add_f32_e32 v52, v67, v52
	v_add_f32_e32 v52, v104, v52
	v_pk_mul_f32 v[106:107], v[16:17], v[16:17]
	v_add_f32_e32 v52, v105, v52
	v_add_f32_e32 v52, v106, v52
	v_pk_mul_f32 v[108:109], v[20:21], v[20:21]
	v_add_f32_e32 v52, v107, v52
	v_add_f32_e32 v52, v108, v52
	v_pk_mul_f32 v[110:111], v[18:19], v[18:19]
	v_add_f32_e32 v52, v109, v52
	v_add_f32_e32 v52, v110, v52
	v_pk_mul_f32 v[112:113], v[22:23], v[22:23]
	v_add_f32_e32 v52, v111, v52
	v_add_f32_e32 v52, v112, v52
	v_pk_mul_f32 v[114:115], v[8:9], v[8:9]
	v_add_f32_e32 v52, v113, v52
	v_add_f32_e32 v52, v114, v52
	v_pk_mul_f32 v[116:117], v[12:13], v[12:13]
	v_add_f32_e32 v52, v115, v52
	v_add_f32_e32 v52, v116, v52
	v_pk_mul_f32 v[118:119], v[10:11], v[10:11]
	v_add_f32_e32 v52, v117, v52
	v_add_f32_e32 v52, v118, v52
	v_pk_mul_f32 v[120:121], v[14:15], v[14:15]
	v_add_f32_e32 v52, v119, v52
	v_add_f32_e32 v52, v120, v52
	v_pk_mul_f32 v[122:123], v[50:51], v[50:51]
	v_add_f32_e32 v52, v121, v52
	v_add_f32_e32 v52, v122, v52
	v_pk_mul_f32 v[126:127], v[30:31], v[30:31]
	v_add_f32_e32 v52, v123, v52
	v_add_f32_e32 v52, v126, v52
	v_pk_mul_f32 v[124:125], v[46:47], v[46:47]
	v_add_f32_e32 v52, v127, v52
	v_add_f32_e32 v52, v124, v52
	v_add_f32_e32 v52, v125, v52
	ds_bpermute_b32 v53, v79, v52
	s_waitcnt lgkmcnt(0)
	v_add_f32_e32 v52, v52, v53
	ds_bpermute_b32 v53, v80, v52
	s_waitcnt lgkmcnt(0)
	v_add_f32_e32 v52, v52, v53
	ds_bpermute_b32 v53, v81, v52
	s_waitcnt lgkmcnt(0)
	v_add_f32_e32 v52, v52, v53
	ds_bpermute_b32 v53, v82, v52
	s_waitcnt lgkmcnt(0)
	v_add_f32_e32 v52, v52, v53
	ds_bpermute_b32 v53, v83, v52
	s_waitcnt lgkmcnt(0)
	v_add_f32_e32 v52, v52, v53
	ds_bpermute_b32 v53, v84, v52
	s_waitcnt lgkmcnt(0)
	v_add_f32_e32 v52, v52, v53
	v_fmamk_f32 v52, v52, 0x3a000000, v101
	v_mul_f32_e32 v53, 0x4f800000, v52
	v_cmp_gt_f32_e32 vcc, s7, v52
	s_nop 1
	v_cndmask_b32_e32 v52, v52, v53, vcc
	v_sqrt_f32_e32 v53, v52
	s_nop 0
	v_add_u32_e32 v54, -1, v53
	v_add_u32_e32 v55, 1, v53
	v_fma_f32 v64, -v54, v53, v52
	v_fma_f32 v65, -v55, v53, v52
	v_cmp_ge_f32_e64 s[0:1], 0, v64
	s_nop 1
	v_cndmask_b32_e64 v53, v53, v54, s[0:1]
	v_cmp_lt_f32_e64 s[0:1], 0, v65
	s_nop 1
	v_cndmask_b32_e64 v53, v53, v55, s[0:1]
	v_mul_f32_e32 v54, 0x37800000, v53
	v_cndmask_b32_e32 v53, v53, v54, vcc
	v_cmp_class_f32_e32 vcc, v52, v102
	s_nop 1
	v_cndmask_b32_e32 v54, v53, v52, vcc
	v_div_scale_f32 v55, s[0:1], v54, v54, 1.0
	v_rcp_f32_e32 v64, v55
	v_div_scale_f32 v65, vcc, 1.0, v54, 1.0
	v_lshl_add_u64 v[52:53], s[14:15], 0, v[36:37]
	v_fma_f32 v66, -v55, v64, 1.0
	v_fmac_f32_e32 v64, v66, v64
	v_mul_f32_e32 v66, v65, v64
	v_fma_f32 v67, -v55, v66, v65
	v_fmac_f32_e32 v66, v67, v64
	v_fma_f32 v55, -v55, v66, v65
	v_div_fmas_f32 v55, v55, v64, v66
	v_div_fixup_f32 v54, v55, v54, 1.0
	v_pk_mul_f32 v[44:45], v[44:45], v[54:55] op_sel_hi:[1,0]
	v_pk_mul_f32 v[24:25], v[24:25], v[54:55] op_sel_hi:[1,0]
	v_pk_fma_f32 v[0:1], v[172:173], v[44:45], v[204:205]
	v_pk_fma_f32 v[2:3], v[174:175], v[24:25], v[206:207]
	global_store_dwordx4 v[52:53], v[0:3], off
	s_nop 1
	s_nop 0
	v_pk_mul_f32 v[24:25], v[26:27], v[54:55] op_sel_hi:[1,0]
	v_pk_mul_f32 v[26:27], v[48:49], v[54:55] op_sel_hi:[1,0]
	v_pk_mul_f32 v[16:17], v[16:17], v[54:55] op_sel_hi:[1,0]
	v_pk_mul_f32 v[8:9], v[8:9], v[54:55] op_sel_hi:[1,0]
	s_or_b32 s0, s10, 2
	s_ashr_i32 s1, s0, 31
	s_lshl_b64 s[14:15], s[0:1], 11
	v_cvt_f32_f16_sdwa v49, v73 dst_sel:DWORD dst_unused:UNUSED_PAD src0_sel:WORD_1
	v_cvt_f32_f16_e32 v48, v73
	v_cvt_f32_f16_sdwa v65, v69 dst_sel:DWORD dst_unused:UNUSED_PAD src0_sel:WORD_1
	v_cvt_f32_f16_e32 v64, v69
	v_cvt_f32_f16_sdwa v67, v68 dst_sel:DWORD dst_unused:UNUSED_PAD src0_sel:WORD_1
	v_cvt_f32_f16_e32 v66, v68
	v_cvt_f32_f16_sdwa v69, v63 dst_sel:DWORD dst_unused:UNUSED_PAD src0_sel:WORD_1
	v_cvt_f32_f16_e32 v68, v63
	v_cvt_f32_f16_sdwa v63, v62 dst_sel:DWORD dst_unused:UNUSED_PAD src0_sel:WORD_1
	v_cvt_f32_f16_e32 v62, v62
	v_cvt_f32_f16_sdwa v73, v59 dst_sel:DWORD dst_unused:UNUSED_PAD src0_sel:WORD_1
	s_lshl_b64 s[0:1], s[0:1], 13
	v_pk_fma_f32 v[0:1], v[176:177], v[26:27], v[208:209]
	v_pk_fma_f32 v[2:3], v[178:179], v[24:25], v[210:211]
	global_store_dwordx4 v[52:53], v[0:3], off offset:16
	s_nop 1
	s_nop 0
	v_pk_mul_f32 v[24:25], v[28:29], v[54:55] op_sel_hi:[1,0]
	v_pk_fma_f32 v[2:3], v[182:183], v[16:17], v[214:215]
	v_pk_fma_f32 v[0:1], v[180:181], v[24:25], v[212:213]
	global_store_dwordx4 v[52:53], v[0:3], off offset:32
	s_nop 1
	s_nop 0
	v_pk_mul_f32 v[16:17], v[18:19], v[54:55] op_sel_hi:[1,0]
	v_pk_mul_f32 v[18:19], v[20:21], v[54:55] op_sel_hi:[1,0]
	v_pk_fma_f32 v[2:3], v[186:187], v[16:17], v[218:219]
	v_pk_fma_f32 v[0:1], v[184:185], v[18:19], v[216:217]
	global_store_dwordx4 v[52:53], v[0:3], off offset:48
	s_nop 1
	s_nop 0
	v_add_co_u32_e32 v16, vcc, s12, v52
	v_pk_mul_f32 v[18:19], v[22:23], v[54:55] op_sel_hi:[1,0]
	s_nop 0
	v_addc_co_u32_e32 v17, vcc, 0, v53, vcc
	v_cvt_f32_f16_sdwa v53, v71 dst_sel:DWORD dst_unused:UNUSED_PAD src0_sel:WORD_1
	v_cvt_f32_f16_e32 v52, v71
	v_cvt_f32_f16_sdwa v71, v61 dst_sel:DWORD dst_unused:UNUSED_PAD src0_sel:WORD_1
	v_pk_fma_f32 v[0:1], v[188:189], v[18:19], v[220:221]
	v_pk_fma_f32 v[2:3], v[190:191], v[8:9], v[222:223]
	global_store_dwordx4 v[16:17], v[0:3], off
	s_nop 1
	s_nop 0
	v_pk_mul_f32 v[8:9], v[10:11], v[54:55] op_sel_hi:[1,0]
	v_pk_mul_f32 v[10:11], v[12:13], v[54:55] op_sel_hi:[1,0]
	v_pk_mul_f32 v[12:13], v[30:31], v[54:55] op_sel_hi:[1,0]
	v_pk_fma_f32 v[0:1], v[192:193], v[10:11], v[224:225]
	v_pk_fma_f32 v[2:3], v[194:195], v[8:9], v[226:227]
	global_store_dwordx4 v[16:17], v[0:3], off offset:16
	s_nop 1
	s_nop 0
	v_pk_mul_f32 v[8:9], v[50:51], v[54:55] op_sel_hi:[1,0]
	v_pk_mul_f32 v[10:11], v[14:15], v[54:55] op_sel_hi:[1,0]
	v_cvt_f32_f16_sdwa v51, v72 dst_sel:DWORD dst_unused:UNUSED_PAD src0_sel:WORD_1
	v_cvt_f32_f16_e32 v50, v72
	v_cvt_f32_f16_e32 v72, v59
	v_cvt_f32_f16_sdwa v59, v58 dst_sel:DWORD dst_unused:UNUSED_PAD src0_sel:WORD_1
	v_cvt_f32_f16_e32 v58, v58
	v_pk_fma_f32 v[0:1], v[196:197], v[10:11], v[228:229]
	v_pk_fma_f32 v[2:3], v[198:199], v[8:9], v[230:231]
	global_store_dwordx4 v[16:17], v[0:3], off offset:32
	s_nop 1
	s_nop 0
	v_lshl_add_u64 v[8:9], s[14:15], 0, v[42:43]
	v_pk_mul_f32 v[10:11], v[46:47], v[54:55] op_sel_hi:[1,0]
	v_lshlrev_b64 v[8:9], 1, v[8:9]
	v_lshl_add_u64 v[44:45], s[70:71], 0, v[8:9]
	v_lshl_add_u64 v[46:47], s[2:3], 0, v[8:9]
	v_cvt_f32_f16_sdwa v55, v70 dst_sel:DWORD dst_unused:UNUSED_PAD src0_sel:WORD_1
	v_cvt_f32_f16_e32 v54, v70
	v_cvt_f32_f16_e32 v70, v61
	v_cvt_f32_f16_sdwa v61, v60 dst_sel:DWORD dst_unused:UNUSED_PAD src0_sel:WORD_1
	v_cvt_f32_f16_e32 v60, v60
	s_add_u32 s14, s20, s0
	s_addc_u32 s15, s21, s1
	v_pk_fma_f32 v[0:1], v[200:201], v[12:13], v[232:233]
	v_pk_fma_f32 v[2:3], v[202:203], v[10:11], v[234:235]
	global_store_dwordx4 v[16:17], v[0:3], off offset:48
	s_nop 1
	global_load_dwordx4 v[4:7], v[44:45], off offset:2064
	s_nop 0
	global_load_dwordx4 v[0:3], v[46:47], off offset:2064
	global_load_dwordx4 v[28:31], v[44:45], off
	global_load_dwordx4 v[24:27], v[46:47], off
	global_load_dwordx4 v[20:23], v[44:45], off offset:16
	global_load_dwordx4 v[16:19], v[46:47], off offset:16
	global_load_dwordx4 v[12:15], v[44:45], off offset:2048
	global_load_dwordx4 v[8:11], v[46:47], off offset:2048
	v_cvt_f32_f16_sdwa v45, v75 dst_sel:DWORD dst_unused:UNUSED_PAD src0_sel:WORD_1
	v_cvt_f32_f16_e32 v44, v75
	v_cvt_f32_f16_sdwa v47, v74 dst_sel:DWORD dst_unused:UNUSED_PAD src0_sel:WORD_1
	v_cvt_f32_f16_e32 v46, v74
	v_cvt_f32_f16_sdwa v75, v57 dst_sel:DWORD dst_unused:UNUSED_PAD src0_sel:WORD_1
	v_cvt_f32_f16_e32 v74, v57
	v_cvt_f32_f16_sdwa v57, v56 dst_sel:DWORD dst_unused:UNUSED_PAD src0_sel:WORD_1
	v_cvt_f32_f16_e32 v56, v56
	s_waitcnt vmcnt(6)
	v_and_b32_e32 v107, 0xffff0000, v2
	v_lshlrev_b32_e32 v106, 16, v2
	s_waitcnt vmcnt(5)
	v_lshlrev_b32_e32 v108, 16, v28
	v_and_b32_e32 v109, 0xffff0000, v28
	s_waitcnt vmcnt(4)
	v_lshlrev_b32_e32 v110, 16, v24
	v_and_b32_e32 v105, 0xffff0000, v6
	v_lshlrev_b32_e32 v104, 16, v6
	v_and_b32_e32 v111, 0xffff0000, v24
	v_and_b32_e32 v113, 0xffff0000, v7
	v_lshlrev_b32_e32 v112, 16, v7
	v_and_b32_e32 v7, 0xffff0000, v3
	v_lshlrev_b32_e32 v6, 16, v3
	v_lshlrev_b32_e32 v2, 16, v30
	v_and_b32_e32 v3, 0xffff0000, v30
	v_lshlrev_b32_e32 v114, 16, v26
	v_and_b32_e32 v115, 0xffff0000, v26
	v_lshlrev_b32_e32 v30, 16, v31
	v_and_b32_e32 v31, 0xffff0000, v31
	v_lshlrev_b32_e32 v26, 16, v27
	v_and_b32_e32 v27, 0xffff0000, v27
	v_lshlrev_b32_e32 v132, 16, v4
	v_and_b32_e32 v133, 0xffff0000, v4
	v_lshlrev_b32_e32 v134, 16, v0
	v_and_b32_e32 v135, 0xffff0000, v0
	v_lshlrev_b32_e32 v4, 16, v5
	v_and_b32_e32 v5, 0xffff0000, v5
	v_lshlrev_b32_e32 v0, 16, v1
	v_and_b32_e32 v1, 0xffff0000, v1
	v_pk_fma_f32 v[104:105], v[104:105], s[6:7], v[106:107] op_sel_hi:[1,0,1]
	v_pk_fma_f32 v[106:107], v[108:109], s[6:7], v[110:111] op_sel_hi:[1,0,1]
	v_lshlrev_b32_e32 v28, 16, v29
	v_and_b32_e32 v29, 0xffff0000, v29
	v_lshlrev_b32_e32 v24, 16, v25
	v_and_b32_e32 v25, 0xffff0000, v25
	v_pk_fma_f32 v[6:7], v[112:113], s[6:7], v[6:7] op_sel_hi:[1,0,1]
	v_pk_fma_f32 v[26:27], v[30:31], s[6:7], v[26:27] op_sel_hi:[1,0,1]
	v_pk_fma_f32 v[0:1], v[4:5], s[6:7], v[0:1] op_sel_hi:[1,0,1]
	v_pk_add_f32 v[30:31], v[104:105], v[44:45]
	v_pk_add_f32 v[44:45], v[106:107], v[46:47]
	v_pk_fma_f32 v[24:25], v[28:29], s[6:7], v[24:25] op_sel_hi:[1,0,1]
	v_pk_add_f32 v[46:47], v[6:7], v[50:51]
	v_pk_add_f32 v[50:51], v[0:1], v[56:57]
	v_add_f32_e32 v0, 0, v44
	v_pk_add_f32 v[24:25], v[24:25], v[48:49]
	v_add_f32_e32 v0, v45, v0
	v_pk_fma_f32 v[2:3], v[2:3], s[6:7], v[114:115] op_sel_hi:[1,0,1]
	v_add_f32_e32 v0, v24, v0
	v_pk_add_f32 v[48:49], v[2:3], v[52:53]
	v_add_f32_e32 v0, v25, v0
	v_add_f32_e32 v0, v48, v0
	s_waitcnt vmcnt(3)
	v_lshlrev_b32_e32 v116, 16, v20
	v_and_b32_e32 v117, 0xffff0000, v20
	s_waitcnt vmcnt(2)
	v_lshlrev_b32_e32 v118, 16, v16
	v_and_b32_e32 v119, 0xffff0000, v16
	v_pk_add_f32 v[26:27], v[26:27], v[54:55]
	v_add_f32_e32 v0, v49, v0
	v_pk_fma_f32 v[28:29], v[116:117], s[6:7], v[118:119] op_sel_hi:[1,0,1]
	v_add_f32_e32 v0, v26, v0
	v_lshlrev_b32_e32 v20, 16, v21
	v_and_b32_e32 v21, 0xffff0000, v21
	v_lshlrev_b32_e32 v16, 16, v17
	v_and_b32_e32 v17, 0xffff0000, v17
	v_pk_add_f32 v[28:29], v[28:29], v[64:65]
	v_add_f32_e32 v0, v27, v0
	v_pk_fma_f32 v[16:17], v[20:21], s[6:7], v[16:17] op_sel_hi:[1,0,1]
	v_add_f32_e32 v0, v28, v0
	v_lshlrev_b32_e32 v120, 16, v22
	v_and_b32_e32 v121, 0xffff0000, v22
	v_lshlrev_b32_e32 v122, 16, v18
	v_and_b32_e32 v123, 0xffff0000, v18
	v_pk_add_f32 v[16:17], v[16:17], v[66:67]
	v_add_f32_e32 v0, v29, v0
	v_pk_fma_f32 v[20:21], v[120:121], s[6:7], v[122:123] op_sel_hi:[1,0,1]
	v_add_f32_e32 v0, v16, v0
	v_lshlrev_b32_e32 v22, 16, v23
	v_and_b32_e32 v23, 0xffff0000, v23
	v_lshlrev_b32_e32 v18, 16, v19
	v_and_b32_e32 v19, 0xffff0000, v19
	v_pk_add_f32 v[20:21], v[20:21], v[68:69]
	v_add_f32_e32 v0, v17, v0
	v_pk_fma_f32 v[18:19], v[22:23], s[6:7], v[18:19] op_sel_hi:[1,0,1]
	v_add_f32_e32 v0, v20, v0
	s_waitcnt vmcnt(1)
	v_lshlrev_b32_e32 v124, 16, v12
	v_and_b32_e32 v125, 0xffff0000, v12
	s_waitcnt vmcnt(0)
	v_lshlrev_b32_e32 v126, 16, v8
	v_and_b32_e32 v127, 0xffff0000, v8
	v_pk_add_f32 v[18:19], v[18:19], v[62:63]
	v_add_f32_e32 v0, v21, v0
	v_pk_fma_f32 v[22:23], v[124:125], s[6:7], v[126:127] op_sel_hi:[1,0,1]
	v_add_f32_e32 v0, v18, v0
	v_lshlrev_b32_e32 v12, 16, v13
	v_and_b32_e32 v13, 0xffff0000, v13
	v_lshlrev_b32_e32 v8, 16, v9
	v_and_b32_e32 v9, 0xffff0000, v9
	v_pk_add_f32 v[22:23], v[22:23], v[70:71]
	v_add_f32_e32 v0, v19, v0
	v_pk_fma_f32 v[8:9], v[12:13], s[6:7], v[8:9] op_sel_hi:[1,0,1]
	v_add_f32_e32 v0, v22, v0
	v_lshlrev_b32_e32 v128, 16, v14
	v_and_b32_e32 v129, 0xffff0000, v14
	v_lshlrev_b32_e32 v130, 16, v10
	v_and_b32_e32 v131, 0xffff0000, v10
	v_pk_add_f32 v[8:9], v[8:9], v[60:61]
	v_add_f32_e32 v0, v23, v0
	v_pk_fma_f32 v[12:13], v[128:129], s[6:7], v[130:131] op_sel_hi:[1,0,1]
	v_add_f32_e32 v0, v8, v0
	v_lshlrev_b32_e32 v14, 16, v15
	v_and_b32_e32 v15, 0xffff0000, v15
	v_lshlrev_b32_e32 v10, 16, v11
	v_and_b32_e32 v11, 0xffff0000, v11
	v_pk_add_f32 v[12:13], v[12:13], v[72:73]
	v_add_f32_e32 v0, v9, v0
	v_pk_fma_f32 v[10:11], v[14:15], s[6:7], v[10:11] op_sel_hi:[1,0,1]
	v_add_f32_e32 v0, v12, v0
	v_pk_add_f32 v[10:11], v[10:11], v[58:59]
	v_add_f32_e32 v0, v13, v0
	v_pk_fma_f32 v[14:15], v[132:133], s[6:7], v[134:135] op_sel_hi:[1,0,1]
	v_add_f32_e32 v0, v10, v0
	v_pk_add_f32 v[14:15], v[14:15], v[74:75]
	v_add_f32_e32 v0, v11, v0
	v_add_f32_e32 v0, v14, v0
	v_add_f32_e32 v0, v15, v0
	v_add_f32_e32 v0, v50, v0
	v_add_f32_e32 v0, v51, v0
	v_add_f32_e32 v0, v30, v0
	v_add_f32_e32 v0, v31, v0
	v_add_f32_e32 v0, v46, v0
	v_add_f32_e32 v0, v47, v0
	ds_bpermute_b32 v1, v79, v0
	s_waitcnt lgkmcnt(0)
	v_add_f32_e32 v0, v0, v1
	ds_bpermute_b32 v1, v80, v0
	s_waitcnt lgkmcnt(0)
	v_add_f32_e32 v0, v0, v1
	ds_bpermute_b32 v1, v81, v0
	s_waitcnt lgkmcnt(0)
	v_add_f32_e32 v0, v0, v1
	ds_bpermute_b32 v1, v82, v0
	s_waitcnt lgkmcnt(0)
	v_add_f32_e32 v0, v0, v1
	ds_bpermute_b32 v1, v83, v0
	s_waitcnt lgkmcnt(0)
	v_add_f32_e32 v52, v0, v1
	ds_bpermute_b32 v53, v84, v52
	s_waitcnt lgkmcnt(0)
	v_add_f32_e32 v52, v52, v53
	v_mul_f32_e32 v52, 0x3a000000, v52
	v_pk_add_f32 v[44:45], v[44:45], v[52:53] op_sel_hi:[1,0] neg_lo:[0,1] neg_hi:[0,1]
	v_pk_add_f32 v[24:25], v[24:25], v[52:53] op_sel_hi:[1,0] neg_lo:[0,1] neg_hi:[0,1]
	v_pk_add_f32 v[48:49], v[48:49], v[52:53] op_sel_hi:[1,0] neg_lo:[0,1] neg_hi:[0,1]
	v_pk_add_f32 v[26:27], v[26:27], v[52:53] op_sel_hi:[1,0] neg_lo:[0,1] neg_hi:[0,1]
	v_pk_add_f32 v[28:29], v[28:29], v[52:53] op_sel_hi:[1,0] neg_lo:[0,1] neg_hi:[0,1]
	v_pk_add_f32 v[16:17], v[16:17], v[52:53] op_sel_hi:[1,0] neg_lo:[0,1] neg_hi:[0,1]
	v_pk_add_f32 v[20:21], v[20:21], v[52:53] op_sel_hi:[1,0] neg_lo:[0,1] neg_hi:[0,1]
	v_pk_add_f32 v[18:19], v[18:19], v[52:53] op_sel_hi:[1,0] neg_lo:[0,1] neg_hi:[0,1]
	v_pk_add_f32 v[22:23], v[22:23], v[52:53] op_sel_hi:[1,0] neg_lo:[0,1] neg_hi:[0,1]
	v_pk_add_f32 v[8:9], v[8:9], v[52:53] op_sel_hi:[1,0] neg_lo:[0,1] neg_hi:[0,1]
	v_pk_add_f32 v[12:13], v[12:13], v[52:53] op_sel_hi:[1,0] neg_lo:[0,1] neg_hi:[0,1]
	v_pk_add_f32 v[10:11], v[10:11], v[52:53] op_sel_hi:[1,0] neg_lo:[0,1] neg_hi:[0,1]
	v_pk_add_f32 v[14:15], v[14:15], v[52:53] op_sel_hi:[1,0] neg_lo:[0,1] neg_hi:[0,1]
	v_pk_add_f32 v[50:51], v[50:51], v[52:53] op_sel_hi:[1,0] neg_lo:[0,1] neg_hi:[0,1]
	v_pk_add_f32 v[46:47], v[46:47], v[52:53] op_sel_hi:[1,0] neg_lo:[0,1] neg_hi:[0,1]
	v_pk_add_f32 v[30:31], v[30:31], v[52:53] op_sel_hi:[1,0] neg_lo:[0,1] neg_hi:[0,1]
	v_pk_mul_f32 v[52:53], v[44:45], v[44:45]
	v_pk_mul_f32 v[54:55], v[24:25], v[24:25]
	v_add_f32_e32 v52, v52, v53
	v_add_f32_e32 v52, v54, v52
	v_pk_mul_f32 v[56:57], v[48:49], v[48:49]
	v_add_f32_e32 v52, v55, v52
	v_add_f32_e32 v52, v56, v52
	v_pk_mul_f32 v[58:59], v[26:27], v[26:27]
	v_add_f32_e32 v52, v57, v52
	v_add_f32_e32 v52, v58, v52
	v_pk_mul_f32 v[60:61], v[28:29], v[28:29]
	v_add_f32_e32 v52, v59, v52
	v_add_f32_e32 v52, v60, v52
	v_pk_mul_f32 v[62:63], v[16:17], v[16:17]
	v_add_f32_e32 v52, v61, v52
	v_add_f32_e32 v52, v62, v52
	v_pk_mul_f32 v[64:65], v[20:21], v[20:21]
	v_add_f32_e32 v52, v63, v52
	v_add_f32_e32 v52, v64, v52
	v_pk_mul_f32 v[66:67], v[18:19], v[18:19]
	v_add_f32_e32 v52, v65, v52
	v_add_f32_e32 v52, v66, v52
	v_pk_mul_f32 v[68:69], v[22:23], v[22:23]
	v_add_f32_e32 v52, v67, v52
	v_add_f32_e32 v52, v68, v52
	v_pk_mul_f32 v[70:71], v[8:9], v[8:9]
	v_add_f32_e32 v52, v69, v52
	v_add_f32_e32 v52, v70, v52
	v_pk_mul_f32 v[72:73], v[12:13], v[12:13]
	v_add_f32_e32 v52, v71, v52
	v_add_f32_e32 v52, v72, v52
	v_pk_mul_f32 v[74:75], v[10:11], v[10:11]
	v_add_f32_e32 v52, v73, v52
	v_add_f32_e32 v52, v74, v52
	v_pk_mul_f32 v[104:105], v[14:15], v[14:15]
	v_add_f32_e32 v52, v75, v52
	v_add_f32_e32 v52, v104, v52
	v_pk_mul_f32 v[106:107], v[50:51], v[50:51]
	v_add_f32_e32 v52, v105, v52
	v_add_f32_e32 v52, v106, v52
	v_pk_mul_f32 v[110:111], v[30:31], v[30:31]
	v_add_f32_e32 v52, v107, v52
	v_add_f32_e32 v52, v110, v52
	v_pk_mul_f32 v[108:109], v[46:47], v[46:47]
	v_add_f32_e32 v52, v111, v52
	v_add_f32_e32 v52, v108, v52
	v_add_f32_e32 v52, v109, v52
	ds_bpermute_b32 v53, v79, v52
	v_cvt_f32_f16_sdwa v73, v141 dst_sel:DWORD dst_unused:UNUSED_PAD src0_sel:WORD_1
	v_cvt_f32_f16_e32 v72, v141
	v_cvt_f32_f16_sdwa v61, v147 dst_sel:DWORD dst_unused:UNUSED_PAD src0_sel:WORD_1
	v_cvt_f32_f16_e32 v60, v147
	s_waitcnt lgkmcnt(0)
	v_add_f32_e32 v52, v52, v53
	ds_bpermute_b32 v53, v80, v52
	v_cvt_f32_f16_sdwa v63, v146 dst_sel:DWORD dst_unused:UNUSED_PAD src0_sel:WORD_1
	v_cvt_f32_f16_e32 v62, v146
	v_cvt_f32_f16_sdwa v65, v145 dst_sel:DWORD dst_unused:UNUSED_PAD src0_sel:WORD_1
	v_cvt_f32_f16_e32 v64, v145
	s_waitcnt lgkmcnt(0)
	v_add_f32_e32 v52, v52, v53
	ds_bpermute_b32 v53, v81, v52
	v_cvt_f32_f16_sdwa v67, v144 dst_sel:DWORD dst_unused:UNUSED_PAD src0_sel:WORD_1
	v_cvt_f32_f16_e32 v66, v144
	v_cvt_f32_f16_sdwa v69, v143 dst_sel:DWORD dst_unused:UNUSED_PAD src0_sel:WORD_1
	v_cvt_f32_f16_e32 v68, v143
	s_waitcnt lgkmcnt(0)
	v_add_f32_e32 v52, v52, v53
	ds_bpermute_b32 v53, v82, v52
	v_cvt_f32_f16_sdwa v71, v142 dst_sel:DWORD dst_unused:UNUSED_PAD src0_sel:WORD_1
	v_cvt_f32_f16_e32 v70, v142
	s_waitcnt lgkmcnt(0)
	v_add_f32_e32 v52, v52, v53
	ds_bpermute_b32 v53, v83, v52
	s_waitcnt lgkmcnt(0)
	v_add_f32_e32 v52, v52, v53
	ds_bpermute_b32 v53, v84, v52
	s_waitcnt lgkmcnt(0)
	v_add_f32_e32 v52, v52, v53
	v_fmamk_f32 v52, v52, 0x3a000000, v101
	v_mul_f32_e32 v53, 0x4f800000, v52
	v_cmp_gt_f32_e32 vcc, s7, v52
	s_nop 1
	v_cndmask_b32_e32 v52, v52, v53, vcc
	v_sqrt_f32_e32 v53, v52
	s_nop 0
	v_add_u32_e32 v54, -1, v53
	v_add_u32_e32 v55, 1, v53
	v_fma_f32 v56, -v54, v53, v52
	v_fma_f32 v57, -v55, v53, v52
	v_cmp_ge_f32_e64 s[0:1], 0, v56
	s_nop 1
	v_cndmask_b32_e64 v53, v53, v54, s[0:1]
	v_cmp_lt_f32_e64 s[0:1], 0, v57
	s_nop 1
	v_cndmask_b32_e64 v53, v53, v55, s[0:1]
	v_mul_f32_e32 v54, 0x37800000, v53
	v_cndmask_b32_e32 v53, v53, v54, vcc
	v_cmp_class_f32_e32 vcc, v52, v102
	s_nop 1
	v_cndmask_b32_e32 v54, v53, v52, vcc
	v_div_scale_f32 v55, s[0:1], v54, v54, 1.0
	v_rcp_f32_e32 v56, v55
	v_div_scale_f32 v57, vcc, 1.0, v54, 1.0
	v_lshl_add_u64 v[52:53], s[14:15], 0, v[36:37]
	v_fma_f32 v58, -v55, v56, 1.0
	v_fmac_f32_e32 v56, v58, v56
	v_mul_f32_e32 v58, v57, v56
	v_fma_f32 v59, -v55, v58, v57
	v_fmac_f32_e32 v58, v59, v56
	v_fma_f32 v55, -v55, v58, v57
	v_div_fmas_f32 v55, v55, v56, v58
	v_div_fixup_f32 v54, v55, v54, 1.0
	v_pk_mul_f32 v[44:45], v[44:45], v[54:55] op_sel_hi:[1,0]
	v_pk_mul_f32 v[24:25], v[24:25], v[54:55] op_sel_hi:[1,0]
	v_pk_fma_f32 v[0:1], v[172:173], v[44:45], v[204:205]
	v_pk_fma_f32 v[2:3], v[174:175], v[24:25], v[206:207]
	global_store_dwordx4 v[52:53], v[0:3], off
	s_nop 1
	s_nop 0
	v_pk_mul_f32 v[24:25], v[26:27], v[54:55] op_sel_hi:[1,0]
	v_pk_mul_f32 v[26:27], v[48:49], v[54:55] op_sel_hi:[1,0]
	v_pk_mul_f32 v[16:17], v[16:17], v[54:55] op_sel_hi:[1,0]
	v_pk_mul_f32 v[8:9], v[8:9], v[54:55] op_sel_hi:[1,0]
	s_or_b32 s0, s10, 3
	s_ashr_i32 s1, s0, 31
	s_lshl_b64 s[10:11], s[0:1], 11
	v_cvt_f32_f16_sdwa v49, v148 dst_sel:DWORD dst_unused:UNUSED_PAD src0_sel:WORD_1
	v_cvt_f32_f16_e32 v48, v148
	v_cvt_f32_f16_sdwa v57, v157 dst_sel:DWORD dst_unused:UNUSED_PAD src0_sel:WORD_1
	v_cvt_f32_f16_e32 v56, v157
	v_cvt_f32_f16_sdwa v59, v156 dst_sel:DWORD dst_unused:UNUSED_PAD src0_sel:WORD_1
	v_cvt_f32_f16_e32 v58, v156
	s_lshl_b64 s[0:1], s[0:1], 13
	v_pk_fma_f32 v[0:1], v[176:177], v[26:27], v[208:209]
	v_pk_fma_f32 v[2:3], v[178:179], v[24:25], v[210:211]
	global_store_dwordx4 v[52:53], v[0:3], off offset:16
	s_nop 1
	s_nop 0
	v_pk_mul_f32 v[24:25], v[28:29], v[54:55] op_sel_hi:[1,0]
	v_pk_fma_f32 v[2:3], v[182:183], v[16:17], v[214:215]
	v_pk_fma_f32 v[0:1], v[180:181], v[24:25], v[212:213]
	global_store_dwordx4 v[52:53], v[0:3], off offset:32
	s_nop 1
	s_nop 0
	v_pk_mul_f32 v[16:17], v[18:19], v[54:55] op_sel_hi:[1,0]
	v_pk_mul_f32 v[18:19], v[20:21], v[54:55] op_sel_hi:[1,0]
	v_pk_fma_f32 v[2:3], v[186:187], v[16:17], v[218:219]
	v_pk_fma_f32 v[0:1], v[184:185], v[18:19], v[216:217]
	global_store_dwordx4 v[52:53], v[0:3], off offset:48
	s_nop 1
	s_nop 0
	v_add_co_u32_e32 v16, vcc, s12, v52
	v_pk_mul_f32 v[18:19], v[22:23], v[54:55] op_sel_hi:[1,0]
	s_nop 0
	v_addc_co_u32_e32 v17, vcc, 0, v53, vcc
	v_cvt_f32_f16_sdwa v53, v159 dst_sel:DWORD dst_unused:UNUSED_PAD src0_sel:WORD_1
	v_cvt_f32_f16_e32 v52, v159
	v_pk_fma_f32 v[0:1], v[188:189], v[18:19], v[220:221]
	v_pk_fma_f32 v[2:3], v[190:191], v[8:9], v[222:223]
	global_store_dwordx4 v[16:17], v[0:3], off
	s_nop 1
	s_nop 0
	v_pk_mul_f32 v[8:9], v[10:11], v[54:55] op_sel_hi:[1,0]
	v_pk_mul_f32 v[10:11], v[12:13], v[54:55] op_sel_hi:[1,0]
	v_pk_mul_f32 v[12:13], v[30:31], v[54:55] op_sel_hi:[1,0]
	v_pk_fma_f32 v[0:1], v[192:193], v[10:11], v[224:225]
	v_pk_fma_f32 v[2:3], v[194:195], v[8:9], v[226:227]
	global_store_dwordx4 v[16:17], v[0:3], off offset:16
	s_nop 1
	s_nop 0
	v_pk_mul_f32 v[8:9], v[50:51], v[54:55] op_sel_hi:[1,0]
	v_pk_mul_f32 v[10:11], v[14:15], v[54:55] op_sel_hi:[1,0]
	v_cvt_f32_f16_sdwa v51, v160 dst_sel:DWORD dst_unused:UNUSED_PAD src0_sel:WORD_1
	v_cvt_f32_f16_e32 v50, v160
	v_pk_fma_f32 v[0:1], v[196:197], v[10:11], v[228:229]
	v_pk_fma_f32 v[2:3], v[198:199], v[8:9], v[230:231]
	global_store_dwordx4 v[16:17], v[0:3], off offset:32
	s_nop 1
	s_nop 0
	v_lshl_add_u64 v[8:9], s[10:11], 0, v[42:43]
	v_pk_mul_f32 v[10:11], v[46:47], v[54:55] op_sel_hi:[1,0]
	v_lshlrev_b64 v[8:9], 1, v[8:9]
	v_lshl_add_u64 v[42:43], s[70:71], 0, v[8:9]
	v_lshl_add_u64 v[44:45], s[2:3], 0, v[8:9]
	v_cvt_f32_f16_sdwa v47, v161 dst_sel:DWORD dst_unused:UNUSED_PAD src0_sel:WORD_1
	v_cvt_f32_f16_e32 v46, v161
	v_cvt_f32_f16_sdwa v55, v158 dst_sel:DWORD dst_unused:UNUSED_PAD src0_sel:WORD_1
	v_cvt_f32_f16_e32 v54, v158
	s_add_u32 s10, s20, s0
	s_addc_u32 s11, s21, s1
	v_lshl_add_u64 v[36:37], s[10:11], 0, v[36:37]
	s_mov_b32 s10, 1
	v_pk_fma_f32 v[0:1], v[200:201], v[12:13], v[232:233]
	v_pk_fma_f32 v[2:3], v[202:203], v[10:11], v[234:235]
	global_store_dwordx4 v[16:17], v[0:3], off offset:48
	s_nop 1
	global_load_dwordx4 v[4:7], v[42:43], off offset:2064
	s_nop 0
	global_load_dwordx4 v[0:3], v[44:45], off offset:2064
	global_load_dwordx4 v[28:31], v[42:43], off
	global_load_dwordx4 v[24:27], v[44:45], off
	global_load_dwordx4 v[20:23], v[42:43], off offset:16
	global_load_dwordx4 v[16:19], v[44:45], off offset:16
	global_load_dwordx4 v[12:15], v[42:43], off offset:2048
	global_load_dwordx4 v[8:11], v[44:45], off offset:2048
	v_cvt_f32_f16_sdwa v43, v149 dst_sel:DWORD dst_unused:UNUSED_PAD src0_sel:WORD_1
	v_cvt_f32_f16_e32 v42, v149
	v_cvt_f32_f16_sdwa v45, v162 dst_sel:DWORD dst_unused:UNUSED_PAD src0_sel:WORD_1
	v_cvt_f32_f16_e32 v44, v162
	s_waitcnt vmcnt(6)
	v_and_b32_e32 v105, 0xffff0000, v2
	v_lshlrev_b32_e32 v104, 16, v2
	s_waitcnt vmcnt(5)
	v_lshlrev_b32_e32 v106, 16, v28
	v_and_b32_e32 v107, 0xffff0000, v28
	s_waitcnt vmcnt(4)
	v_lshlrev_b32_e32 v108, 16, v24
	v_and_b32_e32 v75, 0xffff0000, v6
	v_lshlrev_b32_e32 v74, 16, v6
	v_and_b32_e32 v109, 0xffff0000, v24
	v_and_b32_e32 v111, 0xffff0000, v7
	v_lshlrev_b32_e32 v110, 16, v7
	v_and_b32_e32 v7, 0xffff0000, v3
	v_lshlrev_b32_e32 v6, 16, v3
	v_lshlrev_b32_e32 v2, 16, v30
	v_and_b32_e32 v3, 0xffff0000, v30
	v_lshlrev_b32_e32 v112, 16, v26
	v_and_b32_e32 v113, 0xffff0000, v26
	v_lshlrev_b32_e32 v30, 16, v31
	v_and_b32_e32 v31, 0xffff0000, v31
	v_lshlrev_b32_e32 v26, 16, v27
	v_and_b32_e32 v27, 0xffff0000, v27
	v_lshlrev_b32_e32 v130, 16, v4
	v_and_b32_e32 v131, 0xffff0000, v4
	v_lshlrev_b32_e32 v132, 16, v0
	v_and_b32_e32 v133, 0xffff0000, v0
	v_lshlrev_b32_e32 v4, 16, v5
	v_and_b32_e32 v5, 0xffff0000, v5
	v_lshlrev_b32_e32 v0, 16, v1
	v_and_b32_e32 v1, 0xffff0000, v1
	v_pk_fma_f32 v[74:75], v[74:75], s[6:7], v[104:105] op_sel_hi:[1,0,1]
	v_pk_fma_f32 v[104:105], v[106:107], s[6:7], v[108:109] op_sel_hi:[1,0,1]
	v_lshlrev_b32_e32 v28, 16, v29
	v_and_b32_e32 v29, 0xffff0000, v29
	v_lshlrev_b32_e32 v24, 16, v25
	v_and_b32_e32 v25, 0xffff0000, v25
	v_pk_fma_f32 v[6:7], v[110:111], s[6:7], v[6:7] op_sel_hi:[1,0,1]
	v_pk_fma_f32 v[26:27], v[30:31], s[6:7], v[26:27] op_sel_hi:[1,0,1]
	v_pk_fma_f32 v[0:1], v[4:5], s[6:7], v[0:1] op_sel_hi:[1,0,1]
	v_pk_add_f32 v[30:31], v[74:75], v[42:43]
	v_pk_add_f32 v[42:43], v[104:105], v[44:45]
	v_pk_fma_f32 v[24:25], v[28:29], s[6:7], v[24:25] op_sel_hi:[1,0,1]
	v_pk_add_f32 v[44:45], v[6:7], v[48:49]
	v_pk_add_f32 v[48:49], v[0:1], v[72:73]
	v_add_f32_e32 v0, 0, v42
	v_pk_add_f32 v[24:25], v[24:25], v[46:47]
	v_add_f32_e32 v0, v43, v0
	v_pk_fma_f32 v[2:3], v[2:3], s[6:7], v[112:113] op_sel_hi:[1,0,1]
	v_add_f32_e32 v0, v24, v0
	v_pk_add_f32 v[46:47], v[2:3], v[50:51]
	v_add_f32_e32 v0, v25, v0
	v_add_f32_e32 v0, v46, v0
	s_waitcnt vmcnt(3)
	v_lshlrev_b32_e32 v114, 16, v20
	v_and_b32_e32 v115, 0xffff0000, v20
	s_waitcnt vmcnt(2)
	v_lshlrev_b32_e32 v116, 16, v16
	v_and_b32_e32 v117, 0xffff0000, v16
	v_pk_add_f32 v[26:27], v[26:27], v[52:53]
	v_add_f32_e32 v0, v47, v0
	v_pk_fma_f32 v[28:29], v[114:115], s[6:7], v[116:117] op_sel_hi:[1,0,1]
	v_add_f32_e32 v0, v26, v0
	v_lshlrev_b32_e32 v20, 16, v21
	v_and_b32_e32 v21, 0xffff0000, v21
	v_lshlrev_b32_e32 v16, 16, v17
	v_and_b32_e32 v17, 0xffff0000, v17
	v_pk_add_f32 v[28:29], v[28:29], v[54:55]
	v_add_f32_e32 v0, v27, v0
	v_pk_fma_f32 v[16:17], v[20:21], s[6:7], v[16:17] op_sel_hi:[1,0,1]
	v_add_f32_e32 v0, v28, v0
	v_lshlrev_b32_e32 v118, 16, v22
	v_and_b32_e32 v119, 0xffff0000, v22
	v_lshlrev_b32_e32 v120, 16, v18
	v_and_b32_e32 v121, 0xffff0000, v18
	v_pk_add_f32 v[16:17], v[16:17], v[56:57]
	v_add_f32_e32 v0, v29, v0
	v_pk_fma_f32 v[20:21], v[118:119], s[6:7], v[120:121] op_sel_hi:[1,0,1]
	v_add_f32_e32 v0, v16, v0
	v_lshlrev_b32_e32 v22, 16, v23
	v_and_b32_e32 v23, 0xffff0000, v23
	v_lshlrev_b32_e32 v18, 16, v19
	v_and_b32_e32 v19, 0xffff0000, v19
	v_pk_add_f32 v[20:21], v[20:21], v[58:59]
	v_add_f32_e32 v0, v17, v0
	v_pk_fma_f32 v[18:19], v[22:23], s[6:7], v[18:19] op_sel_hi:[1,0,1]
	v_add_f32_e32 v0, v20, v0
	s_waitcnt vmcnt(1)
	v_lshlrev_b32_e32 v122, 16, v12
	v_and_b32_e32 v123, 0xffff0000, v12
	s_waitcnt vmcnt(0)
	v_lshlrev_b32_e32 v124, 16, v8
	v_and_b32_e32 v125, 0xffff0000, v8
	v_pk_add_f32 v[18:19], v[18:19], v[60:61]
	v_add_f32_e32 v0, v21, v0
	v_pk_fma_f32 v[22:23], v[122:123], s[6:7], v[124:125] op_sel_hi:[1,0,1]
	v_add_f32_e32 v0, v18, v0
	v_lshlrev_b32_e32 v12, 16, v13
	v_and_b32_e32 v13, 0xffff0000, v13
	v_lshlrev_b32_e32 v8, 16, v9
	v_and_b32_e32 v9, 0xffff0000, v9
	v_pk_add_f32 v[22:23], v[22:23], v[62:63]
	v_add_f32_e32 v0, v19, v0
	v_pk_fma_f32 v[8:9], v[12:13], s[6:7], v[8:9] op_sel_hi:[1,0,1]
	v_add_f32_e32 v0, v22, v0
	v_lshlrev_b32_e32 v126, 16, v14
	v_and_b32_e32 v127, 0xffff0000, v14
	v_lshlrev_b32_e32 v128, 16, v10
	v_and_b32_e32 v129, 0xffff0000, v10
	v_pk_add_f32 v[8:9], v[8:9], v[64:65]
	v_add_f32_e32 v0, v23, v0
	v_pk_fma_f32 v[12:13], v[126:127], s[6:7], v[128:129] op_sel_hi:[1,0,1]
	v_add_f32_e32 v0, v8, v0
	v_lshlrev_b32_e32 v14, 16, v15
	v_and_b32_e32 v15, 0xffff0000, v15
	v_lshlrev_b32_e32 v10, 16, v11
	v_and_b32_e32 v11, 0xffff0000, v11
	v_pk_add_f32 v[12:13], v[12:13], v[66:67]
	v_add_f32_e32 v0, v9, v0
	v_pk_fma_f32 v[10:11], v[14:15], s[6:7], v[10:11] op_sel_hi:[1,0,1]
	v_add_f32_e32 v0, v12, v0
	v_pk_add_f32 v[10:11], v[10:11], v[68:69]
	v_add_f32_e32 v0, v13, v0
	v_pk_fma_f32 v[14:15], v[130:131], s[6:7], v[132:133] op_sel_hi:[1,0,1]
	v_add_f32_e32 v0, v10, v0
	v_pk_add_f32 v[14:15], v[14:15], v[70:71]
	v_add_f32_e32 v0, v11, v0
	v_add_f32_e32 v0, v14, v0
	v_add_f32_e32 v0, v15, v0
	v_add_f32_e32 v0, v48, v0
	v_add_f32_e32 v0, v49, v0
	v_add_f32_e32 v0, v30, v0
	v_add_f32_e32 v0, v31, v0
	v_add_f32_e32 v0, v44, v0
	v_add_f32_e32 v0, v45, v0
	ds_bpermute_b32 v1, v79, v0
	s_waitcnt lgkmcnt(0)
	v_add_f32_e32 v0, v0, v1
	ds_bpermute_b32 v1, v80, v0
	s_waitcnt lgkmcnt(0)
	v_add_f32_e32 v0, v0, v1
	ds_bpermute_b32 v1, v81, v0
	s_waitcnt lgkmcnt(0)
	v_add_f32_e32 v0, v0, v1
	ds_bpermute_b32 v1, v82, v0
	s_waitcnt lgkmcnt(0)
	v_add_f32_e32 v0, v0, v1
	ds_bpermute_b32 v1, v83, v0
	s_waitcnt lgkmcnt(0)
	v_add_f32_e32 v50, v0, v1
	ds_bpermute_b32 v51, v84, v50
	s_waitcnt lgkmcnt(0)
	v_add_f32_e32 v50, v50, v51
	v_mul_f32_e32 v50, 0x3a000000, v50
	v_pk_add_f32 v[42:43], v[42:43], v[50:51] op_sel_hi:[1,0] neg_lo:[0,1] neg_hi:[0,1]
	v_pk_add_f32 v[24:25], v[24:25], v[50:51] op_sel_hi:[1,0] neg_lo:[0,1] neg_hi:[0,1]
	v_pk_add_f32 v[46:47], v[46:47], v[50:51] op_sel_hi:[1,0] neg_lo:[0,1] neg_hi:[0,1]
	v_pk_add_f32 v[26:27], v[26:27], v[50:51] op_sel_hi:[1,0] neg_lo:[0,1] neg_hi:[0,1]
	v_pk_add_f32 v[28:29], v[28:29], v[50:51] op_sel_hi:[1,0] neg_lo:[0,1] neg_hi:[0,1]
	v_pk_add_f32 v[16:17], v[16:17], v[50:51] op_sel_hi:[1,0] neg_lo:[0,1] neg_hi:[0,1]
	v_pk_add_f32 v[20:21], v[20:21], v[50:51] op_sel_hi:[1,0] neg_lo:[0,1] neg_hi:[0,1]
	v_pk_add_f32 v[18:19], v[18:19], v[50:51] op_sel_hi:[1,0] neg_lo:[0,1] neg_hi:[0,1]
	v_pk_add_f32 v[22:23], v[22:23], v[50:51] op_sel_hi:[1,0] neg_lo:[0,1] neg_hi:[0,1]
	v_pk_add_f32 v[8:9], v[8:9], v[50:51] op_sel_hi:[1,0] neg_lo:[0,1] neg_hi:[0,1]
	v_pk_add_f32 v[12:13], v[12:13], v[50:51] op_sel_hi:[1,0] neg_lo:[0,1] neg_hi:[0,1]
	v_pk_add_f32 v[10:11], v[10:11], v[50:51] op_sel_hi:[1,0] neg_lo:[0,1] neg_hi:[0,1]
	v_pk_add_f32 v[14:15], v[14:15], v[50:51] op_sel_hi:[1,0] neg_lo:[0,1] neg_hi:[0,1]
	v_pk_add_f32 v[48:49], v[48:49], v[50:51] op_sel_hi:[1,0] neg_lo:[0,1] neg_hi:[0,1]
	v_pk_add_f32 v[44:45], v[44:45], v[50:51] op_sel_hi:[1,0] neg_lo:[0,1] neg_hi:[0,1]
	v_pk_add_f32 v[30:31], v[30:31], v[50:51] op_sel_hi:[1,0] neg_lo:[0,1] neg_hi:[0,1]
	v_pk_mul_f32 v[50:51], v[42:43], v[42:43]
	v_pk_mul_f32 v[52:53], v[24:25], v[24:25]
	v_add_f32_e32 v50, v50, v51
	v_add_f32_e32 v50, v52, v50
	v_pk_mul_f32 v[54:55], v[46:47], v[46:47]
	v_add_f32_e32 v50, v53, v50
	v_add_f32_e32 v50, v54, v50
	v_pk_mul_f32 v[56:57], v[26:27], v[26:27]
	v_add_f32_e32 v50, v55, v50
	v_add_f32_e32 v50, v56, v50
	v_pk_mul_f32 v[58:59], v[28:29], v[28:29]
	v_add_f32_e32 v50, v57, v50
	v_add_f32_e32 v50, v58, v50
	v_pk_mul_f32 v[60:61], v[16:17], v[16:17]
	v_add_f32_e32 v50, v59, v50
	v_add_f32_e32 v50, v60, v50
	v_pk_mul_f32 v[62:63], v[20:21], v[20:21]
	v_add_f32_e32 v50, v61, v50
	v_add_f32_e32 v50, v62, v50
	v_pk_mul_f32 v[64:65], v[18:19], v[18:19]
	v_add_f32_e32 v50, v63, v50
	v_add_f32_e32 v50, v64, v50
	v_pk_mul_f32 v[66:67], v[22:23], v[22:23]
	v_add_f32_e32 v50, v65, v50
	v_add_f32_e32 v50, v66, v50
	v_pk_mul_f32 v[68:69], v[8:9], v[8:9]
	v_add_f32_e32 v50, v67, v50
	v_add_f32_e32 v50, v68, v50
	v_pk_mul_f32 v[70:71], v[12:13], v[12:13]
	v_add_f32_e32 v50, v69, v50
	v_add_f32_e32 v50, v70, v50
	v_pk_mul_f32 v[72:73], v[10:11], v[10:11]
	v_add_f32_e32 v50, v71, v50
	v_add_f32_e32 v50, v72, v50
	v_pk_mul_f32 v[74:75], v[14:15], v[14:15]
	v_add_f32_e32 v50, v73, v50
	v_add_f32_e32 v50, v74, v50
	v_pk_mul_f32 v[104:105], v[48:49], v[48:49]
	v_add_f32_e32 v50, v75, v50
	v_add_f32_e32 v50, v104, v50
	v_pk_mul_f32 v[108:109], v[30:31], v[30:31]
	v_add_f32_e32 v50, v105, v50
	v_add_f32_e32 v50, v108, v50
	v_pk_mul_f32 v[106:107], v[44:45], v[44:45]
	v_add_f32_e32 v50, v109, v50
	v_add_f32_e32 v50, v106, v50
	v_add_f32_e32 v50, v107, v50
	ds_bpermute_b32 v51, v79, v50
	s_waitcnt lgkmcnt(0)
	v_add_f32_e32 v50, v50, v51
	ds_bpermute_b32 v51, v80, v50
	s_waitcnt lgkmcnt(0)
	v_add_f32_e32 v50, v50, v51
	ds_bpermute_b32 v51, v81, v50
	s_waitcnt lgkmcnt(0)
	v_add_f32_e32 v50, v50, v51
	ds_bpermute_b32 v51, v82, v50
	s_waitcnt lgkmcnt(0)
	v_add_f32_e32 v50, v50, v51
	ds_bpermute_b32 v51, v83, v50
	s_waitcnt lgkmcnt(0)
	v_add_f32_e32 v50, v50, v51
	ds_bpermute_b32 v51, v84, v50
	s_waitcnt lgkmcnt(0)
	v_add_f32_e32 v50, v50, v51
	v_fmamk_f32 v50, v50, 0x3a000000, v101
	v_mul_f32_e32 v51, 0x4f800000, v50
	v_cmp_gt_f32_e32 vcc, s7, v50
	s_nop 1
	v_cndmask_b32_e32 v50, v50, v51, vcc
	v_sqrt_f32_e32 v51, v50
	s_nop 0
	v_add_u32_e32 v52, -1, v51
	v_add_u32_e32 v53, 1, v51
	v_fma_f32 v54, -v52, v51, v50
	v_fma_f32 v55, -v53, v51, v50
	v_cmp_ge_f32_e64 s[0:1], 0, v54
	s_nop 1
	v_cndmask_b32_e64 v51, v51, v52, s[0:1]
	v_cmp_lt_f32_e64 s[0:1], 0, v55
	s_nop 1
	v_cndmask_b32_e64 v51, v51, v53, s[0:1]
	v_mul_f32_e32 v52, 0x37800000, v51
	v_cndmask_b32_e32 v51, v51, v52, vcc
	v_cmp_class_f32_e32 vcc, v50, v102
	s_nop 1
	v_cndmask_b32_e32 v50, v51, v50, vcc
	v_div_scale_f32 v51, s[0:1], v50, v50, 1.0
	v_rcp_f32_e32 v52, v51
	v_div_scale_f32 v53, vcc, 1.0, v50, 1.0
	s_mov_b64 s[0:1], 0
	v_fma_f32 v54, -v51, v52, 1.0
	v_fmac_f32_e32 v52, v54, v52
	v_mul_f32_e32 v54, v53, v52
	v_fma_f32 v55, -v51, v54, v53
	v_fmac_f32_e32 v54, v55, v52
	v_fma_f32 v51, -v51, v54, v53
	v_div_fmas_f32 v51, v51, v52, v54
	v_div_fixup_f32 v50, v51, v50, 1.0
	v_pk_mul_f32 v[42:43], v[42:43], v[50:51] op_sel_hi:[1,0]
	v_pk_mul_f32 v[24:25], v[24:25], v[50:51] op_sel_hi:[1,0]
	v_pk_fma_f32 v[0:1], v[172:173], v[42:43], v[204:205]
	v_pk_fma_f32 v[2:3], v[174:175], v[24:25], v[206:207]
	global_store_dwordx4 v[36:37], v[0:3], off
	s_nop 1
	s_nop 0
	v_pk_mul_f32 v[24:25], v[26:27], v[50:51] op_sel_hi:[1,0]
	v_pk_mul_f32 v[26:27], v[46:47], v[50:51] op_sel_hi:[1,0]
	v_pk_mul_f32 v[16:17], v[16:17], v[50:51] op_sel_hi:[1,0]
	v_pk_mul_f32 v[8:9], v[8:9], v[50:51] op_sel_hi:[1,0]
	v_pk_fma_f32 v[0:1], v[176:177], v[26:27], v[208:209]
	v_pk_fma_f32 v[2:3], v[178:179], v[24:25], v[210:211]
	global_store_dwordx4 v[36:37], v[0:3], off offset:16
	s_nop 1
	s_nop 0
	v_pk_mul_f32 v[24:25], v[28:29], v[50:51] op_sel_hi:[1,0]
	v_pk_fma_f32 v[2:3], v[182:183], v[16:17], v[214:215]
	v_pk_fma_f32 v[0:1], v[180:181], v[24:25], v[212:213]
	global_store_dwordx4 v[36:37], v[0:3], off offset:32
	s_nop 1
	s_nop 0
	v_pk_mul_f32 v[16:17], v[18:19], v[50:51] op_sel_hi:[1,0]
	v_pk_mul_f32 v[18:19], v[20:21], v[50:51] op_sel_hi:[1,0]
	v_pk_fma_f32 v[2:3], v[186:187], v[16:17], v[218:219]
	v_pk_fma_f32 v[0:1], v[184:185], v[18:19], v[216:217]
	global_store_dwordx4 v[36:37], v[0:3], off offset:48
	s_nop 1
	s_nop 0
	v_add_co_u32_e32 v16, vcc, s12, v36
	v_pk_mul_f32 v[18:19], v[22:23], v[50:51] op_sel_hi:[1,0]
	s_nop 0
	v_addc_co_u32_e32 v17, vcc, 0, v37, vcc
	s_and_b64 vcc, exec, s[8:9]
	v_pk_fma_f32 v[0:1], v[188:189], v[18:19], v[220:221]
	v_pk_fma_f32 v[2:3], v[190:191], v[8:9], v[222:223]
	global_store_dwordx4 v[16:17], v[0:3], off
	s_nop 1
	s_nop 0
	v_pk_mul_f32 v[8:9], v[10:11], v[50:51] op_sel_hi:[1,0]
	v_pk_mul_f32 v[10:11], v[12:13], v[50:51] op_sel_hi:[1,0]
	v_pk_fma_f32 v[2:3], v[194:195], v[8:9], v[226:227]
	v_pk_fma_f32 v[0:1], v[192:193], v[10:11], v[224:225]
	global_store_dwordx4 v[16:17], v[0:3], off offset:16
	s_nop 1
	s_nop 0
	v_pk_mul_f32 v[8:9], v[48:49], v[50:51] op_sel_hi:[1,0]
	v_pk_mul_f32 v[10:11], v[14:15], v[50:51] op_sel_hi:[1,0]
	v_pk_fma_f32 v[2:3], v[198:199], v[8:9], v[230:231]
	v_pk_fma_f32 v[0:1], v[196:197], v[10:11], v[228:229]
	global_store_dwordx4 v[16:17], v[0:3], off offset:32
	s_nop 1
	s_nop 0
	v_pk_mul_f32 v[8:9], v[44:45], v[50:51] op_sel_hi:[1,0]
	v_pk_mul_f32 v[10:11], v[30:31], v[50:51] op_sel_hi:[1,0]
	v_pk_fma_f32 v[2:3], v[202:203], v[8:9], v[234:235]
	v_pk_fma_f32 v[0:1], v[200:201], v[10:11], v[232:233]
	global_store_dwordx4 v[16:17], v[0:3], off offset:48
	s_nop 1
	s_waitcnt vmcnt(0)
	s_cbranch_vccz .LBB0_1012
	s_lshr_b32 s1, s26, 14
	s_cmp_lt_u32 s1, 4
	s_cbranch_scc1 .LBB0_1015
	s_cmp_lg_u32 s100, 1
	s_cbranch_scc1 .LBB0_1015
	s_mov_b32 s100, 2
	s_lshl_b32 s1, s22, 11
	s_add_u32 s24, s72, 0xab00000
	s_addc_u32 s25, s73, 0
	s_add_u32 s24, s24, s1
	s_addc_u32 s25, s25, 0
	v_lshlrev_b32_e32 v236, 2, v78
	v_add_u32_e32 v237, 0x1000, v236
	v_add_u32_e32 v238, 0x2000, v236
	v_add_u32_e32 v239, 0x3000, v236
	global_load_dword v139, v236, s[24:25] offset:0
	global_load_dword v138, v236, s[24:25] offset:256
	global_load_dword v136, v236, s[24:25] offset:512
	global_load_dword v135, v236, s[24:25] offset:768
	global_load_dword v134, v236, s[24:25] offset:1024
	global_load_dword v133, v236, s[24:25] offset:1280
	global_load_dword v132, v236, s[24:25] offset:1536
	global_load_dword v131, v236, s[24:25] offset:1792
	global_load_dword v130, v236, s[24:25] offset:2048
	global_load_dword v129, v236, s[24:25] offset:2304
	global_load_dword v128, v236, s[24:25] offset:2560
	global_load_dword v127, v236, s[24:25] offset:2816
	global_load_dword v126, v236, s[24:25] offset:3072
	global_load_dword v114, v236, s[24:25] offset:3328
	global_load_dword v140, v236, s[24:25] offset:3584
	global_load_dword v137, v236, s[24:25] offset:3840
	global_load_dword v124, v237, s[24:25] offset:0
	global_load_dword v123, v237, s[24:25] offset:256
	global_load_dword v121, v237, s[24:25] offset:512
	global_load_dword v120, v237, s[24:25] offset:768
	global_load_dword v119, v237, s[24:25] offset:1024
	global_load_dword v118, v237, s[24:25] offset:1280
	global_load_dword v117, v237, s[24:25] offset:1536
	global_load_dword v116, v237, s[24:25] offset:1792
	global_load_dword v113, v237, s[24:25] offset:2048
	global_load_dword v112, v237, s[24:25] offset:2304
	global_load_dword v67, v237, s[24:25] offset:2560
	global_load_dword v66, v237, s[24:25] offset:2816
	global_load_dword v65, v237, s[24:25] offset:3072
	global_load_dword v64, v237, s[24:25] offset:3328
	global_load_dword v125, v237, s[24:25] offset:3584
	global_load_dword v122, v237, s[24:25] offset:3840
	global_load_dword v74, v238, s[24:25] offset:0
	global_load_dword v73, v238, s[24:25] offset:256
	global_load_dword v71, v238, s[24:25] offset:512
	global_load_dword v70, v238, s[24:25] offset:768
	global_load_dword v69, v238, s[24:25] offset:1024
	global_load_dword v68, v238, s[24:25] offset:1280
	global_load_dword v63, v238, s[24:25] offset:1536
	global_load_dword v62, v238, s[24:25] offset:1792
	global_load_dword v61, v238, s[24:25] offset:2048
	global_load_dword v60, v238, s[24:25] offset:2304
	global_load_dword v59, v238, s[24:25] offset:2560
	global_load_dword v58, v238, s[24:25] offset:2816
	global_load_dword v57, v238, s[24:25] offset:3072
	global_load_dword v56, v238, s[24:25] offset:3328
	global_load_dword v75, v238, s[24:25] offset:3584
	global_load_dword v72, v238, s[24:25] offset:3840
	global_load_dword v162, v239, s[24:25] offset:0
	global_load_dword v161, v239, s[24:25] offset:256
	global_load_dword v160, v239, s[24:25] offset:512
	global_load_dword v159, v239, s[24:25] offset:768
	global_load_dword v158, v239, s[24:25] offset:1024
	global_load_dword v157, v239, s[24:25] offset:1280
	global_load_dword v156, v239, s[24:25] offset:1536
	global_load_dword v147, v239, s[24:25] offset:1792
	global_load_dword v146, v239, s[24:25] offset:2048
	global_load_dword v145, v239, s[24:25] offset:2304
	global_load_dword v144, v239, s[24:25] offset:2560
	global_load_dword v143, v239, s[24:25] offset:2816
	global_load_dword v142, v239, s[24:25] offset:3072
	global_load_dword v141, v239, s[24:25] offset:3328
	global_load_dword v149, v239, s[24:25] offset:3584
	global_load_dword v148, v239, s[24:25] offset:3840
	s_mov_b32 s10, 0
	s_waitcnt vmcnt(0)
	s_branch .Lmy_ap_ln2

	.amdhsa_kernel _Z6mk_fwd4Args
		.amdhsa_group_segment_fixed_size 0
		.amdhsa_private_segment_fixed_size 0
		.amdhsa_kernarg_size 424
		.amdhsa_user_sgpr_count 2
		.amdhsa_user_sgpr_dispatch_ptr 0
		.amdhsa_user_sgpr_queue_ptr 0
		.amdhsa_user_sgpr_kernarg_segment_ptr 1
		.amdhsa_user_sgpr_dispatch_id 0
		.amdhsa_user_sgpr_kernarg_preload_length 0
		.amdhsa_user_sgpr_kernarg_preload_offset 0
		.amdhsa_user_sgpr_private_segment_size 0
		.amdhsa_uses_dynamic_stack 0
		.amdhsa_enable_private_segment 0
		.amdhsa_system_sgpr_workgroup_id_x 1
		.amdhsa_system_sgpr_workgroup_id_y 0
		.amdhsa_system_sgpr_workgroup_id_z 0
		.amdhsa_system_sgpr_workgroup_info 0
		.amdhsa_system_vgpr_workitem_id 0
		.amdhsa_next_free_vgpr 256
		.amdhsa_next_free_sgpr 102
		.amdhsa_accum_offset 256
		.amdhsa_reserve_vcc 1
		.amdhsa_float_round_mode_32 0
		.amdhsa_float_round_mode_16_64 0
		.amdhsa_float_denorm_mode_32 3
		.amdhsa_float_denorm_mode_16_64 3
		.amdhsa_dx10_clamp 1
		.amdhsa_ieee_mode 1
		.amdhsa_fp16_overflow 0
		.amdhsa_tg_split 0
		.amdhsa_exception_fp_ieee_invalid_op 0
		.amdhsa_exception_fp_denorm_src 0
		.amdhsa_exception_fp_ieee_div_zero 0
		.amdhsa_exception_fp_ieee_overflow 0
		.amdhsa_exception_fp_ieee_underflow 0
		.amdhsa_exception_fp_ieee_inexact 0
		.amdhsa_exception_int_div_zero 0
	.end_amdhsa_kernel

amdhsa.kernels:
  - .agpr_count:     0
    .args:
      - .offset:         0
        .size:           168
        .value_kind:     by_value
      - .offset:         168
        .size:           4
        .value_kind:     hidden_block_count_x
      - .offset:         172
        .size:           4
        .value_kind:     hidden_block_count_y
      - .offset:         176
        .size:           4
        .value_kind:     hidden_block_count_z
      - .offset:         180
        .size:           2
        .value_kind:     hidden_group_size_x
      - .offset:         182
        .size:           2
        .value_kind:     hidden_group_size_y
      - .offset:         184
        .size:           2
        .value_kind:     hidden_group_size_z
      - .offset:         186
        .size:           2
        .value_kind:     hidden_remainder_x
      - .offset:         188
        .size:           2
        .value_kind:     hidden_remainder_y
      - .offset:         190
        .size:           2
        .value_kind:     hidden_remainder_z
      - .offset:         208
        .size:           8
        .value_kind:     hidden_global_offset_x
      - .offset:         216
        .size:           8
        .value_kind:     hidden_global_offset_y
      - .offset:         224
        .size:           8
        .value_kind:     hidden_global_offset_z
      - .offset:         232
        .size:           2
        .value_kind:     hidden_grid_dims
      - .offset:         288
        .size:           4
        .value_kind:     hidden_dynamic_lds_size
    .group_segment_fixed_size: 0
    .kernarg_segment_align: 8
    .kernarg_segment_size: 424
    .language:       OpenCL C
    .language_version:
      - 2
      - 0
    .max_flat_workgroup_size: 512
    .name:           _Z6mk_fwd4Args
    .private_segment_fixed_size: 0
    .sgpr_count:     108
    .sgpr_spill_count: 111
    .symbol:         _Z6mk_fwd4Args.kd
    .uniform_work_group_size: 1
    .uses_dynamic_stack: false
    .vgpr_count:     256
    .vgpr_spill_count: 0
    .wavefront_size: 64
